# GEMM K loops: LDS-DMA addresses whose 64-bit vector sum is not reused are formed as scalar base + 32-bit lane offset (64 vector adds removed across the 8 GEMM loops)
# baseline (speedup 1.0000x reference)
; #define PG8_STAGE(bufoff, gbase, voff) do { _Pragma("unroll") for (int _i = 0; _i < 2; ++_i) \
;         __builtin_amdgcn_global_load_lds((const unsigned*)((const char*)(gbase) + (voff)[_i]), (PG8_LAS unsigned*)(lds + (bufoff) + ldsw + _i * 8192), 16, 0, 0); } while (0)
; #define PG8_LDA(dst, b, h) do { _Pragma("unroll") for (int m = 0; m < 4; ++m) _Pragma("unroll") for (int k = 0; k < 2; ++k) dst[m][k] = *(const PG8_LAS bf16x8*)(lds + PG8_SA(b, h) + aoff + m * 2048 + k * 1024); } while (0)
; #define PG8_LDB(dst, b, h) do { _Pragma("unroll") for (int n = 0; n < 2; ++n) _Pragma("unroll") for (int k = 0; k < 2; ++k) dst[n][k] = *(const PG8_LAS bf16x8*)(lds + PG8_SB(b, h) + boff + n * 2048 + k * 1024); } while (0)
; #define PG8_MMA(ai, bj, At, Bt) do { __builtin_amdgcn_s_setprio(1); _Pragma("unroll") for (int m = 0; m < 4; ++m) _Pragma("unroll") for (int n = 0; n < 2; ++n) _Pragma("unroll") for (int k = 0; k < 2; ++k) \
;         acc[ai][bj][m][n] = __builtin_amdgcn_mfma_f32_16x16x32_bf16(Bt[n][k], At[m][k], acc[ai][bj][m][n], 0, 0, 0); __builtin_amdgcn_s_setprio(0); } while (0)
; #define PG8_WAIT_V(n) asm volatile("s_waitcnt vmcnt(" #n ")" ::: "memory")
; #define PG8_WAIT_L(n) asm volatile("s_waitcnt lgkmcnt(" #n ")" ::: "memory")
; #define PG8_BAR __builtin_amdgcn_s_barrier()
; #define PG8_SCHED __builtin_amdgcn_sched_barrier(0)
; template <class Epi, class Sched, bool ALIGN_EPI = false, bool SP2 = false>
; __device__ __forceinline__ void gemm_phase(PG8_LAS unsigned char* lds, const Gemm g, const Sched& S, const Epi& E) {
;     ...
;             PG8_LDB(B0, 0, 0); PG8_LDB(B1, 0, 1); PG8_SCHED; PG8_LDA(At, 0, 0); PG8_STAGE(PG8_SA(1, 1), a1 + hstep, voffA);
;             PG8_WAIT_V(8); PG8_WAIT_L(0); PG8_BAR; PG8_MMA(0, 0, At, B0); PG8_MMA(0, 1, At, B1); PG8_BAR; PG8_SCHED;
;             PG8_LDA(At, 0, 1); PG8_STAGE(PG8_SB(0, 0), b2, voffB); PG8_STAGE(PG8_SB(0, 1), b2 + hstep, voffB); PG8_STAGE(PG8_SA(0, 0), a2, voffA);
.LBB0_132:
	s_add_u32 s10, s54, 0xfffc0080
	s_addc_u32 s11, s55, -1
	s_add_i32 s12, 0, 0x10000
	s_cmp_eq_u32 s31, 12
	s_cselect_b32 s59, s49, s11
	s_cselect_b32 s58, s73, s10
	v_add_u32_e32 v152, s12, v156
	s_cselect_b32 s57, s43, s30
	s_cselect_b32 s56, vcc_lo, vcc_hi
	s_add_i32 s13, 0, 0x14000
	ds_read_b128 v[144:147], v152
	ds_read_b128 v[148:151], v152 offset:1024
	ds_read_b128 v[160:163], v152 offset:2048
	ds_read_b128 v[164:167], v152 offset:3072
	v_add_u32_e32 v152, s13, v156
	ds_read_b128 v[168:171], v152
	ds_read_b128 v[172:175], v152 offset:1024
	ds_read_b128 v[176:179], v152 offset:2048
	ds_read_b128 v[180:183], v152 offset:3072
	s_add_i32 m0, s0, 0xc000
	ds_read_b128 v[198:201], v158
	ds_read_b128 v[202:205], v158 offset:1024
	ds_read_b128 v[206:209], v158 offset:2048
	ds_read_b128 v[210:213], v158 offset:3072
	ds_read_b128 v[214:217], v158 offset:4096
	ds_read_b128 v[226:229], v158 offset:5120
	ds_read_b128 v[230:233], v158 offset:6144
	ds_read_b128 v[234:237], v158 offset:7168
	global_load_lds_dwordx4 v140, s[54:55]
	s_add_i32 m0, s0, 0xe000
	s_nop 0
	global_load_lds_dwordx4 v142, s[54:55]
	s_waitcnt vmcnt(8)
	s_waitcnt lgkmcnt(0)
	s_barrier
	s_setprio 1
	s_waitcnt lgkmcnt(0)
	v_mfma_f32_16x16x32_bf16 v[124:127], v[144:147], v[198:201], v[124:127]
	v_mfma_f32_16x16x32_bf16 v[120:123], v[160:163], v[198:201], v[120:123]
	v_mfma_f32_16x16x32_bf16 v[108:111], v[144:147], v[206:209], v[108:111]
	v_mfma_f32_16x16x32_bf16 v[104:107], v[160:163], v[206:209], v[104:107]
	v_mfma_f32_16x16x32_bf16 v[92:95], v[144:147], v[214:217], v[92:95]
	v_mfma_f32_16x16x32_bf16 v[88:91], v[160:163], v[214:217], v[88:91]
	v_mfma_f32_16x16x32_bf16 v[76:79], v[144:147], v[230:233], v[76:79]
	v_mfma_f32_16x16x32_bf16 v[72:75], v[160:163], v[230:233], v[72:75]
	v_mfma_f32_16x16x32_bf16 v[124:127], v[148:151], v[202:205], v[124:127]
	v_mfma_f32_16x16x32_bf16 v[120:123], v[164:167], v[202:205], v[120:123]
	v_mfma_f32_16x16x32_bf16 v[108:111], v[148:151], v[210:213], v[108:111]
	v_mfma_f32_16x16x32_bf16 v[104:107], v[164:167], v[210:213], v[104:107]
	v_mfma_f32_16x16x32_bf16 v[92:95], v[148:151], v[226:229], v[92:95]
	v_mfma_f32_16x16x32_bf16 v[88:91], v[164:167], v[226:229], v[88:91]
	v_mfma_f32_16x16x32_bf16 v[76:79], v[148:151], v[234:237], v[76:79]
	v_mfma_f32_16x16x32_bf16 v[72:75], v[164:167], v[234:237], v[72:75]
	s_setprio 0
	s_setprio 1
	v_mfma_f32_16x16x32_bf16 v[116:119], v[168:171], v[198:201], v[116:119]
	v_mfma_f32_16x16x32_bf16 v[112:115], v[176:179], v[198:201], v[112:115]
	v_mfma_f32_16x16x32_bf16 v[100:103], v[168:171], v[206:209], v[100:103]
	v_mfma_f32_16x16x32_bf16 v[96:99], v[176:179], v[206:209], v[96:99]
	v_mfma_f32_16x16x32_bf16 v[84:87], v[168:171], v[214:217], v[84:87]
	v_mfma_f32_16x16x32_bf16 v[80:83], v[176:179], v[214:217], v[80:83]
	v_mfma_f32_16x16x32_bf16 v[68:71], v[168:171], v[230:233], v[68:71]
	v_mfma_f32_16x16x32_bf16 v[64:67], v[176:179], v[230:233], v[64:67]
	v_mfma_f32_16x16x32_bf16 v[116:119], v[172:175], v[202:205], v[116:119]
	v_mfma_f32_16x16x32_bf16 v[112:115], v[180:183], v[202:205], v[112:115]
	v_mfma_f32_16x16x32_bf16 v[100:103], v[172:175], v[210:213], v[100:103]
	v_mfma_f32_16x16x32_bf16 v[96:99], v[180:183], v[210:213], v[96:99]
	v_mfma_f32_16x16x32_bf16 v[84:87], v[172:175], v[226:229], v[84:87]
	v_mfma_f32_16x16x32_bf16 v[80:83], v[180:183], v[226:229], v[80:83]
	v_mfma_f32_16x16x32_bf16 v[68:71], v[172:175], v[234:237], v[68:71]
	v_mfma_f32_16x16x32_bf16 v[64:67], v[180:183], v[234:237], v[64:67]
	s_setprio 0
	s_barrier
	s_add_i32 s10, s12, s29
	v_lshl_add_u64 v[152:153], s[56:57], 0, v[132:133]
	s_mov_b32 m0, s10
	ds_read_b128 v[198:201], v158 offset:16384
	ds_read_b128 v[202:205], v158 offset:17408
	ds_read_b128 v[206:209], v158 offset:18432
	ds_read_b128 v[210:213], v158 offset:19456
	ds_read_b128 v[214:217], v158 offset:20480
	ds_read_b128 v[226:229], v158 offset:21504
	ds_read_b128 v[230:233], v158 offset:22528
	ds_read_b128 v[234:237], v158 offset:23552
	global_load_lds_dwordx4 v[152:153], off
	s_add_i32 m0, s10, 0x2000
	s_add_u32 s10, s56, 0x40000
	v_lshl_add_u64 v[238:239], s[56:57], 0, v[128:129]
	s_addc_u32 s11, s57, 0
	s_add_i32 s12, s13, s29
	global_load_lds_dwordx4 v[238:239], off
	s_mov_b32 m0, s12
	v_lshl_add_u64 v[242:243], s[58:59], 0, v[130:131]
	global_load_lds_dwordx4 v132, s[10:11]
	s_add_i32 m0, s12, 0x2000
	s_nop 0
	global_load_lds_dwordx4 v128, s[10:11]
	v_lshl_add_u64 v[240:241], s[58:59], 0, v[134:135]
	s_mov_b32 m0, s0
	s_nop 0
	global_load_lds_dwordx4 v[240:241], off
	s_mov_b32 m0, s1
	s_nop 0
	global_load_lds_dwordx4 v[242:243], off
	s_waitcnt vmcnt(8)
	s_waitcnt lgkmcnt(0)
	s_barrier
; #define PG8_STAGE(bufoff, gbase, voff) do { _Pragma("unroll") for (int _i = 0; _i < 2; ++_i) \
;         __builtin_amdgcn_global_load_lds((const unsigned*)((const char*)(gbase) + (voff)[_i]), (PG8_LAS unsigned*)(lds + (bufoff) + ldsw + _i * 8192), 16, 0, 0); } while (0)
; #define PG8_LDA(dst, b, h) do { _Pragma("unroll") for (int m = 0; m < 4; ++m) _Pragma("unroll") for (int k = 0; k < 2; ++k) dst[m][k] = *(const PG8_LAS bf16x8*)(lds + PG8_SA(b, h) + aoff + m * 2048 + k * 1024); } while (0)
; #define PG8_LDB(dst, b, h) do { _Pragma("unroll") for (int n = 0; n < 2; ++n) _Pragma("unroll") for (int k = 0; k < 2; ++k) dst[n][k] = *(const PG8_LAS bf16x8*)(lds + PG8_SB(b, h) + boff + n * 2048 + k * 1024); } while (0)
; #define PG8_MMA(ai, bj, At, Bt) do { __builtin_amdgcn_s_setprio(1); _Pragma("unroll") for (int m = 0; m < 4; ++m) _Pragma("unroll") for (int n = 0; n < 2; ++n) _Pragma("unroll") for (int k = 0; k < 2; ++k) \
;         acc[ai][bj][m][n] = __builtin_amdgcn_mfma_f32_16x16x32_bf16(Bt[n][k], At[m][k], acc[ai][bj][m][n], 0, 0, 0); __builtin_amdgcn_s_setprio(0); } while (0)
; #define PG8_WAIT_V(n) asm volatile("s_waitcnt vmcnt(" #n ")" ::: "memory")
; #define PG8_WAIT_L(n) asm volatile("s_waitcnt lgkmcnt(" #n ")" ::: "memory")
; #define PG8_BAR __builtin_amdgcn_s_barrier()
; #define PG8_SCHED __builtin_amdgcn_sched_barrier(0)
; template <class Epi, class Sched, bool ALIGN_EPI = false, bool SP2 = false>
; __device__ __forceinline__ void gemm_phase(PG8_LAS unsigned char* lds, const Gemm g, const Sched& S, const Epi& E) {
;     ...
;             PG8_WAIT_V(8); PG8_WAIT_L(0); PG8_BAR; PG8_MMA(1, 0, At, B0); PG8_MMA(1, 1, At, B1); PG8_BAR; PG8_SCHED;
;             PG8_LDB(B0, 1, 0); PG8_LDB(B1, 1, 1); PG8_SCHED; PG8_LDA(At, 1, 0); PG8_STAGE(PG8_SA(0, 1), a2 + hstep, voffA);
;             PG8_WAIT_V(8); PG8_WAIT_L(0); PG8_BAR; PG8_MMA(0, 0, At, B0); PG8_MMA(0, 1, At, B1); PG8_BAR; PG8_SCHED;
	s_setprio 1
	s_waitcnt lgkmcnt(0)
	v_mfma_f32_16x16x32_bf16 v[60:63], v[144:147], v[198:201], v[60:63]
	v_mfma_f32_16x16x32_bf16 v[56:59], v[160:163], v[198:201], v[56:59]
	v_mfma_f32_16x16x32_bf16 v[44:47], v[144:147], v[206:209], v[44:47]
	v_mfma_f32_16x16x32_bf16 v[40:43], v[160:163], v[206:209], v[40:43]
	v_mfma_f32_16x16x32_bf16 v[28:31], v[144:147], v[214:217], v[28:31]
	v_mfma_f32_16x16x32_bf16 v[24:27], v[160:163], v[214:217], v[24:27]
	v_mfma_f32_16x16x32_bf16 v[12:15], v[144:147], v[230:233], v[12:15]
	v_mfma_f32_16x16x32_bf16 v[8:11], v[160:163], v[230:233], v[8:11]
	v_mfma_f32_16x16x32_bf16 v[60:63], v[148:151], v[202:205], v[60:63]
	v_mfma_f32_16x16x32_bf16 v[56:59], v[164:167], v[202:205], v[56:59]
	v_mfma_f32_16x16x32_bf16 v[44:47], v[148:151], v[210:213], v[44:47]
	v_mfma_f32_16x16x32_bf16 v[40:43], v[164:167], v[210:213], v[40:43]
	v_mfma_f32_16x16x32_bf16 v[28:31], v[148:151], v[226:229], v[28:31]
	v_mfma_f32_16x16x32_bf16 v[24:27], v[164:167], v[226:229], v[24:27]
	v_mfma_f32_16x16x32_bf16 v[12:15], v[148:151], v[234:237], v[12:15]
	v_mfma_f32_16x16x32_bf16 v[8:11], v[164:167], v[234:237], v[8:11]
	s_setprio 0
	s_setprio 1
	v_mfma_f32_16x16x32_bf16 v[52:55], v[168:171], v[198:201], v[52:55]
	v_mfma_f32_16x16x32_bf16 v[48:51], v[176:179], v[198:201], v[48:51]
	v_mfma_f32_16x16x32_bf16 v[36:39], v[168:171], v[206:209], v[36:39]
	v_mfma_f32_16x16x32_bf16 v[32:35], v[176:179], v[206:209], v[32:35]
	v_mfma_f32_16x16x32_bf16 v[20:23], v[168:171], v[214:217], v[20:23]
	v_mfma_f32_16x16x32_bf16 v[16:19], v[176:179], v[214:217], v[16:19]
	v_mfma_f32_16x16x32_bf16 v[4:7], v[168:171], v[230:233], v[4:7]
	v_mfma_f32_16x16x32_bf16 v[0:3], v[176:179], v[230:233], v[0:3]
	v_mfma_f32_16x16x32_bf16 v[52:55], v[172:175], v[202:205], v[52:55]
	v_mfma_f32_16x16x32_bf16 v[48:51], v[180:183], v[202:205], v[48:51]
	v_mfma_f32_16x16x32_bf16 v[36:39], v[172:175], v[210:213], v[36:39]
	v_mfma_f32_16x16x32_bf16 v[32:35], v[180:183], v[210:213], v[32:35]
	v_mfma_f32_16x16x32_bf16 v[20:23], v[172:175], v[226:229], v[20:23]
	v_mfma_f32_16x16x32_bf16 v[16:19], v[180:183], v[226:229], v[16:19]
	v_mfma_f32_16x16x32_bf16 v[4:7], v[172:175], v[234:237], v[4:7]
	v_mfma_f32_16x16x32_bf16 v[0:3], v[180:183], v[234:237], v[0:3]
	s_setprio 0
	s_barrier
	s_add_i32 s12, 0, 0x18000
	v_add_u32_e32 v159, s12, v156
	s_add_i32 s13, 0, 0x1c000
	ds_read_b128 v[144:147], v159
	ds_read_b128 v[148:151], v159 offset:1024
	ds_read_b128 v[160:163], v159 offset:2048
	ds_read_b128 v[164:167], v159 offset:3072
	v_add_u32_e32 v159, s13, v156
	ds_read_b128 v[168:171], v159
	ds_read_b128 v[172:175], v159 offset:1024
	ds_read_b128 v[176:179], v159 offset:2048
	ds_read_b128 v[180:183], v159 offset:3072
	s_add_u32 s10, s58, 0x40000
	s_addc_u32 s11, s59, 0
	s_mov_b32 m0, s3
	ds_read_b128 v[198:201], v158 offset:32768
	ds_read_b128 v[202:205], v158 offset:33792
	ds_read_b128 v[206:209], v158 offset:34816
	ds_read_b128 v[210:213], v158 offset:35840
	ds_read_b128 v[214:217], v158 offset:36864
	ds_read_b128 v[226:229], v158 offset:37888
	ds_read_b128 v[230:233], v158 offset:38912
	ds_read_b128 v[234:237], v158 offset:39936
	global_load_lds_dwordx4 v134, s[10:11]
	s_mov_b32 m0, s20
	s_nop 0
	global_load_lds_dwordx4 v130, s[10:11]
	s_waitcnt vmcnt(8)
	s_waitcnt lgkmcnt(0)
	s_barrier
	s_setprio 1
	s_waitcnt lgkmcnt(0)
	v_mfma_f32_16x16x32_bf16 v[124:127], v[144:147], v[198:201], v[124:127]
	v_mfma_f32_16x16x32_bf16 v[120:123], v[160:163], v[198:201], v[120:123]
	v_mfma_f32_16x16x32_bf16 v[108:111], v[144:147], v[206:209], v[108:111]
	v_mfma_f32_16x16x32_bf16 v[104:107], v[160:163], v[206:209], v[104:107]
	v_mfma_f32_16x16x32_bf16 v[92:95], v[144:147], v[214:217], v[92:95]
	v_mfma_f32_16x16x32_bf16 v[88:91], v[160:163], v[214:217], v[88:91]
	v_mfma_f32_16x16x32_bf16 v[76:79], v[144:147], v[230:233], v[76:79]
	v_mfma_f32_16x16x32_bf16 v[72:75], v[160:163], v[230:233], v[72:75]
	v_mfma_f32_16x16x32_bf16 v[124:127], v[148:151], v[202:205], v[124:127]
	v_mfma_f32_16x16x32_bf16 v[120:123], v[164:167], v[202:205], v[120:123]
	v_mfma_f32_16x16x32_bf16 v[108:111], v[148:151], v[210:213], v[108:111]
	v_mfma_f32_16x16x32_bf16 v[104:107], v[164:167], v[210:213], v[104:107]
	v_mfma_f32_16x16x32_bf16 v[92:95], v[148:151], v[226:229], v[92:95]
	v_mfma_f32_16x16x32_bf16 v[88:91], v[164:167], v[226:229], v[88:91]
	v_mfma_f32_16x16x32_bf16 v[76:79], v[148:151], v[234:237], v[76:79]
	v_mfma_f32_16x16x32_bf16 v[72:75], v[164:167], v[234:237], v[72:75]
	s_setprio 0
	s_setprio 1
	v_mfma_f32_16x16x32_bf16 v[116:119], v[168:171], v[198:201], v[116:119]
	v_mfma_f32_16x16x32_bf16 v[112:115], v[176:179], v[198:201], v[112:115]
	v_mfma_f32_16x16x32_bf16 v[100:103], v[168:171], v[206:209], v[100:103]
	v_mfma_f32_16x16x32_bf16 v[96:99], v[176:179], v[206:209], v[96:99]
	v_mfma_f32_16x16x32_bf16 v[84:87], v[168:171], v[214:217], v[84:87]
	v_mfma_f32_16x16x32_bf16 v[80:83], v[176:179], v[214:217], v[80:83]
	v_mfma_f32_16x16x32_bf16 v[68:71], v[168:171], v[230:233], v[68:71]
	v_mfma_f32_16x16x32_bf16 v[64:67], v[176:179], v[230:233], v[64:67]
	v_mfma_f32_16x16x32_bf16 v[116:119], v[172:175], v[202:205], v[116:119]
	v_mfma_f32_16x16x32_bf16 v[112:115], v[180:183], v[202:205], v[112:115]
	v_mfma_f32_16x16x32_bf16 v[100:103], v[172:175], v[210:213], v[100:103]
	v_mfma_f32_16x16x32_bf16 v[96:99], v[180:183], v[210:213], v[96:99]
	v_mfma_f32_16x16x32_bf16 v[84:87], v[172:175], v[226:229], v[84:87]
	v_mfma_f32_16x16x32_bf16 v[80:83], v[180:183], v[226:229], v[80:83]
	v_mfma_f32_16x16x32_bf16 v[68:71], v[172:175], v[234:237], v[68:71]
	v_mfma_f32_16x16x32_bf16 v[64:67], v[180:183], v[234:237], v[64:67]
	s_setprio 0
	s_barrier
; #define PG8_STAGE(bufoff, gbase, voff) do { _Pragma("unroll") for (int _i = 0; _i < 2; ++_i) \
;         __builtin_amdgcn_global_load_lds((const unsigned*)((const char*)(gbase) + (voff)[_i]), (PG8_LAS unsigned*)(lds + (bufoff) + ldsw + _i * 8192), 16, 0, 0); } while (0)
; #define PG8_LDA(dst, b, h) do { _Pragma("unroll") for (int m = 0; m < 4; ++m) _Pragma("unroll") for (int k = 0; k < 2; ++k) dst[m][k] = *(const PG8_LAS bf16x8*)(lds + PG8_SA(b, h) + aoff + m * 2048 + k * 1024); } while (0)
; #define PG8_MMA(ai, bj, At, Bt) do { __builtin_amdgcn_s_setprio(1); _Pragma("unroll") for (int m = 0; m < 4; ++m) _Pragma("unroll") for (int n = 0; n < 2; ++n) _Pragma("unroll") for (int k = 0; k < 2; ++k) \
;         acc[ai][bj][m][n] = __builtin_amdgcn_mfma_f32_16x16x32_bf16(Bt[n][k], At[m][k], acc[ai][bj][m][n], 0, 0, 0); __builtin_amdgcn_s_setprio(0); } while (0)
; #define PG8_WAIT_V(n) asm volatile("s_waitcnt vmcnt(" #n ")" ::: "memory")
; #define PG8_WAIT_L(n) asm volatile("s_waitcnt lgkmcnt(" #n ")" ::: "memory")
; #define PG8_BAR __builtin_amdgcn_s_barrier()
; #define PG8_SCHED __builtin_amdgcn_sched_barrier(0)
; template <class Epi, class Sched, bool ALIGN_EPI = false, bool SP2 = false>
; __device__ __forceinline__ void gemm_phase(PG8_LAS unsigned char* lds, const Gemm g, const Sched& S, const Epi& E) {
;     ...
;             PG8_LDA(At, 1, 1); PG8_STAGE(PG8_SB(1, 0), b3, voffB); PG8_STAGE(PG8_SB(1, 1), b3 + hstep, voffB); PG8_STAGE(PG8_SA(1, 0), a3, voffA);
;             PG8_WAIT_V(8); PG8_WAIT_L(0); PG8_BAR; PG8_MMA(1, 0, At, B0); PG8_MMA(1, 1, At, B1); PG8_BAR; PG8_SCHED;
	s_add_i32 s10, s12, s29
	v_lshl_add_u64 v[152:153], v[152:153], 0, s[34:35]
	s_mov_b32 m0, s10
	ds_read_b128 v[198:201], v158 offset:49152
	ds_read_b128 v[202:205], v158 offset:50176
	ds_read_b128 v[206:209], v158 offset:51200
	ds_read_b128 v[210:213], v158 offset:52224
	ds_read_b128 v[214:217], v158 offset:53248
	ds_read_b128 v[226:229], v158 offset:54272
	ds_read_b128 v[230:233], v158 offset:55296
	ds_read_b128 v[234:237], v158 offset:56320
	global_load_lds_dwordx4 v[152:153], off
	s_add_i32 m0, s10, 0x2000
	s_add_u32 s10, s56, 0x40080
	v_lshl_add_u64 v[152:153], v[238:239], 0, s[34:35]
	s_addc_u32 s11, s57, 0
	s_add_i32 s12, s13, s29
	global_load_lds_dwordx4 v[152:153], off
	s_mov_b32 m0, s12
	s_nop 0
	global_load_lds_dwordx4 v132, s[10:11]
	s_add_i32 m0, s12, 0x2000
	s_nop 0
	global_load_lds_dwordx4 v128, s[10:11]
	v_lshl_add_u64 v[152:153], v[240:241], 0, s[34:35]
	s_mov_b32 m0, s8
	s_nop 0
	global_load_lds_dwordx4 v[152:153], off
	v_lshl_add_u64 v[152:153], v[242:243], 0, s[34:35]
	s_mov_b32 m0, s21
	s_nop 0
	global_load_lds_dwordx4 v[152:153], off
	s_waitcnt vmcnt(8)
	s_waitcnt lgkmcnt(0)
	s_barrier
	s_setprio 1
	s_waitcnt lgkmcnt(0)
	v_mfma_f32_16x16x32_bf16 v[60:63], v[144:147], v[198:201], v[60:63]
	v_mfma_f32_16x16x32_bf16 v[56:59], v[160:163], v[198:201], v[56:59]
	v_mfma_f32_16x16x32_bf16 v[44:47], v[144:147], v[206:209], v[44:47]
	v_mfma_f32_16x16x32_bf16 v[40:43], v[160:163], v[206:209], v[40:43]
	v_mfma_f32_16x16x32_bf16 v[28:31], v[144:147], v[214:217], v[28:31]
	v_mfma_f32_16x16x32_bf16 v[24:27], v[160:163], v[214:217], v[24:27]
	v_mfma_f32_16x16x32_bf16 v[12:15], v[144:147], v[230:233], v[12:15]
	v_mfma_f32_16x16x32_bf16 v[8:11], v[160:163], v[230:233], v[8:11]
	v_mfma_f32_16x16x32_bf16 v[60:63], v[148:151], v[202:205], v[60:63]
	v_mfma_f32_16x16x32_bf16 v[56:59], v[164:167], v[202:205], v[56:59]
	v_mfma_f32_16x16x32_bf16 v[44:47], v[148:151], v[210:213], v[44:47]
	v_mfma_f32_16x16x32_bf16 v[40:43], v[164:167], v[210:213], v[40:43]
	v_mfma_f32_16x16x32_bf16 v[28:31], v[148:151], v[226:229], v[28:31]
	v_mfma_f32_16x16x32_bf16 v[24:27], v[164:167], v[226:229], v[24:27]
	v_mfma_f32_16x16x32_bf16 v[12:15], v[148:151], v[234:237], v[12:15]
	v_mfma_f32_16x16x32_bf16 v[8:11], v[164:167], v[234:237], v[8:11]
	s_setprio 0
	s_setprio 1
	v_mfma_f32_16x16x32_bf16 v[52:55], v[168:171], v[198:201], v[52:55]
	v_mfma_f32_16x16x32_bf16 v[48:51], v[176:179], v[198:201], v[48:51]
	v_mfma_f32_16x16x32_bf16 v[36:39], v[168:171], v[206:209], v[36:39]
	v_mfma_f32_16x16x32_bf16 v[32:35], v[176:179], v[206:209], v[32:35]
	v_mfma_f32_16x16x32_bf16 v[20:23], v[168:171], v[214:217], v[20:23]
	v_mfma_f32_16x16x32_bf16 v[16:19], v[176:179], v[214:217], v[16:19]
	v_mfma_f32_16x16x32_bf16 v[4:7], v[168:171], v[230:233], v[4:7]
	v_mfma_f32_16x16x32_bf16 v[0:3], v[176:179], v[230:233], v[0:3]
	v_mfma_f32_16x16x32_bf16 v[52:55], v[172:175], v[202:205], v[52:55]
	v_mfma_f32_16x16x32_bf16 v[48:51], v[180:183], v[202:205], v[48:51]
	v_mfma_f32_16x16x32_bf16 v[36:39], v[172:175], v[210:213], v[36:39]
	v_mfma_f32_16x16x32_bf16 v[32:35], v[180:183], v[210:213], v[32:35]
	v_mfma_f32_16x16x32_bf16 v[20:23], v[172:175], v[226:229], v[20:23]
	v_mfma_f32_16x16x32_bf16 v[16:19], v[180:183], v[226:229], v[16:19]
	v_mfma_f32_16x16x32_bf16 v[4:7], v[172:175], v[234:237], v[4:7]
	v_mfma_f32_16x16x32_bf16 v[0:3], v[180:183], v[234:237], v[0:3]
	s_setprio 0
	s_barrier
	s_add_i32 s31, s31, 2
	s_add_u32 s54, s54, 0x100
	s_addc_u32 s55, s55, 0
	s_add_u32 vcc_hi, vcc_hi, 0x100
	s_addc_u32 s30, s30, 0
	s_cmp_gt_u32 s31, 13
	s_cbranch_scc0 .LBB0_132
	s_and_b64 vcc, exec, s[22:23]
	s_cbranch_vccz .LBB0_135
	s_barrier

; #define PG8_STAGE(bufoff, gbase, voff) do { _Pragma("unroll") for (int _i = 0; _i < 2; ++_i) \
;         __builtin_amdgcn_global_load_lds((const unsigned*)((const char*)(gbase) + (voff)[_i]), (PG8_LAS unsigned*)(lds + (bufoff) + ldsw + _i * 8192), 16, 0, 0); } while (0)
; #define PG8_LDA(dst, b, h) do { _Pragma("unroll") for (int m = 0; m < 4; ++m) _Pragma("unroll") for (int k = 0; k < 2; ++k) dst[m][k] = *(const PG8_LAS bf16x8*)(lds + PG8_SA(b, h) + aoff + m * 2048 + k * 1024); } while (0)
; #define PG8_LDB(dst, b, h) do { _Pragma("unroll") for (int n = 0; n < 2; ++n) _Pragma("unroll") for (int k = 0; k < 2; ++k) dst[n][k] = *(const PG8_LAS bf16x8*)(lds + PG8_SB(b, h) + boff + n * 2048 + k * 1024); } while (0)
; #define PG8_MMA(ai, bj, At, Bt) do { __builtin_amdgcn_s_setprio(1); _Pragma("unroll") for (int m = 0; m < 4; ++m) _Pragma("unroll") for (int n = 0; n < 2; ++n) _Pragma("unroll") for (int k = 0; k < 2; ++k) \
;         acc[ai][bj][m][n] = __builtin_amdgcn_mfma_f32_16x16x32_bf16(Bt[n][k], At[m][k], acc[ai][bj][m][n], 0, 0, 0); __builtin_amdgcn_s_setprio(0); } while (0)
; #define PG8_WAIT_V(n) asm volatile("s_waitcnt vmcnt(" #n ")" ::: "memory")
; #define PG8_WAIT_L(n) asm volatile("s_waitcnt lgkmcnt(" #n ")" ::: "memory")
; #define PG8_BAR __builtin_amdgcn_s_barrier()
; #define PG8_SCHED __builtin_amdgcn_sched_barrier(0)
; template <class Epi, class Sched, bool ALIGN_EPI = false, bool SP2 = false>
; __device__ __forceinline__ void gemm_phase(PG8_LAS unsigned char* lds, const Gemm g, const Sched& S, const Epi& E) {
;     ...
;             PG8_LDB(B0, 0, 0); PG8_LDB(B1, 0, 1); PG8_SCHED; PG8_LDA(At, 0, 0); PG8_STAGE(PG8_SA(1, 1), a1 + hstep, voffA);
;             PG8_WAIT_V(8); PG8_WAIT_L(0); PG8_BAR; PG8_MMA(0, 0, At, B0); PG8_MMA(0, 1, At, B1); PG8_BAR; PG8_SCHED;
;             PG8_LDA(At, 0, 1); PG8_STAGE(PG8_SB(0, 0), b2, voffB); PG8_STAGE(PG8_SB(0, 1), b2 + hstep, voffB); PG8_STAGE(PG8_SA(0, 0), a2, voffA);
.LBB0_418:
	s_add_u32 s11, s58, 0xfffc0080
	s_addc_u32 s12, s59, -1
	s_add_i32 s13, 0, 0x10000
	s_cmp_eq_u32 s10, 12
	s_cselect_b32 s63, s53, s12
	s_cselect_b32 s62, vcc_lo, s11
	s_cselect_b32 s61, s51, s31
	s_cselect_b32 s60, vcc_hi, s30
	s_add_i32 s11, 0, 0x14000
	v_add_u32_e32 v154, s13, v143
	v_add_u32_e32 v170, s11, v143
	ds_read_b128 v[138:141], v154
	ds_read_b128 v[146:149], v154 offset:1024
	ds_read_b128 v[150:153], v154 offset:2048
	ds_read_b128 v[154:157], v154 offset:3072
	ds_read_b128 v[158:161], v170
	ds_read_b128 v[162:165], v170 offset:1024
	ds_read_b128 v[166:169], v170 offset:2048
	ds_read_b128 v[170:173], v170 offset:3072
	s_add_i32 m0, s8, 0xc000
	ds_read_b128 v[174:177], v145
	ds_read_b128 v[178:181], v145 offset:1024
	ds_read_b128 v[198:201], v145 offset:2048
	ds_read_b128 v[202:205], v145 offset:3072
	ds_read_b128 v[206:209], v145 offset:4096
	ds_read_b128 v[210:213], v145 offset:5120
	ds_read_b128 v[214:217], v145 offset:6144
	ds_read_b128 v[232:235], v145 offset:7168
	global_load_lds_dwordx4 v134, s[58:59]
	s_add_i32 m0, s8, 0xe000
	s_nop 0
	global_load_lds_dwordx4 v136, s[58:59]
	s_waitcnt vmcnt(8)
	s_waitcnt lgkmcnt(0)
	s_barrier
	s_setprio 1
	s_waitcnt lgkmcnt(0)
	v_mfma_f32_16x16x32_bf16 v[124:127], v[138:141], v[174:177], v[124:127]
	v_mfma_f32_16x16x32_bf16 v[120:123], v[150:153], v[174:177], v[120:123]
	v_mfma_f32_16x16x32_bf16 v[108:111], v[138:141], v[198:201], v[108:111]
	v_mfma_f32_16x16x32_bf16 v[104:107], v[150:153], v[198:201], v[104:107]
	v_mfma_f32_16x16x32_bf16 v[92:95], v[138:141], v[206:209], v[92:95]
	v_mfma_f32_16x16x32_bf16 v[88:91], v[150:153], v[206:209], v[88:91]
	v_mfma_f32_16x16x32_bf16 v[76:79], v[138:141], v[214:217], v[76:79]
	v_mfma_f32_16x16x32_bf16 v[72:75], v[150:153], v[214:217], v[72:75]
	v_mfma_f32_16x16x32_bf16 v[124:127], v[146:149], v[178:181], v[124:127]
	v_mfma_f32_16x16x32_bf16 v[120:123], v[154:157], v[178:181], v[120:123]
	v_mfma_f32_16x16x32_bf16 v[108:111], v[146:149], v[202:205], v[108:111]
	v_mfma_f32_16x16x32_bf16 v[104:107], v[154:157], v[202:205], v[104:107]
	v_mfma_f32_16x16x32_bf16 v[92:95], v[146:149], v[210:213], v[92:95]
	v_mfma_f32_16x16x32_bf16 v[88:91], v[154:157], v[210:213], v[88:91]
	v_mfma_f32_16x16x32_bf16 v[76:79], v[146:149], v[232:235], v[76:79]
	v_mfma_f32_16x16x32_bf16 v[72:75], v[154:157], v[232:235], v[72:75]
	s_setprio 0
	s_setprio 1
	v_mfma_f32_16x16x32_bf16 v[116:119], v[158:161], v[174:177], v[116:119]
	v_mfma_f32_16x16x32_bf16 v[112:115], v[166:169], v[174:177], v[112:115]
	v_mfma_f32_16x16x32_bf16 v[100:103], v[158:161], v[198:201], v[100:103]
	v_mfma_f32_16x16x32_bf16 v[96:99], v[166:169], v[198:201], v[96:99]
	v_mfma_f32_16x16x32_bf16 v[84:87], v[158:161], v[206:209], v[84:87]
	v_mfma_f32_16x16x32_bf16 v[80:83], v[166:169], v[206:209], v[80:83]
	v_mfma_f32_16x16x32_bf16 v[68:71], v[158:161], v[214:217], v[68:71]
	v_mfma_f32_16x16x32_bf16 v[64:67], v[166:169], v[214:217], v[64:67]
	v_mfma_f32_16x16x32_bf16 v[116:119], v[162:165], v[178:181], v[116:119]
	v_mfma_f32_16x16x32_bf16 v[112:115], v[170:173], v[178:181], v[112:115]
	v_mfma_f32_16x16x32_bf16 v[100:103], v[162:165], v[202:205], v[100:103]
	v_mfma_f32_16x16x32_bf16 v[96:99], v[170:173], v[202:205], v[96:99]
	v_mfma_f32_16x16x32_bf16 v[84:87], v[162:165], v[210:213], v[84:87]
	v_mfma_f32_16x16x32_bf16 v[80:83], v[170:173], v[210:213], v[80:83]
	v_mfma_f32_16x16x32_bf16 v[68:71], v[162:165], v[232:235], v[68:71]
	v_mfma_f32_16x16x32_bf16 v[64:67], v[170:173], v[232:235], v[64:67]
	s_setprio 0
	s_barrier
	s_add_i32 s12, s13, s3
	v_lshl_add_u64 v[182:183], s[60:61], 0, v[188:189]
	s_mov_b32 m0, s12
	ds_read_b128 v[174:177], v145 offset:16384
	ds_read_b128 v[178:181], v145 offset:17408
	ds_read_b128 v[198:201], v145 offset:18432
	ds_read_b128 v[202:205], v145 offset:19456
	ds_read_b128 v[206:209], v145 offset:20480
	ds_read_b128 v[210:213], v145 offset:21504
	ds_read_b128 v[214:217], v145 offset:22528
	ds_read_b128 v[232:235], v145 offset:23552
	global_load_lds_dwordx4 v[182:183], off
	s_add_i32 m0, s12, 0x2000
	s_add_u32 s12, s60, 0x40000
	v_lshl_add_u64 v[236:237], s[60:61], 0, v[128:129]
	s_addc_u32 s13, s61, 0
	s_add_i32 s11, s11, s3
	global_load_lds_dwordx4 v[236:237], off
	s_mov_b32 m0, s11
	v_lshl_add_u64 v[240:241], s[62:63], 0, v[130:131]
	global_load_lds_dwordx4 v188, s[12:13]
	s_add_i32 m0, s11, 0x2000
	s_nop 0
	global_load_lds_dwordx4 v128, s[12:13]
	v_lshl_add_u64 v[238:239], s[62:63], 0, v[132:133]
	s_mov_b32 m0, s8
	s_nop 0
	global_load_lds_dwordx4 v[238:239], off
	s_mov_b32 m0, s9
	s_nop 0
	global_load_lds_dwordx4 v[240:241], off
	s_waitcnt vmcnt(8)
	s_waitcnt lgkmcnt(0)
	s_barrier
; #define PG8_STAGE(bufoff, gbase, voff) do { _Pragma("unroll") for (int _i = 0; _i < 2; ++_i) \
;         __builtin_amdgcn_global_load_lds((const unsigned*)((const char*)(gbase) + (voff)[_i]), (PG8_LAS unsigned*)(lds + (bufoff) + ldsw + _i * 8192), 16, 0, 0); } while (0)
; #define PG8_LDA(dst, b, h) do { _Pragma("unroll") for (int m = 0; m < 4; ++m) _Pragma("unroll") for (int k = 0; k < 2; ++k) dst[m][k] = *(const PG8_LAS bf16x8*)(lds + PG8_SA(b, h) + aoff + m * 2048 + k * 1024); } while (0)
; #define PG8_LDB(dst, b, h) do { _Pragma("unroll") for (int n = 0; n < 2; ++n) _Pragma("unroll") for (int k = 0; k < 2; ++k) dst[n][k] = *(const PG8_LAS bf16x8*)(lds + PG8_SB(b, h) + boff + n * 2048 + k * 1024); } while (0)
; #define PG8_MMA(ai, bj, At, Bt) do { __builtin_amdgcn_s_setprio(1); _Pragma("unroll") for (int m = 0; m < 4; ++m) _Pragma("unroll") for (int n = 0; n < 2; ++n) _Pragma("unroll") for (int k = 0; k < 2; ++k) \
;         acc[ai][bj][m][n] = __builtin_amdgcn_mfma_f32_16x16x32_bf16(Bt[n][k], At[m][k], acc[ai][bj][m][n], 0, 0, 0); __builtin_amdgcn_s_setprio(0); } while (0)
; #define PG8_WAIT_V(n) asm volatile("s_waitcnt vmcnt(" #n ")" ::: "memory")
; #define PG8_WAIT_L(n) asm volatile("s_waitcnt lgkmcnt(" #n ")" ::: "memory")
; #define PG8_BAR __builtin_amdgcn_s_barrier()
; #define PG8_SCHED __builtin_amdgcn_sched_barrier(0)
; template <class Epi, class Sched, bool ALIGN_EPI = false, bool SP2 = false>
; __device__ __forceinline__ void gemm_phase(PG8_LAS unsigned char* lds, const Gemm g, const Sched& S, const Epi& E) {
;     ...
;             PG8_WAIT_V(8); PG8_WAIT_L(0); PG8_BAR; PG8_MMA(1, 0, At, B0); PG8_MMA(1, 1, At, B1); PG8_BAR; PG8_SCHED;
;             PG8_LDB(B0, 1, 0); PG8_LDB(B1, 1, 1); PG8_SCHED; PG8_LDA(At, 1, 0); PG8_STAGE(PG8_SA(0, 1), a2 + hstep, voffA);
;             PG8_WAIT_V(8); PG8_WAIT_L(0); PG8_BAR; PG8_MMA(0, 0, At, B0); PG8_MMA(0, 1, At, B1); PG8_BAR; PG8_SCHED;
	s_setprio 1
	s_waitcnt lgkmcnt(0)
	v_mfma_f32_16x16x32_bf16 v[60:63], v[138:141], v[174:177], v[60:63]
	v_mfma_f32_16x16x32_bf16 v[56:59], v[150:153], v[174:177], v[56:59]
	v_mfma_f32_16x16x32_bf16 v[44:47], v[138:141], v[198:201], v[44:47]
	v_mfma_f32_16x16x32_bf16 v[40:43], v[150:153], v[198:201], v[40:43]
	v_mfma_f32_16x16x32_bf16 v[28:31], v[138:141], v[206:209], v[28:31]
	v_mfma_f32_16x16x32_bf16 v[24:27], v[150:153], v[206:209], v[24:27]
	v_mfma_f32_16x16x32_bf16 v[12:15], v[138:141], v[214:217], v[12:15]
	v_mfma_f32_16x16x32_bf16 v[8:11], v[150:153], v[214:217], v[8:11]
	v_mfma_f32_16x16x32_bf16 v[60:63], v[146:149], v[178:181], v[60:63]
	v_mfma_f32_16x16x32_bf16 v[56:59], v[154:157], v[178:181], v[56:59]
	v_mfma_f32_16x16x32_bf16 v[44:47], v[146:149], v[202:205], v[44:47]
	v_mfma_f32_16x16x32_bf16 v[40:43], v[154:157], v[202:205], v[40:43]
	v_mfma_f32_16x16x32_bf16 v[28:31], v[146:149], v[210:213], v[28:31]
	v_mfma_f32_16x16x32_bf16 v[24:27], v[154:157], v[210:213], v[24:27]
	v_mfma_f32_16x16x32_bf16 v[12:15], v[146:149], v[232:235], v[12:15]
	v_mfma_f32_16x16x32_bf16 v[8:11], v[154:157], v[232:235], v[8:11]
	s_setprio 0
	s_setprio 1
	v_mfma_f32_16x16x32_bf16 v[52:55], v[158:161], v[174:177], v[52:55]
	v_mfma_f32_16x16x32_bf16 v[48:51], v[166:169], v[174:177], v[48:51]
	v_mfma_f32_16x16x32_bf16 v[36:39], v[158:161], v[198:201], v[36:39]
	v_mfma_f32_16x16x32_bf16 v[32:35], v[166:169], v[198:201], v[32:35]
	v_mfma_f32_16x16x32_bf16 v[20:23], v[158:161], v[206:209], v[20:23]
	v_mfma_f32_16x16x32_bf16 v[16:19], v[166:169], v[206:209], v[16:19]
	v_mfma_f32_16x16x32_bf16 v[4:7], v[158:161], v[214:217], v[4:7]
	v_mfma_f32_16x16x32_bf16 v[0:3], v[166:169], v[214:217], v[0:3]
	v_mfma_f32_16x16x32_bf16 v[52:55], v[162:165], v[178:181], v[52:55]
	v_mfma_f32_16x16x32_bf16 v[48:51], v[170:173], v[178:181], v[48:51]
	v_mfma_f32_16x16x32_bf16 v[36:39], v[162:165], v[202:205], v[36:39]
	v_mfma_f32_16x16x32_bf16 v[32:35], v[170:173], v[202:205], v[32:35]
	v_mfma_f32_16x16x32_bf16 v[20:23], v[162:165], v[210:213], v[20:23]
	v_mfma_f32_16x16x32_bf16 v[16:19], v[170:173], v[210:213], v[16:19]
	v_mfma_f32_16x16x32_bf16 v[4:7], v[162:165], v[232:235], v[4:7]
	v_mfma_f32_16x16x32_bf16 v[0:3], v[170:173], v[232:235], v[0:3]
	s_setprio 0
	s_barrier
	s_add_i32 s11, 0, 0x18000
	s_add_i32 s14, 0, 0x1c000
	v_add_u32_e32 v154, s11, v143
	v_add_u32_e32 v170, s14, v143
	ds_read_b128 v[138:141], v154
	ds_read_b128 v[146:149], v154 offset:1024
	ds_read_b128 v[150:153], v154 offset:2048
	ds_read_b128 v[154:157], v154 offset:3072
	ds_read_b128 v[158:161], v170
	ds_read_b128 v[162:165], v170 offset:1024
	ds_read_b128 v[166:169], v170 offset:2048
	ds_read_b128 v[170:173], v170 offset:3072
	s_add_u32 s12, s62, 0x40000
	s_addc_u32 s13, s63, 0
	s_mov_b32 m0, s20
	ds_read_b128 v[174:177], v145 offset:32768
	ds_read_b128 v[178:181], v145 offset:33792
	ds_read_b128 v[198:201], v145 offset:34816
	ds_read_b128 v[202:205], v145 offset:35840
	ds_read_b128 v[206:209], v145 offset:36864
	ds_read_b128 v[210:213], v145 offset:37888
	ds_read_b128 v[214:217], v145 offset:38912
	ds_read_b128 v[232:235], v145 offset:39936
	global_load_lds_dwordx4 v132, s[12:13]
	s_mov_b32 m0, s21
	s_nop 0
	global_load_lds_dwordx4 v130, s[12:13]
	s_waitcnt vmcnt(8)
	s_waitcnt lgkmcnt(0)
	s_barrier
	s_setprio 1
	s_waitcnt lgkmcnt(0)
	v_mfma_f32_16x16x32_bf16 v[124:127], v[138:141], v[174:177], v[124:127]
	v_mfma_f32_16x16x32_bf16 v[120:123], v[150:153], v[174:177], v[120:123]
	v_mfma_f32_16x16x32_bf16 v[108:111], v[138:141], v[198:201], v[108:111]
	v_mfma_f32_16x16x32_bf16 v[104:107], v[150:153], v[198:201], v[104:107]
	v_mfma_f32_16x16x32_bf16 v[92:95], v[138:141], v[206:209], v[92:95]
	v_mfma_f32_16x16x32_bf16 v[88:91], v[150:153], v[206:209], v[88:91]
	v_mfma_f32_16x16x32_bf16 v[76:79], v[138:141], v[214:217], v[76:79]
	v_mfma_f32_16x16x32_bf16 v[72:75], v[150:153], v[214:217], v[72:75]
	v_mfma_f32_16x16x32_bf16 v[124:127], v[146:149], v[178:181], v[124:127]
	v_mfma_f32_16x16x32_bf16 v[120:123], v[154:157], v[178:181], v[120:123]
	v_mfma_f32_16x16x32_bf16 v[108:111], v[146:149], v[202:205], v[108:111]
	v_mfma_f32_16x16x32_bf16 v[104:107], v[154:157], v[202:205], v[104:107]
	v_mfma_f32_16x16x32_bf16 v[92:95], v[146:149], v[210:213], v[92:95]
	v_mfma_f32_16x16x32_bf16 v[88:91], v[154:157], v[210:213], v[88:91]
	v_mfma_f32_16x16x32_bf16 v[76:79], v[146:149], v[232:235], v[76:79]
	v_mfma_f32_16x16x32_bf16 v[72:75], v[154:157], v[232:235], v[72:75]
	s_setprio 0
	s_setprio 1
	v_mfma_f32_16x16x32_bf16 v[116:119], v[158:161], v[174:177], v[116:119]
	v_mfma_f32_16x16x32_bf16 v[112:115], v[166:169], v[174:177], v[112:115]
	v_mfma_f32_16x16x32_bf16 v[100:103], v[158:161], v[198:201], v[100:103]
	v_mfma_f32_16x16x32_bf16 v[96:99], v[166:169], v[198:201], v[96:99]
	v_mfma_f32_16x16x32_bf16 v[84:87], v[158:161], v[206:209], v[84:87]
	v_mfma_f32_16x16x32_bf16 v[80:83], v[166:169], v[206:209], v[80:83]
	v_mfma_f32_16x16x32_bf16 v[68:71], v[158:161], v[214:217], v[68:71]
	v_mfma_f32_16x16x32_bf16 v[64:67], v[166:169], v[214:217], v[64:67]
	v_mfma_f32_16x16x32_bf16 v[116:119], v[162:165], v[178:181], v[116:119]
	v_mfma_f32_16x16x32_bf16 v[112:115], v[170:173], v[178:181], v[112:115]
	v_mfma_f32_16x16x32_bf16 v[100:103], v[162:165], v[202:205], v[100:103]
	v_mfma_f32_16x16x32_bf16 v[96:99], v[170:173], v[202:205], v[96:99]
	v_mfma_f32_16x16x32_bf16 v[84:87], v[162:165], v[210:213], v[84:87]
	v_mfma_f32_16x16x32_bf16 v[80:83], v[170:173], v[210:213], v[80:83]
	v_mfma_f32_16x16x32_bf16 v[68:71], v[162:165], v[232:235], v[68:71]
	v_mfma_f32_16x16x32_bf16 v[64:67], v[170:173], v[232:235], v[64:67]
	s_setprio 0
	s_barrier
; #define PG8_STAGE(bufoff, gbase, voff) do { _Pragma("unroll") for (int _i = 0; _i < 2; ++_i) \
;         __builtin_amdgcn_global_load_lds((const unsigned*)((const char*)(gbase) + (voff)[_i]), (PG8_LAS unsigned*)(lds + (bufoff) + ldsw + _i * 8192), 16, 0, 0); } while (0)
; #define PG8_LDA(dst, b, h) do { _Pragma("unroll") for (int m = 0; m < 4; ++m) _Pragma("unroll") for (int k = 0; k < 2; ++k) dst[m][k] = *(const PG8_LAS bf16x8*)(lds + PG8_SA(b, h) + aoff + m * 2048 + k * 1024); } while (0)
; #define PG8_MMA(ai, bj, At, Bt) do { __builtin_amdgcn_s_setprio(1); _Pragma("unroll") for (int m = 0; m < 4; ++m) _Pragma("unroll") for (int n = 0; n < 2; ++n) _Pragma("unroll") for (int k = 0; k < 2; ++k) \
;         acc[ai][bj][m][n] = __builtin_amdgcn_mfma_f32_16x16x32_bf16(Bt[n][k], At[m][k], acc[ai][bj][m][n], 0, 0, 0); __builtin_amdgcn_s_setprio(0); } while (0)
; #define PG8_WAIT_V(n) asm volatile("s_waitcnt vmcnt(" #n ")" ::: "memory")
; #define PG8_WAIT_L(n) asm volatile("s_waitcnt lgkmcnt(" #n ")" ::: "memory")
; #define PG8_BAR __builtin_amdgcn_s_barrier()
; #define PG8_SCHED __builtin_amdgcn_sched_barrier(0)
; template <class Epi, class Sched, bool ALIGN_EPI = false, bool SP2 = false>
; __device__ __forceinline__ void gemm_phase(PG8_LAS unsigned char* lds, const Gemm g, const Sched& S, const Epi& E) {
;     ...
;             PG8_LDA(At, 1, 1); PG8_STAGE(PG8_SB(1, 0), b3, voffB); PG8_STAGE(PG8_SB(1, 1), b3 + hstep, voffB); PG8_STAGE(PG8_SA(1, 0), a3, voffA);
;             PG8_WAIT_V(8); PG8_WAIT_L(0); PG8_BAR; PG8_MMA(1, 0, At, B0); PG8_MMA(1, 1, At, B1); PG8_BAR; PG8_SCHED;
;     ...
;         if constexpr (ALIGN_EPI) { if (wr == 0) PG8_BAR; }
	s_add_i32 s11, s11, s3
	v_lshl_add_u64 v[182:183], v[182:183], 0, s[34:35]
	s_mov_b32 m0, s11
	ds_read_b128 v[174:177], v145 offset:49152
	ds_read_b128 v[178:181], v145 offset:50176
	ds_read_b128 v[198:201], v145 offset:51200
	ds_read_b128 v[202:205], v145 offset:52224
	ds_read_b128 v[206:209], v145 offset:53248
	ds_read_b128 v[210:213], v145 offset:54272
	ds_read_b128 v[214:217], v145 offset:55296
	ds_read_b128 v[232:235], v145 offset:56320
	global_load_lds_dwordx4 v[182:183], off
	s_add_i32 m0, s11, 0x2000
	s_add_u32 s12, s60, 0x40080
	v_lshl_add_u64 v[182:183], v[236:237], 0, s[34:35]
	s_addc_u32 s13, s61, 0
	s_add_i32 s11, s14, s3
	global_load_lds_dwordx4 v[182:183], off
	s_mov_b32 m0, s11
	s_nop 0
	global_load_lds_dwordx4 v188, s[12:13]
	s_add_i32 m0, s11, 0x2000
	s_nop 0
	global_load_lds_dwordx4 v128, s[12:13]
	v_lshl_add_u64 v[182:183], v[238:239], 0, s[34:35]
	s_mov_b32 m0, s29
	s_nop 0
	global_load_lds_dwordx4 v[182:183], off
	v_lshl_add_u64 v[182:183], v[240:241], 0, s[34:35]
	s_mov_b32 m0, s39
	s_nop 0
	global_load_lds_dwordx4 v[182:183], off
	s_waitcnt vmcnt(8)
	s_waitcnt lgkmcnt(0)
	s_barrier
	s_setprio 1
	s_waitcnt lgkmcnt(0)
	v_mfma_f32_16x16x32_bf16 v[60:63], v[138:141], v[174:177], v[60:63]
	v_mfma_f32_16x16x32_bf16 v[56:59], v[150:153], v[174:177], v[56:59]
	v_mfma_f32_16x16x32_bf16 v[44:47], v[138:141], v[198:201], v[44:47]
	v_mfma_f32_16x16x32_bf16 v[40:43], v[150:153], v[198:201], v[40:43]
	v_mfma_f32_16x16x32_bf16 v[28:31], v[138:141], v[206:209], v[28:31]
	v_mfma_f32_16x16x32_bf16 v[24:27], v[150:153], v[206:209], v[24:27]
	v_mfma_f32_16x16x32_bf16 v[12:15], v[138:141], v[214:217], v[12:15]
	v_mfma_f32_16x16x32_bf16 v[8:11], v[150:153], v[214:217], v[8:11]
	v_mfma_f32_16x16x32_bf16 v[60:63], v[146:149], v[178:181], v[60:63]
	v_mfma_f32_16x16x32_bf16 v[56:59], v[154:157], v[178:181], v[56:59]
	v_mfma_f32_16x16x32_bf16 v[44:47], v[146:149], v[202:205], v[44:47]
	v_mfma_f32_16x16x32_bf16 v[40:43], v[154:157], v[202:205], v[40:43]
	v_mfma_f32_16x16x32_bf16 v[28:31], v[146:149], v[210:213], v[28:31]
	v_mfma_f32_16x16x32_bf16 v[24:27], v[154:157], v[210:213], v[24:27]
	v_mfma_f32_16x16x32_bf16 v[12:15], v[146:149], v[232:235], v[12:15]
	v_mfma_f32_16x16x32_bf16 v[8:11], v[154:157], v[232:235], v[8:11]
	s_setprio 0
	s_setprio 1
	v_mfma_f32_16x16x32_bf16 v[52:55], v[158:161], v[174:177], v[52:55]
	v_mfma_f32_16x16x32_bf16 v[48:51], v[166:169], v[174:177], v[48:51]
	v_mfma_f32_16x16x32_bf16 v[36:39], v[158:161], v[198:201], v[36:39]
	v_mfma_f32_16x16x32_bf16 v[32:35], v[166:169], v[198:201], v[32:35]
	v_mfma_f32_16x16x32_bf16 v[20:23], v[158:161], v[206:209], v[20:23]
	v_mfma_f32_16x16x32_bf16 v[16:19], v[166:169], v[206:209], v[16:19]
	v_mfma_f32_16x16x32_bf16 v[4:7], v[158:161], v[214:217], v[4:7]
	v_mfma_f32_16x16x32_bf16 v[0:3], v[166:169], v[214:217], v[0:3]
	v_mfma_f32_16x16x32_bf16 v[52:55], v[162:165], v[178:181], v[52:55]
	v_mfma_f32_16x16x32_bf16 v[48:51], v[170:173], v[178:181], v[48:51]
	v_mfma_f32_16x16x32_bf16 v[36:39], v[162:165], v[202:205], v[36:39]
	v_mfma_f32_16x16x32_bf16 v[32:35], v[170:173], v[202:205], v[32:35]
	v_mfma_f32_16x16x32_bf16 v[20:23], v[162:165], v[210:213], v[20:23]
	v_mfma_f32_16x16x32_bf16 v[16:19], v[170:173], v[210:213], v[16:19]
	v_mfma_f32_16x16x32_bf16 v[4:7], v[162:165], v[232:235], v[4:7]
	v_mfma_f32_16x16x32_bf16 v[0:3], v[170:173], v[232:235], v[0:3]
	s_setprio 0
	s_barrier
	s_add_i32 s10, s10, 2
	s_add_u32 s58, s58, 0x100
	s_addc_u32 s59, s59, 0
	s_add_u32 s30, s30, 0x100
	s_addc_u32 s31, s31, 0
	s_cmp_gt_u32 s10, 13
	s_cbranch_scc0 .LBB0_418
	s_and_b64 vcc, exec, s[48:49]
	s_cbranch_vccz .LBB0_421
	s_barrier

; #define PG8_STAGE(bufoff, gbase, voff) do { _Pragma("unroll") for (int _i = 0; _i < 2; ++_i) \
;         __builtin_amdgcn_global_load_lds((const unsigned*)((const char*)(gbase) + (voff)[_i]), (PG8_LAS unsigned*)(lds + (bufoff) + ldsw + _i * 8192), 16, 0, 0); } while (0)
; #define PG8_LDA(dst, b, h) do { _Pragma("unroll") for (int m = 0; m < 4; ++m) _Pragma("unroll") for (int k = 0; k < 2; ++k) dst[m][k] = *(const PG8_LAS bf16x8*)(lds + PG8_SA(b, h) + aoff + m * 2048 + k * 1024); } while (0)
; #define PG8_LDB(dst, b, h) do { _Pragma("unroll") for (int n = 0; n < 2; ++n) _Pragma("unroll") for (int k = 0; k < 2; ++k) dst[n][k] = *(const PG8_LAS bf16x8*)(lds + PG8_SB(b, h) + boff + n * 2048 + k * 1024); } while (0)
; #define PG8_MMA(ai, bj, At, Bt) do { __builtin_amdgcn_s_setprio(1); _Pragma("unroll") for (int m = 0; m < 4; ++m) _Pragma("unroll") for (int n = 0; n < 2; ++n) _Pragma("unroll") for (int k = 0; k < 2; ++k) \
;         acc[ai][bj][m][n] = __builtin_amdgcn_mfma_f32_16x16x32_bf16(Bt[n][k], At[m][k], acc[ai][bj][m][n], 0, 0, 0); __builtin_amdgcn_s_setprio(0); } while (0)
; #define PG8_WAIT_V(n) asm volatile("s_waitcnt vmcnt(" #n ")" ::: "memory")
; #define PG8_WAIT_L(n) asm volatile("s_waitcnt lgkmcnt(" #n ")" ::: "memory")
; #define PG8_BAR __builtin_amdgcn_s_barrier()
; #define PG8_SCHED __builtin_amdgcn_sched_barrier(0)
; template <class Epi, class Sched, bool ALIGN_EPI = false, bool SP2 = false>
; __device__ __forceinline__ void gemm_phase(PG8_LAS unsigned char* lds, const Gemm g, const Sched& S, const Epi& E) {
;     ...
;             const char* a1 = cA + (size_t)(t + 1) * kstep;
;             const char* a2 = last ? nA : cA + (size_t)(t + 2) * kstep; const char* b2 = last ? nB : cB + (size_t)(t + 2) * kstep;
;             const char* a3 = a2 + kstep; const char* b3 = b2 + kstep;
;             if (last && has_next) S.a_ready(nxt);
;             if constexpr (SP2) {
;             PG8_LDB(B0, 0, 0); PG8_LDB(B1, 0, 1); PG8_SCHED; PG8_LDA(At, 0, 0); PG8_STAGE(PG8_SA(1, 1), a1 + hstep, voffA);
;             PG8_WAIT_V(8); PG8_WAIT_L(0); PG8_BAR; PG8_MMA(0, 0, At, B0); PG8_MMA(0, 1, At, B1); PG8_BAR; PG8_SCHED;
;             PG8_LDA(At, 0, 1); PG8_STAGE(PG8_SB(0, 0), b2, voffB); PG8_STAGE(PG8_SB(0, 1), b2 + hstep, voffB); PG8_STAGE(PG8_SA(0, 0), a2, voffA);
.LBB0_438:
	s_add_u32 s11, s56, 0xfffc0080
	s_addc_u32 s12, s57, -1
	s_add_i32 s13, 0, 0x10000
	s_cmp_eq_u32 s10, 12
	s_cselect_b32 s61, s51, s12
	s_cselect_b32 s60, s72, s11
	s_cselect_b32 s59, s49, s31
	s_cselect_b32 s58, s73, s30
	s_add_i32 s11, 0, 0x14000
	v_add_u32_e32 v154, s13, v143
	v_add_u32_e32 v170, s11, v143
	ds_read_b128 v[138:141], v154
	ds_read_b128 v[146:149], v154 offset:1024
	ds_read_b128 v[150:153], v154 offset:2048
	ds_read_b128 v[154:157], v154 offset:3072
	ds_read_b128 v[158:161], v170
	ds_read_b128 v[162:165], v170 offset:1024
	ds_read_b128 v[166:169], v170 offset:2048
	ds_read_b128 v[170:173], v170 offset:3072
	s_add_i32 m0, s8, 0xc000
	ds_read_b128 v[174:177], v145
	ds_read_b128 v[178:181], v145 offset:1024
	ds_read_b128 v[198:201], v145 offset:2048
	ds_read_b128 v[202:205], v145 offset:3072
	ds_read_b128 v[206:209], v145 offset:4096
	ds_read_b128 v[210:213], v145 offset:5120
	ds_read_b128 v[214:217], v145 offset:6144
	ds_read_b128 v[232:235], v145 offset:7168
	global_load_lds_dwordx4 v134, s[56:57]
	s_add_i32 m0, s8, 0xe000
	s_nop 0
	global_load_lds_dwordx4 v136, s[56:57]
	s_waitcnt vmcnt(8)
	s_waitcnt lgkmcnt(0)
	s_barrier
	s_setprio 1
	s_waitcnt lgkmcnt(0)
	v_mfma_f32_16x16x32_bf16 v[124:127], v[138:141], v[174:177], v[124:127]
	v_mfma_f32_16x16x32_bf16 v[120:123], v[150:153], v[174:177], v[120:123]
	v_mfma_f32_16x16x32_bf16 v[108:111], v[138:141], v[198:201], v[108:111]
	v_mfma_f32_16x16x32_bf16 v[104:107], v[150:153], v[198:201], v[104:107]
	v_mfma_f32_16x16x32_bf16 v[92:95], v[138:141], v[206:209], v[92:95]
	v_mfma_f32_16x16x32_bf16 v[88:91], v[150:153], v[206:209], v[88:91]
	v_mfma_f32_16x16x32_bf16 v[76:79], v[138:141], v[214:217], v[76:79]
	v_mfma_f32_16x16x32_bf16 v[72:75], v[150:153], v[214:217], v[72:75]
	v_mfma_f32_16x16x32_bf16 v[124:127], v[146:149], v[178:181], v[124:127]
	v_mfma_f32_16x16x32_bf16 v[120:123], v[154:157], v[178:181], v[120:123]
	v_mfma_f32_16x16x32_bf16 v[108:111], v[146:149], v[202:205], v[108:111]
	v_mfma_f32_16x16x32_bf16 v[104:107], v[154:157], v[202:205], v[104:107]
	v_mfma_f32_16x16x32_bf16 v[92:95], v[146:149], v[210:213], v[92:95]
	v_mfma_f32_16x16x32_bf16 v[88:91], v[154:157], v[210:213], v[88:91]
	v_mfma_f32_16x16x32_bf16 v[76:79], v[146:149], v[232:235], v[76:79]
	v_mfma_f32_16x16x32_bf16 v[72:75], v[154:157], v[232:235], v[72:75]
	s_setprio 0
	s_setprio 1
	v_mfma_f32_16x16x32_bf16 v[116:119], v[158:161], v[174:177], v[116:119]
	v_mfma_f32_16x16x32_bf16 v[112:115], v[166:169], v[174:177], v[112:115]
	v_mfma_f32_16x16x32_bf16 v[100:103], v[158:161], v[198:201], v[100:103]
	v_mfma_f32_16x16x32_bf16 v[96:99], v[166:169], v[198:201], v[96:99]
	v_mfma_f32_16x16x32_bf16 v[84:87], v[158:161], v[206:209], v[84:87]
	v_mfma_f32_16x16x32_bf16 v[80:83], v[166:169], v[206:209], v[80:83]
	v_mfma_f32_16x16x32_bf16 v[68:71], v[158:161], v[214:217], v[68:71]
	v_mfma_f32_16x16x32_bf16 v[64:67], v[166:169], v[214:217], v[64:67]
	v_mfma_f32_16x16x32_bf16 v[116:119], v[162:165], v[178:181], v[116:119]
	v_mfma_f32_16x16x32_bf16 v[112:115], v[170:173], v[178:181], v[112:115]
	v_mfma_f32_16x16x32_bf16 v[100:103], v[162:165], v[202:205], v[100:103]
	v_mfma_f32_16x16x32_bf16 v[96:99], v[170:173], v[202:205], v[96:99]
	v_mfma_f32_16x16x32_bf16 v[84:87], v[162:165], v[210:213], v[84:87]
	v_mfma_f32_16x16x32_bf16 v[80:83], v[170:173], v[210:213], v[80:83]
	v_mfma_f32_16x16x32_bf16 v[68:71], v[162:165], v[232:235], v[68:71]
	v_mfma_f32_16x16x32_bf16 v[64:67], v[170:173], v[232:235], v[64:67]
	s_setprio 0
	s_barrier
	s_add_i32 s12, s13, s3
	v_lshl_add_u64 v[182:183], s[58:59], 0, v[188:189]
	s_mov_b32 m0, s12
	ds_read_b128 v[174:177], v145 offset:16384
	ds_read_b128 v[178:181], v145 offset:17408
	ds_read_b128 v[198:201], v145 offset:18432
	ds_read_b128 v[202:205], v145 offset:19456
	ds_read_b128 v[206:209], v145 offset:20480
	ds_read_b128 v[210:213], v145 offset:21504
	ds_read_b128 v[214:217], v145 offset:22528
	ds_read_b128 v[232:235], v145 offset:23552
	global_load_lds_dwordx4 v[182:183], off
	s_add_i32 m0, s12, 0x2000
	s_add_u32 s12, s58, 0x40000
	v_lshl_add_u64 v[236:237], s[58:59], 0, v[128:129]
	s_addc_u32 s13, s59, 0
	s_add_i32 s11, s11, s3
	global_load_lds_dwordx4 v[236:237], off
	s_mov_b32 m0, s11
	v_lshl_add_u64 v[240:241], s[60:61], 0, v[130:131]
	global_load_lds_dwordx4 v188, s[12:13]
	s_add_i32 m0, s11, 0x2000
	s_nop 0
	global_load_lds_dwordx4 v128, s[12:13]
	v_lshl_add_u64 v[238:239], s[60:61], 0, v[132:133]
	s_mov_b32 m0, s8
	s_nop 0
	global_load_lds_dwordx4 v[238:239], off
	s_mov_b32 m0, s9
	s_nop 0
	global_load_lds_dwordx4 v[240:241], off
	s_waitcnt vmcnt(8)
	s_waitcnt lgkmcnt(0)
	s_barrier
; #define PG8_STAGE(bufoff, gbase, voff) do { _Pragma("unroll") for (int _i = 0; _i < 2; ++_i) \
;         __builtin_amdgcn_global_load_lds((const unsigned*)((const char*)(gbase) + (voff)[_i]), (PG8_LAS unsigned*)(lds + (bufoff) + ldsw + _i * 8192), 16, 0, 0); } while (0)
; #define PG8_LDA(dst, b, h) do { _Pragma("unroll") for (int m = 0; m < 4; ++m) _Pragma("unroll") for (int k = 0; k < 2; ++k) dst[m][k] = *(const PG8_LAS bf16x8*)(lds + PG8_SA(b, h) + aoff + m * 2048 + k * 1024); } while (0)
; #define PG8_LDB(dst, b, h) do { _Pragma("unroll") for (int n = 0; n < 2; ++n) _Pragma("unroll") for (int k = 0; k < 2; ++k) dst[n][k] = *(const PG8_LAS bf16x8*)(lds + PG8_SB(b, h) + boff + n * 2048 + k * 1024); } while (0)
; #define PG8_MMA(ai, bj, At, Bt) do { __builtin_amdgcn_s_setprio(1); _Pragma("unroll") for (int m = 0; m < 4; ++m) _Pragma("unroll") for (int n = 0; n < 2; ++n) _Pragma("unroll") for (int k = 0; k < 2; ++k) \
;         acc[ai][bj][m][n] = __builtin_amdgcn_mfma_f32_16x16x32_bf16(Bt[n][k], At[m][k], acc[ai][bj][m][n], 0, 0, 0); __builtin_amdgcn_s_setprio(0); } while (0)
; #define PG8_WAIT_V(n) asm volatile("s_waitcnt vmcnt(" #n ")" ::: "memory")
; #define PG8_WAIT_L(n) asm volatile("s_waitcnt lgkmcnt(" #n ")" ::: "memory")
; #define PG8_BAR __builtin_amdgcn_s_barrier()
; #define PG8_SCHED __builtin_amdgcn_sched_barrier(0)
; template <class Epi, class Sched, bool ALIGN_EPI = false, bool SP2 = false>
; __device__ __forceinline__ void gemm_phase(PG8_LAS unsigned char* lds, const Gemm g, const Sched& S, const Epi& E) {
;     ...
;             PG8_WAIT_V(8); PG8_WAIT_L(0); PG8_BAR; PG8_MMA(1, 0, At, B0); PG8_MMA(1, 1, At, B1); PG8_BAR; PG8_SCHED;
;             PG8_LDB(B0, 1, 0); PG8_LDB(B1, 1, 1); PG8_SCHED; PG8_LDA(At, 1, 0); PG8_STAGE(PG8_SA(0, 1), a2 + hstep, voffA);
;             PG8_WAIT_V(8); PG8_WAIT_L(0); PG8_BAR; PG8_MMA(0, 0, At, B0); PG8_MMA(0, 1, At, B1); PG8_BAR; PG8_SCHED;
	s_setprio 1
	s_waitcnt lgkmcnt(0)
	v_mfma_f32_16x16x32_bf16 v[60:63], v[138:141], v[174:177], v[60:63]
	v_mfma_f32_16x16x32_bf16 v[56:59], v[150:153], v[174:177], v[56:59]
	v_mfma_f32_16x16x32_bf16 v[44:47], v[138:141], v[198:201], v[44:47]
	v_mfma_f32_16x16x32_bf16 v[40:43], v[150:153], v[198:201], v[40:43]
	v_mfma_f32_16x16x32_bf16 v[28:31], v[138:141], v[206:209], v[28:31]
	v_mfma_f32_16x16x32_bf16 v[24:27], v[150:153], v[206:209], v[24:27]
	v_mfma_f32_16x16x32_bf16 v[12:15], v[138:141], v[214:217], v[12:15]
	v_mfma_f32_16x16x32_bf16 v[8:11], v[150:153], v[214:217], v[8:11]
	v_mfma_f32_16x16x32_bf16 v[60:63], v[146:149], v[178:181], v[60:63]
	v_mfma_f32_16x16x32_bf16 v[56:59], v[154:157], v[178:181], v[56:59]
	v_mfma_f32_16x16x32_bf16 v[44:47], v[146:149], v[202:205], v[44:47]
	v_mfma_f32_16x16x32_bf16 v[40:43], v[154:157], v[202:205], v[40:43]
	v_mfma_f32_16x16x32_bf16 v[28:31], v[146:149], v[210:213], v[28:31]
	v_mfma_f32_16x16x32_bf16 v[24:27], v[154:157], v[210:213], v[24:27]
	v_mfma_f32_16x16x32_bf16 v[12:15], v[146:149], v[232:235], v[12:15]
	v_mfma_f32_16x16x32_bf16 v[8:11], v[154:157], v[232:235], v[8:11]
	s_setprio 0
	s_setprio 1
	v_mfma_f32_16x16x32_bf16 v[52:55], v[158:161], v[174:177], v[52:55]
	v_mfma_f32_16x16x32_bf16 v[48:51], v[166:169], v[174:177], v[48:51]
	v_mfma_f32_16x16x32_bf16 v[36:39], v[158:161], v[198:201], v[36:39]
	v_mfma_f32_16x16x32_bf16 v[32:35], v[166:169], v[198:201], v[32:35]
	v_mfma_f32_16x16x32_bf16 v[20:23], v[158:161], v[206:209], v[20:23]
	v_mfma_f32_16x16x32_bf16 v[16:19], v[166:169], v[206:209], v[16:19]
	v_mfma_f32_16x16x32_bf16 v[4:7], v[158:161], v[214:217], v[4:7]
	v_mfma_f32_16x16x32_bf16 v[0:3], v[166:169], v[214:217], v[0:3]
	v_mfma_f32_16x16x32_bf16 v[52:55], v[162:165], v[178:181], v[52:55]
	v_mfma_f32_16x16x32_bf16 v[48:51], v[170:173], v[178:181], v[48:51]
	v_mfma_f32_16x16x32_bf16 v[36:39], v[162:165], v[202:205], v[36:39]
	v_mfma_f32_16x16x32_bf16 v[32:35], v[170:173], v[202:205], v[32:35]
	v_mfma_f32_16x16x32_bf16 v[20:23], v[162:165], v[210:213], v[20:23]
	v_mfma_f32_16x16x32_bf16 v[16:19], v[170:173], v[210:213], v[16:19]
	v_mfma_f32_16x16x32_bf16 v[4:7], v[162:165], v[232:235], v[4:7]
	v_mfma_f32_16x16x32_bf16 v[0:3], v[170:173], v[232:235], v[0:3]
	s_setprio 0
	s_barrier
	s_add_i32 s11, 0, 0x18000
	s_add_i32 s14, 0, 0x1c000
	v_add_u32_e32 v154, s11, v143
	v_add_u32_e32 v170, s14, v143
	ds_read_b128 v[138:141], v154
	ds_read_b128 v[146:149], v154 offset:1024
	ds_read_b128 v[150:153], v154 offset:2048
	ds_read_b128 v[154:157], v154 offset:3072
	ds_read_b128 v[158:161], v170
	ds_read_b128 v[162:165], v170 offset:1024
	ds_read_b128 v[166:169], v170 offset:2048
	ds_read_b128 v[170:173], v170 offset:3072
	s_add_u32 s12, s60, 0x40000
	s_addc_u32 s13, s61, 0
	s_mov_b32 m0, s20
	ds_read_b128 v[174:177], v145 offset:32768
	ds_read_b128 v[178:181], v145 offset:33792
	ds_read_b128 v[198:201], v145 offset:34816
	ds_read_b128 v[202:205], v145 offset:35840
	ds_read_b128 v[206:209], v145 offset:36864
	ds_read_b128 v[210:213], v145 offset:37888
	ds_read_b128 v[214:217], v145 offset:38912
	ds_read_b128 v[232:235], v145 offset:39936
	global_load_lds_dwordx4 v132, s[12:13]
	s_mov_b32 m0, s21
	s_nop 0
	global_load_lds_dwordx4 v130, s[12:13]
	s_waitcnt vmcnt(8)
	s_waitcnt lgkmcnt(0)
	s_barrier
	s_setprio 1
	s_waitcnt lgkmcnt(0)
	v_mfma_f32_16x16x32_bf16 v[124:127], v[138:141], v[174:177], v[124:127]
	v_mfma_f32_16x16x32_bf16 v[120:123], v[150:153], v[174:177], v[120:123]
	v_mfma_f32_16x16x32_bf16 v[108:111], v[138:141], v[198:201], v[108:111]
	v_mfma_f32_16x16x32_bf16 v[104:107], v[150:153], v[198:201], v[104:107]
	v_mfma_f32_16x16x32_bf16 v[92:95], v[138:141], v[206:209], v[92:95]
	v_mfma_f32_16x16x32_bf16 v[88:91], v[150:153], v[206:209], v[88:91]
	v_mfma_f32_16x16x32_bf16 v[76:79], v[138:141], v[214:217], v[76:79]
	v_mfma_f32_16x16x32_bf16 v[72:75], v[150:153], v[214:217], v[72:75]
	v_mfma_f32_16x16x32_bf16 v[124:127], v[146:149], v[178:181], v[124:127]
	v_mfma_f32_16x16x32_bf16 v[120:123], v[154:157], v[178:181], v[120:123]
	v_mfma_f32_16x16x32_bf16 v[108:111], v[146:149], v[202:205], v[108:111]
	v_mfma_f32_16x16x32_bf16 v[104:107], v[154:157], v[202:205], v[104:107]
	v_mfma_f32_16x16x32_bf16 v[92:95], v[146:149], v[210:213], v[92:95]
	v_mfma_f32_16x16x32_bf16 v[88:91], v[154:157], v[210:213], v[88:91]
	v_mfma_f32_16x16x32_bf16 v[76:79], v[146:149], v[232:235], v[76:79]
	v_mfma_f32_16x16x32_bf16 v[72:75], v[154:157], v[232:235], v[72:75]
	s_setprio 0
	s_setprio 1
	v_mfma_f32_16x16x32_bf16 v[116:119], v[158:161], v[174:177], v[116:119]
	v_mfma_f32_16x16x32_bf16 v[112:115], v[166:169], v[174:177], v[112:115]
	v_mfma_f32_16x16x32_bf16 v[100:103], v[158:161], v[198:201], v[100:103]
	v_mfma_f32_16x16x32_bf16 v[96:99], v[166:169], v[198:201], v[96:99]
	v_mfma_f32_16x16x32_bf16 v[84:87], v[158:161], v[206:209], v[84:87]
	v_mfma_f32_16x16x32_bf16 v[80:83], v[166:169], v[206:209], v[80:83]
	v_mfma_f32_16x16x32_bf16 v[68:71], v[158:161], v[214:217], v[68:71]
	v_mfma_f32_16x16x32_bf16 v[64:67], v[166:169], v[214:217], v[64:67]
	v_mfma_f32_16x16x32_bf16 v[116:119], v[162:165], v[178:181], v[116:119]
	v_mfma_f32_16x16x32_bf16 v[112:115], v[170:173], v[178:181], v[112:115]
	v_mfma_f32_16x16x32_bf16 v[100:103], v[162:165], v[202:205], v[100:103]
	v_mfma_f32_16x16x32_bf16 v[96:99], v[170:173], v[202:205], v[96:99]
	v_mfma_f32_16x16x32_bf16 v[84:87], v[162:165], v[210:213], v[84:87]
	v_mfma_f32_16x16x32_bf16 v[80:83], v[170:173], v[210:213], v[80:83]
	v_mfma_f32_16x16x32_bf16 v[68:71], v[162:165], v[232:235], v[68:71]
	v_mfma_f32_16x16x32_bf16 v[64:67], v[170:173], v[232:235], v[64:67]
	s_setprio 0
	s_barrier
; #define PG8_STAGE(bufoff, gbase, voff) do { _Pragma("unroll") for (int _i = 0; _i < 2; ++_i) \
;         __builtin_amdgcn_global_load_lds((const unsigned*)((const char*)(gbase) + (voff)[_i]), (PG8_LAS unsigned*)(lds + (bufoff) + ldsw + _i * 8192), 16, 0, 0); } while (0)
; #define PG8_LDA(dst, b, h) do { _Pragma("unroll") for (int m = 0; m < 4; ++m) _Pragma("unroll") for (int k = 0; k < 2; ++k) dst[m][k] = *(const PG8_LAS bf16x8*)(lds + PG8_SA(b, h) + aoff + m * 2048 + k * 1024); } while (0)
; #define PG8_MMA(ai, bj, At, Bt) do { __builtin_amdgcn_s_setprio(1); _Pragma("unroll") for (int m = 0; m < 4; ++m) _Pragma("unroll") for (int n = 0; n < 2; ++n) _Pragma("unroll") for (int k = 0; k < 2; ++k) \
;         acc[ai][bj][m][n] = __builtin_amdgcn_mfma_f32_16x16x32_bf16(Bt[n][k], At[m][k], acc[ai][bj][m][n], 0, 0, 0); __builtin_amdgcn_s_setprio(0); } while (0)
; #define PG8_WAIT_V(n) asm volatile("s_waitcnt vmcnt(" #n ")" ::: "memory")
; #define PG8_WAIT_L(n) asm volatile("s_waitcnt lgkmcnt(" #n ")" ::: "memory")
; #define PG8_BAR __builtin_amdgcn_s_barrier()
; #define PG8_SCHED __builtin_amdgcn_sched_barrier(0)
; template <class Epi, class Sched, bool ALIGN_EPI = false, bool SP2 = false>
; __device__ __forceinline__ void gemm_phase(PG8_LAS unsigned char* lds, const Gemm g, const Sched& S, const Epi& E) {
;     ...
;             PG8_LDA(At, 1, 1); PG8_STAGE(PG8_SB(1, 0), b3, voffB); PG8_STAGE(PG8_SB(1, 1), b3 + hstep, voffB); PG8_STAGE(PG8_SA(1, 0), a3, voffA);
;             PG8_WAIT_V(8); PG8_WAIT_L(0); PG8_BAR; PG8_MMA(1, 0, At, B0); PG8_MMA(1, 1, At, B1); PG8_BAR; PG8_SCHED;
;     ...
;         if constexpr (ALIGN_EPI) { if (wr == 0) PG8_BAR; }
	s_add_i32 s11, s11, s3
	v_lshl_add_u64 v[182:183], v[182:183], 0, s[34:35]
	s_mov_b32 m0, s11
	ds_read_b128 v[174:177], v145 offset:49152
	ds_read_b128 v[178:181], v145 offset:50176
	ds_read_b128 v[198:201], v145 offset:51200
	ds_read_b128 v[202:205], v145 offset:52224
	ds_read_b128 v[206:209], v145 offset:53248
	ds_read_b128 v[210:213], v145 offset:54272
	ds_read_b128 v[214:217], v145 offset:55296
	ds_read_b128 v[232:235], v145 offset:56320
	global_load_lds_dwordx4 v[182:183], off
	s_add_i32 m0, s11, 0x2000
	s_add_u32 s12, s58, 0x40080
	v_lshl_add_u64 v[182:183], v[236:237], 0, s[34:35]
	s_addc_u32 s13, s59, 0
	s_add_i32 s11, s14, s3
	global_load_lds_dwordx4 v[182:183], off
	s_mov_b32 m0, s11
	s_nop 0
	global_load_lds_dwordx4 v188, s[12:13]
	s_add_i32 m0, s11, 0x2000
	s_nop 0
	global_load_lds_dwordx4 v128, s[12:13]
	v_lshl_add_u64 v[182:183], v[238:239], 0, s[34:35]
	s_mov_b32 m0, s29
	s_nop 0
	global_load_lds_dwordx4 v[182:183], off
	v_lshl_add_u64 v[182:183], v[240:241], 0, s[34:35]
	s_mov_b32 m0, s39
	s_nop 0
	global_load_lds_dwordx4 v[182:183], off
	s_waitcnt vmcnt(8)
	s_waitcnt lgkmcnt(0)
	s_barrier
	s_setprio 1
	s_waitcnt lgkmcnt(0)
	v_mfma_f32_16x16x32_bf16 v[60:63], v[138:141], v[174:177], v[60:63]
	v_mfma_f32_16x16x32_bf16 v[56:59], v[150:153], v[174:177], v[56:59]
	v_mfma_f32_16x16x32_bf16 v[44:47], v[138:141], v[198:201], v[44:47]
	v_mfma_f32_16x16x32_bf16 v[40:43], v[150:153], v[198:201], v[40:43]
	v_mfma_f32_16x16x32_bf16 v[28:31], v[138:141], v[206:209], v[28:31]
	v_mfma_f32_16x16x32_bf16 v[24:27], v[150:153], v[206:209], v[24:27]
	v_mfma_f32_16x16x32_bf16 v[12:15], v[138:141], v[214:217], v[12:15]
	v_mfma_f32_16x16x32_bf16 v[8:11], v[150:153], v[214:217], v[8:11]
	v_mfma_f32_16x16x32_bf16 v[60:63], v[146:149], v[178:181], v[60:63]
	v_mfma_f32_16x16x32_bf16 v[56:59], v[154:157], v[178:181], v[56:59]
	v_mfma_f32_16x16x32_bf16 v[44:47], v[146:149], v[202:205], v[44:47]
	v_mfma_f32_16x16x32_bf16 v[40:43], v[154:157], v[202:205], v[40:43]
	v_mfma_f32_16x16x32_bf16 v[28:31], v[146:149], v[210:213], v[28:31]
	v_mfma_f32_16x16x32_bf16 v[24:27], v[154:157], v[210:213], v[24:27]
	v_mfma_f32_16x16x32_bf16 v[12:15], v[146:149], v[232:235], v[12:15]
	v_mfma_f32_16x16x32_bf16 v[8:11], v[154:157], v[232:235], v[8:11]
	s_setprio 0
	s_setprio 1
	v_mfma_f32_16x16x32_bf16 v[52:55], v[158:161], v[174:177], v[52:55]
	v_mfma_f32_16x16x32_bf16 v[48:51], v[166:169], v[174:177], v[48:51]
	v_mfma_f32_16x16x32_bf16 v[36:39], v[158:161], v[198:201], v[36:39]
	v_mfma_f32_16x16x32_bf16 v[32:35], v[166:169], v[198:201], v[32:35]
	v_mfma_f32_16x16x32_bf16 v[20:23], v[158:161], v[206:209], v[20:23]
	v_mfma_f32_16x16x32_bf16 v[16:19], v[166:169], v[206:209], v[16:19]
	v_mfma_f32_16x16x32_bf16 v[4:7], v[158:161], v[214:217], v[4:7]
	v_mfma_f32_16x16x32_bf16 v[0:3], v[166:169], v[214:217], v[0:3]
	v_mfma_f32_16x16x32_bf16 v[52:55], v[162:165], v[178:181], v[52:55]
	v_mfma_f32_16x16x32_bf16 v[48:51], v[170:173], v[178:181], v[48:51]
	v_mfma_f32_16x16x32_bf16 v[36:39], v[162:165], v[202:205], v[36:39]
	v_mfma_f32_16x16x32_bf16 v[32:35], v[170:173], v[202:205], v[32:35]
	v_mfma_f32_16x16x32_bf16 v[20:23], v[162:165], v[210:213], v[20:23]
	v_mfma_f32_16x16x32_bf16 v[16:19], v[170:173], v[210:213], v[16:19]
	v_mfma_f32_16x16x32_bf16 v[4:7], v[162:165], v[232:235], v[4:7]
	v_mfma_f32_16x16x32_bf16 v[0:3], v[170:173], v[232:235], v[0:3]
	s_setprio 0
	s_barrier
	s_add_i32 s10, s10, 2
	s_add_u32 s56, s56, 0x100
	s_addc_u32 s57, s57, 0
	s_add_u32 s30, s30, 0x100
	s_addc_u32 s31, s31, 0
	s_cmp_gt_u32 s10, 13
	s_cbranch_scc0 .LBB0_438
	s_and_b64 vcc, exec, s[42:43]
	s_cbranch_vccz .LBB0_441
	s_barrier

; #define PG8_STAGE(bufoff, gbase, voff) do { _Pragma("unroll") for (int _i = 0; _i < 2; ++_i) \
;         __builtin_amdgcn_global_load_lds((const unsigned*)((const char*)(gbase) + (voff)[_i]), (PG8_LAS unsigned*)(lds + (bufoff) + ldsw + _i * 8192), 16, 0, 0); } while (0)
; #define PG8_LDA(dst, b, h) do { _Pragma("unroll") for (int m = 0; m < 4; ++m) _Pragma("unroll") for (int k = 0; k < 2; ++k) dst[m][k] = *(const PG8_LAS bf16x8*)(lds + PG8_SA(b, h) + aoff + m * 2048 + k * 1024); } while (0)
; #define PG8_LDB(dst, b, h) do { _Pragma("unroll") for (int n = 0; n < 2; ++n) _Pragma("unroll") for (int k = 0; k < 2; ++k) dst[n][k] = *(const PG8_LAS bf16x8*)(lds + PG8_SB(b, h) + boff + n * 2048 + k * 1024); } while (0)
; #define PG8_MMA(ai, bj, At, Bt) do { __builtin_amdgcn_s_setprio(1); _Pragma("unroll") for (int m = 0; m < 4; ++m) _Pragma("unroll") for (int n = 0; n < 2; ++n) _Pragma("unroll") for (int k = 0; k < 2; ++k) \
;         acc[ai][bj][m][n] = __builtin_amdgcn_mfma_f32_16x16x32_bf16(Bt[n][k], At[m][k], acc[ai][bj][m][n], 0, 0, 0); __builtin_amdgcn_s_setprio(0); } while (0)
; #define PG8_WAIT_V(n) asm volatile("s_waitcnt vmcnt(" #n ")" ::: "memory")
; #define PG8_WAIT_L(n) asm volatile("s_waitcnt lgkmcnt(" #n ")" ::: "memory")
; #define PG8_BAR __builtin_amdgcn_s_barrier()
; #define PG8_SCHED __builtin_amdgcn_sched_barrier(0)
; template <class Epi, class Sched, bool ALIGN_EPI = false, bool SP2 = false>
; __device__ __forceinline__ void gemm_phase(PG8_LAS unsigned char* lds, const Gemm g, const Sched& S, const Epi& E) {
;     ...
;             const char* a1 = cA + (size_t)(t + 1) * kstep;
;             const char* a2 = last ? nA : cA + (size_t)(t + 2) * kstep; const char* b2 = last ? nB : cB + (size_t)(t + 2) * kstep;
;             const char* a3 = a2 + kstep; const char* b3 = b2 + kstep;
;             if (last && has_next) S.a_ready(nxt);
;             if constexpr (SP2) {
;             PG8_LDB(B0, 0, 0); PG8_LDB(B1, 0, 1); PG8_SCHED; PG8_LDA(At, 0, 0); PG8_STAGE(PG8_SA(1, 1), a1 + hstep, voffA);
;             PG8_WAIT_V(8); PG8_WAIT_L(0); PG8_BAR; PG8_MMA(0, 0, At, B0); PG8_MMA(0, 1, At, B1); PG8_BAR; PG8_SCHED;
;             PG8_LDA(At, 0, 1); PG8_STAGE(PG8_SB(0, 0), b2, voffB); PG8_STAGE(PG8_SB(0, 1), b2 + hstep, voffB); PG8_STAGE(PG8_SA(0, 0), a2, voffA);
.LBB0_506:
	s_add_u32 s11, s60, 0xfffe0080
	s_addc_u32 s12, s61, -1
	s_add_i32 s13, 0, 0x10000
	s_cmp_eq_u32 s10, 4
	s_cselect_b32 vcc_hi, s55, s12
	s_cselect_b32 vcc_lo, s72, s11
	s_cselect_b32 s63, s53, s31
	s_cselect_b32 s62, s73, s30
	s_add_i32 s11, 0, 0x14000
	v_add_u32_e32 v140, s13, v171
	v_add_u32_e32 v166, s11, v171
	ds_read_b128 v[128:131], v140
	ds_read_b128 v[132:135], v140 offset:1024
	ds_read_b128 v[136:139], v140 offset:2048
	ds_read_b128 v[140:143], v140 offset:3072
	ds_read_b128 v[144:147], v166
	ds_read_b128 v[158:161], v166 offset:1024
	ds_read_b128 v[162:165], v166 offset:2048
	ds_read_b128 v[166:169], v166 offset:3072
	s_add_i32 m0, s8, 0xc000
	ds_read_b128 v[174:177], v173
	ds_read_b128 v[178:181], v173 offset:1024
	ds_read_b128 v[198:201], v173 offset:2048
	ds_read_b128 v[202:205], v173 offset:3072
	ds_read_b128 v[206:209], v173 offset:4096
	ds_read_b128 v[210:213], v173 offset:5120
	ds_read_b128 v[214:217], v173 offset:6144
	ds_read_b128 v[232:235], v173 offset:7168
	global_load_lds_dwordx4 v154, s[60:61]
	s_add_i32 m0, s8, 0xe000
	s_nop 0
	global_load_lds_dwordx4 v156, s[60:61]
	s_waitcnt vmcnt(8)
	s_waitcnt lgkmcnt(0)
	s_barrier
	s_setprio 1
	s_waitcnt lgkmcnt(0)
	v_mfma_f32_16x16x32_bf16 v[124:127], v[128:131], v[174:177], v[124:127]
	v_mfma_f32_16x16x32_bf16 v[120:123], v[136:139], v[174:177], v[120:123]
	v_mfma_f32_16x16x32_bf16 v[116:119], v[128:131], v[198:201], v[116:119]
	v_mfma_f32_16x16x32_bf16 v[112:115], v[136:139], v[198:201], v[112:115]
	v_mfma_f32_16x16x32_bf16 v[96:99], v[128:131], v[206:209], v[96:99]
	v_mfma_f32_16x16x32_bf16 v[92:95], v[136:139], v[206:209], v[92:95]
	v_mfma_f32_16x16x32_bf16 v[84:87], v[128:131], v[214:217], v[84:87]
	v_mfma_f32_16x16x32_bf16 v[80:83], v[136:139], v[214:217], v[80:83]
	v_mfma_f32_16x16x32_bf16 v[124:127], v[132:135], v[178:181], v[124:127]
	v_mfma_f32_16x16x32_bf16 v[120:123], v[140:143], v[178:181], v[120:123]
	v_mfma_f32_16x16x32_bf16 v[116:119], v[132:135], v[202:205], v[116:119]
	v_mfma_f32_16x16x32_bf16 v[112:115], v[140:143], v[202:205], v[112:115]
	v_mfma_f32_16x16x32_bf16 v[96:99], v[132:135], v[210:213], v[96:99]
	v_mfma_f32_16x16x32_bf16 v[92:95], v[140:143], v[210:213], v[92:95]
	v_mfma_f32_16x16x32_bf16 v[84:87], v[132:135], v[232:235], v[84:87]
	v_mfma_f32_16x16x32_bf16 v[80:83], v[140:143], v[232:235], v[80:83]
	s_setprio 0
	s_setprio 1
	v_mfma_f32_16x16x32_bf16 v[108:111], v[144:147], v[174:177], v[108:111]
	v_mfma_f32_16x16x32_bf16 v[104:107], v[162:165], v[174:177], v[104:107]
	v_mfma_f32_16x16x32_bf16 v[100:103], v[144:147], v[198:201], v[100:103]
	v_mfma_f32_16x16x32_bf16 v[88:91], v[162:165], v[198:201], v[88:91]
	v_mfma_f32_16x16x32_bf16 v[76:79], v[144:147], v[206:209], v[76:79]
	v_mfma_f32_16x16x32_bf16 v[72:75], v[162:165], v[206:209], v[72:75]
	v_mfma_f32_16x16x32_bf16 v[68:71], v[144:147], v[214:217], v[68:71]
	v_mfma_f32_16x16x32_bf16 v[64:67], v[162:165], v[214:217], v[64:67]
	v_mfma_f32_16x16x32_bf16 v[108:111], v[158:161], v[178:181], v[108:111]
	v_mfma_f32_16x16x32_bf16 v[104:107], v[166:169], v[178:181], v[104:107]
	v_mfma_f32_16x16x32_bf16 v[100:103], v[158:161], v[202:205], v[100:103]
	v_mfma_f32_16x16x32_bf16 v[88:91], v[166:169], v[202:205], v[88:91]
	v_mfma_f32_16x16x32_bf16 v[76:79], v[158:161], v[210:213], v[76:79]
	v_mfma_f32_16x16x32_bf16 v[72:75], v[166:169], v[210:213], v[72:75]
	v_mfma_f32_16x16x32_bf16 v[68:71], v[158:161], v[232:235], v[68:71]
	v_mfma_f32_16x16x32_bf16 v[64:67], v[166:169], v[232:235], v[64:67]
	s_setprio 0
	s_barrier
	s_add_i32 s12, s13, s3
	v_lshl_add_u64 v[182:183], s[62:63], 0, v[188:189]
	s_mov_b32 m0, s12
	ds_read_b128 v[174:177], v173 offset:16384
	ds_read_b128 v[178:181], v173 offset:17408
	ds_read_b128 v[198:201], v173 offset:18432
	ds_read_b128 v[202:205], v173 offset:19456
	ds_read_b128 v[206:209], v173 offset:20480
	ds_read_b128 v[210:213], v173 offset:21504
	ds_read_b128 v[214:217], v173 offset:22528
	ds_read_b128 v[232:235], v173 offset:23552
	global_load_lds_dwordx4 v[182:183], off
	s_add_i32 m0, s12, 0x2000
	s_add_u32 s12, s62, 0x20000
	v_lshl_add_u64 v[236:237], s[62:63], 0, v[148:149]
	s_addc_u32 s13, s63, 0
	s_add_i32 s11, s11, s3
	global_load_lds_dwordx4 v[236:237], off
	s_mov_b32 m0, s11
	v_lshl_add_u64 v[240:241], vcc, 0, v[150:151]
	global_load_lds_dwordx4 v188, s[12:13]
	s_add_i32 m0, s11, 0x2000
	s_nop 0
	global_load_lds_dwordx4 v148, s[12:13]
	v_lshl_add_u64 v[238:239], vcc, 0, v[152:153]
	s_mov_b32 m0, s8
	s_nop 0
	global_load_lds_dwordx4 v[238:239], off
	s_mov_b32 m0, s9
	s_nop 0
	global_load_lds_dwordx4 v[240:241], off
	s_waitcnt vmcnt(8)
	s_waitcnt lgkmcnt(0)
	s_barrier
; #define PG8_STAGE(bufoff, gbase, voff) do { _Pragma("unroll") for (int _i = 0; _i < 2; ++_i) \
;         __builtin_amdgcn_global_load_lds((const unsigned*)((const char*)(gbase) + (voff)[_i]), (PG8_LAS unsigned*)(lds + (bufoff) + ldsw + _i * 8192), 16, 0, 0); } while (0)
; #define PG8_LDA(dst, b, h) do { _Pragma("unroll") for (int m = 0; m < 4; ++m) _Pragma("unroll") for (int k = 0; k < 2; ++k) dst[m][k] = *(const PG8_LAS bf16x8*)(lds + PG8_SA(b, h) + aoff + m * 2048 + k * 1024); } while (0)
; #define PG8_LDB(dst, b, h) do { _Pragma("unroll") for (int n = 0; n < 2; ++n) _Pragma("unroll") for (int k = 0; k < 2; ++k) dst[n][k] = *(const PG8_LAS bf16x8*)(lds + PG8_SB(b, h) + boff + n * 2048 + k * 1024); } while (0)
; #define PG8_MMA(ai, bj, At, Bt) do { __builtin_amdgcn_s_setprio(1); _Pragma("unroll") for (int m = 0; m < 4; ++m) _Pragma("unroll") for (int n = 0; n < 2; ++n) _Pragma("unroll") for (int k = 0; k < 2; ++k) \
;         acc[ai][bj][m][n] = __builtin_amdgcn_mfma_f32_16x16x32_bf16(Bt[n][k], At[m][k], acc[ai][bj][m][n], 0, 0, 0); __builtin_amdgcn_s_setprio(0); } while (0)
; #define PG8_WAIT_V(n) asm volatile("s_waitcnt vmcnt(" #n ")" ::: "memory")
; #define PG8_WAIT_L(n) asm volatile("s_waitcnt lgkmcnt(" #n ")" ::: "memory")
; #define PG8_BAR __builtin_amdgcn_s_barrier()
; #define PG8_SCHED __builtin_amdgcn_sched_barrier(0)
; template <class Epi, class Sched, bool ALIGN_EPI = false, bool SP2 = false>
; __device__ __forceinline__ void gemm_phase(PG8_LAS unsigned char* lds, const Gemm g, const Sched& S, const Epi& E) {
;     ...
;             PG8_WAIT_V(8); PG8_WAIT_L(0); PG8_BAR; PG8_MMA(1, 0, At, B0); PG8_MMA(1, 1, At, B1); PG8_BAR; PG8_SCHED;
;             PG8_LDB(B0, 1, 0); PG8_LDB(B1, 1, 1); PG8_SCHED; PG8_LDA(At, 1, 0); PG8_STAGE(PG8_SA(0, 1), a2 + hstep, voffA);
;             PG8_WAIT_V(8); PG8_WAIT_L(0); PG8_BAR; PG8_MMA(0, 0, At, B0); PG8_MMA(0, 1, At, B1); PG8_BAR; PG8_SCHED;
	s_setprio 1
	s_waitcnt lgkmcnt(0)
	v_mfma_f32_16x16x32_bf16 v[60:63], v[128:131], v[174:177], v[60:63]
	v_mfma_f32_16x16x32_bf16 v[56:59], v[136:139], v[174:177], v[56:59]
	v_mfma_f32_16x16x32_bf16 v[48:51], v[128:131], v[198:201], v[48:51]
	v_mfma_f32_16x16x32_bf16 v[40:43], v[136:139], v[198:201], v[40:43]
	v_mfma_f32_16x16x32_bf16 v[32:35], v[128:131], v[206:209], v[32:35]
	v_mfma_f32_16x16x32_bf16 v[24:27], v[136:139], v[206:209], v[24:27]
	v_mfma_f32_16x16x32_bf16 v[16:19], v[128:131], v[214:217], v[16:19]
	v_mfma_f32_16x16x32_bf16 v[8:11], v[136:139], v[214:217], v[8:11]
	v_mfma_f32_16x16x32_bf16 v[60:63], v[132:135], v[178:181], v[60:63]
	v_mfma_f32_16x16x32_bf16 v[56:59], v[140:143], v[178:181], v[56:59]
	v_mfma_f32_16x16x32_bf16 v[48:51], v[132:135], v[202:205], v[48:51]
	v_mfma_f32_16x16x32_bf16 v[40:43], v[140:143], v[202:205], v[40:43]
	v_mfma_f32_16x16x32_bf16 v[32:35], v[132:135], v[210:213], v[32:35]
	v_mfma_f32_16x16x32_bf16 v[24:27], v[140:143], v[210:213], v[24:27]
	v_mfma_f32_16x16x32_bf16 v[16:19], v[132:135], v[232:235], v[16:19]
	v_mfma_f32_16x16x32_bf16 v[8:11], v[140:143], v[232:235], v[8:11]
	s_setprio 0
	s_setprio 1
	v_mfma_f32_16x16x32_bf16 v[52:55], v[144:147], v[174:177], v[52:55]
	v_mfma_f32_16x16x32_bf16 v[44:47], v[162:165], v[174:177], v[44:47]
	v_mfma_f32_16x16x32_bf16 v[36:39], v[144:147], v[198:201], v[36:39]
	v_mfma_f32_16x16x32_bf16 v[28:31], v[162:165], v[198:201], v[28:31]
	v_mfma_f32_16x16x32_bf16 v[20:23], v[144:147], v[206:209], v[20:23]
	v_mfma_f32_16x16x32_bf16 v[12:15], v[162:165], v[206:209], v[12:15]
	v_mfma_f32_16x16x32_bf16 v[4:7], v[144:147], v[214:217], v[4:7]
	v_mfma_f32_16x16x32_bf16 v[0:3], v[162:165], v[214:217], v[0:3]
	v_mfma_f32_16x16x32_bf16 v[52:55], v[158:161], v[178:181], v[52:55]
	v_mfma_f32_16x16x32_bf16 v[44:47], v[166:169], v[178:181], v[44:47]
	v_mfma_f32_16x16x32_bf16 v[36:39], v[158:161], v[202:205], v[36:39]
	v_mfma_f32_16x16x32_bf16 v[28:31], v[166:169], v[202:205], v[28:31]
	v_mfma_f32_16x16x32_bf16 v[20:23], v[158:161], v[210:213], v[20:23]
	v_mfma_f32_16x16x32_bf16 v[12:15], v[166:169], v[210:213], v[12:15]
	v_mfma_f32_16x16x32_bf16 v[4:7], v[158:161], v[232:235], v[4:7]
	v_mfma_f32_16x16x32_bf16 v[0:3], v[166:169], v[232:235], v[0:3]
	s_setprio 0
	s_barrier
	s_add_i32 s11, 0, 0x18000
	s_add_i32 s14, 0, 0x1c000
	v_add_u32_e32 v140, s11, v171
	v_add_u32_e32 v166, s14, v171
	ds_read_b128 v[128:131], v140
	ds_read_b128 v[132:135], v140 offset:1024
	ds_read_b128 v[136:139], v140 offset:2048
	ds_read_b128 v[140:143], v140 offset:3072
	ds_read_b128 v[144:147], v166
	ds_read_b128 v[158:161], v166 offset:1024
	ds_read_b128 v[162:165], v166 offset:2048
	ds_read_b128 v[166:169], v166 offset:3072
	s_add_u32 s12, vcc_lo, 0x20000
	s_addc_u32 s13, vcc_hi, 0
	s_mov_b32 m0, s20
	ds_read_b128 v[174:177], v173 offset:32768
	ds_read_b128 v[178:181], v173 offset:33792
	ds_read_b128 v[198:201], v173 offset:34816
	ds_read_b128 v[202:205], v173 offset:35840
	ds_read_b128 v[206:209], v173 offset:36864
	ds_read_b128 v[210:213], v173 offset:37888
	ds_read_b128 v[214:217], v173 offset:38912
	ds_read_b128 v[232:235], v173 offset:39936
	global_load_lds_dwordx4 v152, s[12:13]
	s_mov_b32 m0, s21
	s_nop 0
	global_load_lds_dwordx4 v150, s[12:13]
	s_waitcnt vmcnt(8)
	s_waitcnt lgkmcnt(0)
	s_barrier
	s_setprio 1
	s_waitcnt lgkmcnt(0)
	v_mfma_f32_16x16x32_bf16 v[124:127], v[128:131], v[174:177], v[124:127]
	v_mfma_f32_16x16x32_bf16 v[120:123], v[136:139], v[174:177], v[120:123]
	v_mfma_f32_16x16x32_bf16 v[116:119], v[128:131], v[198:201], v[116:119]
	v_mfma_f32_16x16x32_bf16 v[112:115], v[136:139], v[198:201], v[112:115]
	v_mfma_f32_16x16x32_bf16 v[96:99], v[128:131], v[206:209], v[96:99]
	v_mfma_f32_16x16x32_bf16 v[92:95], v[136:139], v[206:209], v[92:95]
	v_mfma_f32_16x16x32_bf16 v[84:87], v[128:131], v[214:217], v[84:87]
	v_mfma_f32_16x16x32_bf16 v[80:83], v[136:139], v[214:217], v[80:83]
	v_mfma_f32_16x16x32_bf16 v[124:127], v[132:135], v[178:181], v[124:127]
	v_mfma_f32_16x16x32_bf16 v[120:123], v[140:143], v[178:181], v[120:123]
	v_mfma_f32_16x16x32_bf16 v[116:119], v[132:135], v[202:205], v[116:119]
	v_mfma_f32_16x16x32_bf16 v[112:115], v[140:143], v[202:205], v[112:115]
	v_mfma_f32_16x16x32_bf16 v[96:99], v[132:135], v[210:213], v[96:99]
	v_mfma_f32_16x16x32_bf16 v[92:95], v[140:143], v[210:213], v[92:95]
	v_mfma_f32_16x16x32_bf16 v[84:87], v[132:135], v[232:235], v[84:87]
	v_mfma_f32_16x16x32_bf16 v[80:83], v[140:143], v[232:235], v[80:83]
	s_setprio 0
	s_setprio 1
	v_mfma_f32_16x16x32_bf16 v[108:111], v[144:147], v[174:177], v[108:111]
	v_mfma_f32_16x16x32_bf16 v[104:107], v[162:165], v[174:177], v[104:107]
	v_mfma_f32_16x16x32_bf16 v[100:103], v[144:147], v[198:201], v[100:103]
	v_mfma_f32_16x16x32_bf16 v[88:91], v[162:165], v[198:201], v[88:91]
	v_mfma_f32_16x16x32_bf16 v[76:79], v[144:147], v[206:209], v[76:79]
	v_mfma_f32_16x16x32_bf16 v[72:75], v[162:165], v[206:209], v[72:75]
	v_mfma_f32_16x16x32_bf16 v[68:71], v[144:147], v[214:217], v[68:71]
	v_mfma_f32_16x16x32_bf16 v[64:67], v[162:165], v[214:217], v[64:67]
	v_mfma_f32_16x16x32_bf16 v[108:111], v[158:161], v[178:181], v[108:111]
	v_mfma_f32_16x16x32_bf16 v[104:107], v[166:169], v[178:181], v[104:107]
	v_mfma_f32_16x16x32_bf16 v[100:103], v[158:161], v[202:205], v[100:103]
	v_mfma_f32_16x16x32_bf16 v[88:91], v[166:169], v[202:205], v[88:91]
	v_mfma_f32_16x16x32_bf16 v[76:79], v[158:161], v[210:213], v[76:79]
	v_mfma_f32_16x16x32_bf16 v[72:75], v[166:169], v[210:213], v[72:75]
	v_mfma_f32_16x16x32_bf16 v[68:71], v[158:161], v[232:235], v[68:71]
	v_mfma_f32_16x16x32_bf16 v[64:67], v[166:169], v[232:235], v[64:67]
	s_setprio 0
	s_barrier
; #define PG8_STAGE(bufoff, gbase, voff) do { _Pragma("unroll") for (int _i = 0; _i < 2; ++_i) \
;         __builtin_amdgcn_global_load_lds((const unsigned*)((const char*)(gbase) + (voff)[_i]), (PG8_LAS unsigned*)(lds + (bufoff) + ldsw + _i * 8192), 16, 0, 0); } while (0)
; #define PG8_LDA(dst, b, h) do { _Pragma("unroll") for (int m = 0; m < 4; ++m) _Pragma("unroll") for (int k = 0; k < 2; ++k) dst[m][k] = *(const PG8_LAS bf16x8*)(lds + PG8_SA(b, h) + aoff + m * 2048 + k * 1024); } while (0)
; #define PG8_MMA(ai, bj, At, Bt) do { __builtin_amdgcn_s_setprio(1); _Pragma("unroll") for (int m = 0; m < 4; ++m) _Pragma("unroll") for (int n = 0; n < 2; ++n) _Pragma("unroll") for (int k = 0; k < 2; ++k) \
;         acc[ai][bj][m][n] = __builtin_amdgcn_mfma_f32_16x16x32_bf16(Bt[n][k], At[m][k], acc[ai][bj][m][n], 0, 0, 0); __builtin_amdgcn_s_setprio(0); } while (0)
; #define PG8_WAIT_V(n) asm volatile("s_waitcnt vmcnt(" #n ")" ::: "memory")
; #define PG8_WAIT_L(n) asm volatile("s_waitcnt lgkmcnt(" #n ")" ::: "memory")
; #define PG8_BAR __builtin_amdgcn_s_barrier()
; #define PG8_SCHED __builtin_amdgcn_sched_barrier(0)
; template <class Epi, class Sched, bool ALIGN_EPI = false, bool SP2 = false>
; __device__ __forceinline__ void gemm_phase(PG8_LAS unsigned char* lds, const Gemm g, const Sched& S, const Epi& E) {
;     ...
;             PG8_LDA(At, 1, 1); PG8_STAGE(PG8_SB(1, 0), b3, voffB); PG8_STAGE(PG8_SB(1, 1), b3 + hstep, voffB); PG8_STAGE(PG8_SA(1, 0), a3, voffA);
;             PG8_WAIT_V(8); PG8_WAIT_L(0); PG8_BAR; PG8_MMA(1, 0, At, B0); PG8_MMA(1, 1, At, B1); PG8_BAR; PG8_SCHED;
;     ...
;         if constexpr (ALIGN_EPI) { if (wr == 0) PG8_BAR; }
	s_add_i32 s11, s11, s3
	v_lshl_add_u64 v[182:183], v[182:183], 0, s[34:35]
	s_mov_b32 m0, s11
	ds_read_b128 v[174:177], v173 offset:49152
	ds_read_b128 v[178:181], v173 offset:50176
	ds_read_b128 v[198:201], v173 offset:51200
	ds_read_b128 v[202:205], v173 offset:52224
	ds_read_b128 v[206:209], v173 offset:53248
	ds_read_b128 v[210:213], v173 offset:54272
	ds_read_b128 v[214:217], v173 offset:55296
	ds_read_b128 v[232:235], v173 offset:56320
	global_load_lds_dwordx4 v[182:183], off
	s_add_i32 m0, s11, 0x2000
	s_add_u32 s12, s62, 0x20080
	v_lshl_add_u64 v[182:183], v[236:237], 0, s[34:35]
	s_addc_u32 s13, s63, 0
	s_add_i32 s11, s14, s3
	global_load_lds_dwordx4 v[182:183], off
	s_mov_b32 m0, s11
	s_nop 0
	global_load_lds_dwordx4 v188, s[12:13]
	s_add_i32 m0, s11, 0x2000
	s_nop 0
	global_load_lds_dwordx4 v148, s[12:13]
	v_lshl_add_u64 v[182:183], v[238:239], 0, s[34:35]
	s_mov_b32 m0, s24
	s_nop 0
	global_load_lds_dwordx4 v[182:183], off
	v_lshl_add_u64 v[182:183], v[240:241], 0, s[34:35]
	s_mov_b32 m0, s29
	s_nop 0
	global_load_lds_dwordx4 v[182:183], off
	s_waitcnt vmcnt(8)
	s_waitcnt lgkmcnt(0)
	s_barrier
	s_setprio 1
	s_waitcnt lgkmcnt(0)
	v_mfma_f32_16x16x32_bf16 v[60:63], v[128:131], v[174:177], v[60:63]
	v_mfma_f32_16x16x32_bf16 v[56:59], v[136:139], v[174:177], v[56:59]
	v_mfma_f32_16x16x32_bf16 v[48:51], v[128:131], v[198:201], v[48:51]
	v_mfma_f32_16x16x32_bf16 v[40:43], v[136:139], v[198:201], v[40:43]
	v_mfma_f32_16x16x32_bf16 v[32:35], v[128:131], v[206:209], v[32:35]
	v_mfma_f32_16x16x32_bf16 v[24:27], v[136:139], v[206:209], v[24:27]
	v_mfma_f32_16x16x32_bf16 v[16:19], v[128:131], v[214:217], v[16:19]
	v_mfma_f32_16x16x32_bf16 v[8:11], v[136:139], v[214:217], v[8:11]
	v_mfma_f32_16x16x32_bf16 v[60:63], v[132:135], v[178:181], v[60:63]
	v_mfma_f32_16x16x32_bf16 v[56:59], v[140:143], v[178:181], v[56:59]
	v_mfma_f32_16x16x32_bf16 v[48:51], v[132:135], v[202:205], v[48:51]
	v_mfma_f32_16x16x32_bf16 v[40:43], v[140:143], v[202:205], v[40:43]
	v_mfma_f32_16x16x32_bf16 v[32:35], v[132:135], v[210:213], v[32:35]
	v_mfma_f32_16x16x32_bf16 v[24:27], v[140:143], v[210:213], v[24:27]
	v_mfma_f32_16x16x32_bf16 v[16:19], v[132:135], v[232:235], v[16:19]
	v_mfma_f32_16x16x32_bf16 v[8:11], v[140:143], v[232:235], v[8:11]
	s_setprio 0
	s_setprio 1
	v_mfma_f32_16x16x32_bf16 v[52:55], v[144:147], v[174:177], v[52:55]
	v_mfma_f32_16x16x32_bf16 v[44:47], v[162:165], v[174:177], v[44:47]
	v_mfma_f32_16x16x32_bf16 v[36:39], v[144:147], v[198:201], v[36:39]
	v_mfma_f32_16x16x32_bf16 v[28:31], v[162:165], v[198:201], v[28:31]
	v_mfma_f32_16x16x32_bf16 v[20:23], v[144:147], v[206:209], v[20:23]
	v_mfma_f32_16x16x32_bf16 v[12:15], v[162:165], v[206:209], v[12:15]
	v_mfma_f32_16x16x32_bf16 v[4:7], v[144:147], v[214:217], v[4:7]
	v_mfma_f32_16x16x32_bf16 v[0:3], v[162:165], v[214:217], v[0:3]
	v_mfma_f32_16x16x32_bf16 v[52:55], v[158:161], v[178:181], v[52:55]
	v_mfma_f32_16x16x32_bf16 v[44:47], v[166:169], v[178:181], v[44:47]
	v_mfma_f32_16x16x32_bf16 v[36:39], v[158:161], v[202:205], v[36:39]
	v_mfma_f32_16x16x32_bf16 v[28:31], v[166:169], v[202:205], v[28:31]
	v_mfma_f32_16x16x32_bf16 v[20:23], v[158:161], v[210:213], v[20:23]
	v_mfma_f32_16x16x32_bf16 v[12:15], v[166:169], v[210:213], v[12:15]
	v_mfma_f32_16x16x32_bf16 v[4:7], v[158:161], v[232:235], v[4:7]
	v_mfma_f32_16x16x32_bf16 v[0:3], v[166:169], v[232:235], v[0:3]
	s_setprio 0
	s_barrier
	s_add_i32 s10, s10, 2
	s_add_u32 s60, s60, 0x100
	s_addc_u32 s61, s61, 0
	s_add_u32 s30, s30, 0x100
	s_addc_u32 s31, s31, 0
	s_cmp_gt_u32 s10, 5
	s_cbranch_scc0 .LBB0_506
	s_and_b64 vcc, exec, s[50:51]
	s_cbranch_vccz .LBB0_509
	s_barrier

; #define PG8_STAGE(bufoff, gbase, voff) do { _Pragma("unroll") for (int _i = 0; _i < 2; ++_i) \
;         __builtin_amdgcn_global_load_lds((const unsigned*)((const char*)(gbase) + (voff)[_i]), (PG8_LAS unsigned*)(lds + (bufoff) + ldsw + _i * 8192), 16, 0, 0); } while (0)
; #define PG8_LDA(dst, b, h) do { _Pragma("unroll") for (int m = 0; m < 4; ++m) _Pragma("unroll") for (int k = 0; k < 2; ++k) dst[m][k] = *(const PG8_LAS bf16x8*)(lds + PG8_SA(b, h) + aoff + m * 2048 + k * 1024); } while (0)
; #define PG8_LDB(dst, b, h) do { _Pragma("unroll") for (int n = 0; n < 2; ++n) _Pragma("unroll") for (int k = 0; k < 2; ++k) dst[n][k] = *(const PG8_LAS bf16x8*)(lds + PG8_SB(b, h) + boff + n * 2048 + k * 1024); } while (0)
; #define PG8_MMA(ai, bj, At, Bt) do { __builtin_amdgcn_s_setprio(1); _Pragma("unroll") for (int m = 0; m < 4; ++m) _Pragma("unroll") for (int n = 0; n < 2; ++n) _Pragma("unroll") for (int k = 0; k < 2; ++k) \
;         acc[ai][bj][m][n] = __builtin_amdgcn_mfma_f32_16x16x32_bf16(Bt[n][k], At[m][k], acc[ai][bj][m][n], 0, 0, 0); __builtin_amdgcn_s_setprio(0); } while (0)
; #define PG8_WAIT_V(n) asm volatile("s_waitcnt vmcnt(" #n ")" ::: "memory")
; #define PG8_WAIT_L(n) asm volatile("s_waitcnt lgkmcnt(" #n ")" ::: "memory")
; #define PG8_BAR __builtin_amdgcn_s_barrier()
; #define PG8_SCHED __builtin_amdgcn_sched_barrier(0)
; template <class Epi, class Sched, bool ALIGN_EPI = false, bool SP2 = false>
; __device__ __forceinline__ void gemm_phase(PG8_LAS unsigned char* lds, const Gemm g, const Sched& S, const Epi& E) {
;     ...
;             const char* a1 = cA + (size_t)(t + 1) * kstep;
;             const char* a2 = last ? nA : cA + (size_t)(t + 2) * kstep; const char* b2 = last ? nB : cB + (size_t)(t + 2) * kstep;
;             const char* a3 = a2 + kstep; const char* b3 = b2 + kstep;
;             if (last && has_next) S.a_ready(nxt);
;             if constexpr (SP2) {
;             PG8_LDB(B0, 0, 0); PG8_LDB(B1, 0, 1); PG8_SCHED; PG8_LDA(At, 0, 0); PG8_STAGE(PG8_SA(1, 1), a1 + hstep, voffA);
;             PG8_WAIT_V(8); PG8_WAIT_L(0); PG8_BAR; PG8_MMA(0, 0, At, B0); PG8_MMA(0, 1, At, B1); PG8_BAR; PG8_SCHED;
;             PG8_LDA(At, 0, 1); PG8_STAGE(PG8_SB(0, 0), b2, voffB); PG8_STAGE(PG8_SB(0, 1), b2 + hstep, voffB); PG8_STAGE(PG8_SA(0, 0), a2, voffA);
.LBB0_574:
	s_add_u32 s11, s58, 0xfffe0080
	s_addc_u32 s12, s59, -1
	s_add_i32 s13, 0, 0x10000
	s_cmp_eq_u32 s10, 4
	s_cselect_b32 s63, s53, s12
	s_cselect_b32 s62, vcc_lo, s11
	s_cselect_b32 s61, s51, s31
	s_cselect_b32 s60, vcc_hi, s30
	s_add_i32 s11, 0, 0x14000
	v_add_u32_e32 v140, s13, v233
	v_add_u32_e32 v156, s11, v233
	ds_read_b128 v[128:131], v140
	ds_read_b128 v[132:135], v140 offset:1024
	ds_read_b128 v[136:139], v140 offset:2048
	ds_read_b128 v[140:143], v140 offset:3072
	ds_read_b128 v[144:147], v156
	ds_read_b128 v[148:151], v156 offset:1024
	ds_read_b128 v[152:155], v156 offset:2048
	ds_read_b128 v[156:159], v156 offset:3072
	s_add_i32 m0, s20, 0xc000
	ds_read_b128 v[160:163], v235
	ds_read_b128 v[164:167], v235 offset:1024
	ds_read_b128 v[168:171], v235 offset:2048
	ds_read_b128 v[172:175], v235 offset:3072
	ds_read_b128 v[176:179], v235 offset:4096
	ds_read_b128 v[180:183], v235 offset:5120
	ds_read_b128 v[208:211], v235 offset:6144
	ds_read_b128 v[212:215], v235 offset:7168
	global_load_lds_dwordx4 v204, s[58:59]
	s_add_i32 m0, s20, 0xe000
	s_nop 0
	global_load_lds_dwordx4 v206, s[58:59]
	s_waitcnt vmcnt(8)
	s_waitcnt lgkmcnt(0)
	s_barrier
	s_setprio 1
	s_waitcnt lgkmcnt(0)
	v_mfma_f32_16x16x32_bf16 v[124:127], v[128:131], v[160:163], v[124:127]
	v_mfma_f32_16x16x32_bf16 v[120:123], v[136:139], v[160:163], v[120:123]
	v_mfma_f32_16x16x32_bf16 v[108:111], v[128:131], v[168:171], v[108:111]
	v_mfma_f32_16x16x32_bf16 v[104:107], v[136:139], v[168:171], v[104:107]
	v_mfma_f32_16x16x32_bf16 v[92:95], v[128:131], v[176:179], v[92:95]
	v_mfma_f32_16x16x32_bf16 v[88:91], v[136:139], v[176:179], v[88:91]
	v_mfma_f32_16x16x32_bf16 v[76:79], v[128:131], v[208:211], v[76:79]
	v_mfma_f32_16x16x32_bf16 v[72:75], v[136:139], v[208:211], v[72:75]
	v_mfma_f32_16x16x32_bf16 v[124:127], v[132:135], v[164:167], v[124:127]
	v_mfma_f32_16x16x32_bf16 v[120:123], v[140:143], v[164:167], v[120:123]
	v_mfma_f32_16x16x32_bf16 v[108:111], v[132:135], v[172:175], v[108:111]
	v_mfma_f32_16x16x32_bf16 v[104:107], v[140:143], v[172:175], v[104:107]
	v_mfma_f32_16x16x32_bf16 v[92:95], v[132:135], v[180:183], v[92:95]
	v_mfma_f32_16x16x32_bf16 v[88:91], v[140:143], v[180:183], v[88:91]
	v_mfma_f32_16x16x32_bf16 v[76:79], v[132:135], v[212:215], v[76:79]
	v_mfma_f32_16x16x32_bf16 v[72:75], v[140:143], v[212:215], v[72:75]
	s_setprio 0
	s_setprio 1
	v_mfma_f32_16x16x32_bf16 v[116:119], v[144:147], v[160:163], v[116:119]
	v_mfma_f32_16x16x32_bf16 v[112:115], v[152:155], v[160:163], v[112:115]
	v_mfma_f32_16x16x32_bf16 v[100:103], v[144:147], v[168:171], v[100:103]
	v_mfma_f32_16x16x32_bf16 v[96:99], v[152:155], v[168:171], v[96:99]
	v_mfma_f32_16x16x32_bf16 v[84:87], v[144:147], v[176:179], v[84:87]
	v_mfma_f32_16x16x32_bf16 v[80:83], v[152:155], v[176:179], v[80:83]
	v_mfma_f32_16x16x32_bf16 v[68:71], v[144:147], v[208:211], v[68:71]
	v_mfma_f32_16x16x32_bf16 v[64:67], v[152:155], v[208:211], v[64:67]
	v_mfma_f32_16x16x32_bf16 v[116:119], v[148:151], v[164:167], v[116:119]
	v_mfma_f32_16x16x32_bf16 v[112:115], v[156:159], v[164:167], v[112:115]
	v_mfma_f32_16x16x32_bf16 v[100:103], v[148:151], v[172:175], v[100:103]
	v_mfma_f32_16x16x32_bf16 v[96:99], v[156:159], v[172:175], v[96:99]
	v_mfma_f32_16x16x32_bf16 v[84:87], v[148:151], v[180:183], v[84:87]
	v_mfma_f32_16x16x32_bf16 v[80:83], v[156:159], v[180:183], v[80:83]
	v_mfma_f32_16x16x32_bf16 v[68:71], v[148:151], v[212:215], v[68:71]
	v_mfma_f32_16x16x32_bf16 v[64:67], v[156:159], v[212:215], v[64:67]
	s_setprio 0
	s_barrier
	s_add_i32 s12, s13, s9
	v_lshl_add_u64 v[216:217], s[60:61], 0, v[188:189]
	s_mov_b32 m0, s12
	ds_read_b128 v[160:163], v235 offset:16384
	ds_read_b128 v[164:167], v235 offset:17408
	ds_read_b128 v[168:171], v235 offset:18432
	ds_read_b128 v[172:175], v235 offset:19456
	ds_read_b128 v[176:179], v235 offset:20480
	ds_read_b128 v[180:183], v235 offset:21504
	ds_read_b128 v[208:211], v235 offset:22528
	ds_read_b128 v[212:215], v235 offset:23552
	global_load_lds_dwordx4 v[216:217], off
	s_add_i32 m0, s12, 0x2000
	s_add_u32 s12, s60, 0x20000
	v_lshl_add_u64 v[236:237], s[60:61], 0, v[198:199]
	s_addc_u32 s13, s61, 0
	s_add_i32 s11, s11, s9
	global_load_lds_dwordx4 v[236:237], off
	s_mov_b32 m0, s11
	v_lshl_add_u64 v[240:241], s[62:63], 0, v[200:201]
	global_load_lds_dwordx4 v188, s[12:13]
	s_add_i32 m0, s11, 0x2000
	s_nop 0
	global_load_lds_dwordx4 v198, s[12:13]
	v_lshl_add_u64 v[238:239], s[62:63], 0, v[202:203]
	s_mov_b32 m0, s20
	s_nop 0
	global_load_lds_dwordx4 v[238:239], off
	s_mov_b32 m0, s21
	s_nop 0
	global_load_lds_dwordx4 v[240:241], off
	s_waitcnt vmcnt(8)
	s_waitcnt lgkmcnt(0)
	s_barrier
; #define PG8_STAGE(bufoff, gbase, voff) do { _Pragma("unroll") for (int _i = 0; _i < 2; ++_i) \
;         __builtin_amdgcn_global_load_lds((const unsigned*)((const char*)(gbase) + (voff)[_i]), (PG8_LAS unsigned*)(lds + (bufoff) + ldsw + _i * 8192), 16, 0, 0); } while (0)
; #define PG8_LDA(dst, b, h) do { _Pragma("unroll") for (int m = 0; m < 4; ++m) _Pragma("unroll") for (int k = 0; k < 2; ++k) dst[m][k] = *(const PG8_LAS bf16x8*)(lds + PG8_SA(b, h) + aoff + m * 2048 + k * 1024); } while (0)
; #define PG8_LDB(dst, b, h) do { _Pragma("unroll") for (int n = 0; n < 2; ++n) _Pragma("unroll") for (int k = 0; k < 2; ++k) dst[n][k] = *(const PG8_LAS bf16x8*)(lds + PG8_SB(b, h) + boff + n * 2048 + k * 1024); } while (0)
; #define PG8_MMA(ai, bj, At, Bt) do { __builtin_amdgcn_s_setprio(1); _Pragma("unroll") for (int m = 0; m < 4; ++m) _Pragma("unroll") for (int n = 0; n < 2; ++n) _Pragma("unroll") for (int k = 0; k < 2; ++k) \
;         acc[ai][bj][m][n] = __builtin_amdgcn_mfma_f32_16x16x32_bf16(Bt[n][k], At[m][k], acc[ai][bj][m][n], 0, 0, 0); __builtin_amdgcn_s_setprio(0); } while (0)
; #define PG8_WAIT_V(n) asm volatile("s_waitcnt vmcnt(" #n ")" ::: "memory")
; #define PG8_WAIT_L(n) asm volatile("s_waitcnt lgkmcnt(" #n ")" ::: "memory")
; #define PG8_BAR __builtin_amdgcn_s_barrier()
; #define PG8_SCHED __builtin_amdgcn_sched_barrier(0)
; template <class Epi, class Sched, bool ALIGN_EPI = false, bool SP2 = false>
; __device__ __forceinline__ void gemm_phase(PG8_LAS unsigned char* lds, const Gemm g, const Sched& S, const Epi& E) {
;     ...
;             PG8_WAIT_V(8); PG8_WAIT_L(0); PG8_BAR; PG8_MMA(1, 0, At, B0); PG8_MMA(1, 1, At, B1); PG8_BAR; PG8_SCHED;
;             PG8_LDB(B0, 1, 0); PG8_LDB(B1, 1, 1); PG8_SCHED; PG8_LDA(At, 1, 0); PG8_STAGE(PG8_SA(0, 1), a2 + hstep, voffA);
;             PG8_WAIT_V(8); PG8_WAIT_L(0); PG8_BAR; PG8_MMA(0, 0, At, B0); PG8_MMA(0, 1, At, B1); PG8_BAR; PG8_SCHED;
	s_setprio 1
	s_waitcnt lgkmcnt(0)
	v_mfma_f32_16x16x32_bf16 v[60:63], v[128:131], v[160:163], v[60:63]
	v_mfma_f32_16x16x32_bf16 v[56:59], v[136:139], v[160:163], v[56:59]
	v_mfma_f32_16x16x32_bf16 v[44:47], v[128:131], v[168:171], v[44:47]
	v_mfma_f32_16x16x32_bf16 v[40:43], v[136:139], v[168:171], v[40:43]
	v_mfma_f32_16x16x32_bf16 v[28:31], v[128:131], v[176:179], v[28:31]
	v_mfma_f32_16x16x32_bf16 v[24:27], v[136:139], v[176:179], v[24:27]
	v_mfma_f32_16x16x32_bf16 v[12:15], v[128:131], v[208:211], v[12:15]
	v_mfma_f32_16x16x32_bf16 v[8:11], v[136:139], v[208:211], v[8:11]
	v_mfma_f32_16x16x32_bf16 v[60:63], v[132:135], v[164:167], v[60:63]
	v_mfma_f32_16x16x32_bf16 v[56:59], v[140:143], v[164:167], v[56:59]
	v_mfma_f32_16x16x32_bf16 v[44:47], v[132:135], v[172:175], v[44:47]
	v_mfma_f32_16x16x32_bf16 v[40:43], v[140:143], v[172:175], v[40:43]
	v_mfma_f32_16x16x32_bf16 v[28:31], v[132:135], v[180:183], v[28:31]
	v_mfma_f32_16x16x32_bf16 v[24:27], v[140:143], v[180:183], v[24:27]
	v_mfma_f32_16x16x32_bf16 v[12:15], v[132:135], v[212:215], v[12:15]
	v_mfma_f32_16x16x32_bf16 v[8:11], v[140:143], v[212:215], v[8:11]
	s_setprio 0
	s_setprio 1
	v_mfma_f32_16x16x32_bf16 v[52:55], v[144:147], v[160:163], v[52:55]
	v_mfma_f32_16x16x32_bf16 v[48:51], v[152:155], v[160:163], v[48:51]
	v_mfma_f32_16x16x32_bf16 v[36:39], v[144:147], v[168:171], v[36:39]
	v_mfma_f32_16x16x32_bf16 v[32:35], v[152:155], v[168:171], v[32:35]
	v_mfma_f32_16x16x32_bf16 v[20:23], v[144:147], v[176:179], v[20:23]
	v_mfma_f32_16x16x32_bf16 v[16:19], v[152:155], v[176:179], v[16:19]
	v_mfma_f32_16x16x32_bf16 v[4:7], v[144:147], v[208:211], v[4:7]
	v_mfma_f32_16x16x32_bf16 v[0:3], v[152:155], v[208:211], v[0:3]
	v_mfma_f32_16x16x32_bf16 v[52:55], v[148:151], v[164:167], v[52:55]
	v_mfma_f32_16x16x32_bf16 v[48:51], v[156:159], v[164:167], v[48:51]
	v_mfma_f32_16x16x32_bf16 v[36:39], v[148:151], v[172:175], v[36:39]
	v_mfma_f32_16x16x32_bf16 v[32:35], v[156:159], v[172:175], v[32:35]
	v_mfma_f32_16x16x32_bf16 v[20:23], v[148:151], v[180:183], v[20:23]
	v_mfma_f32_16x16x32_bf16 v[16:19], v[156:159], v[180:183], v[16:19]
	v_mfma_f32_16x16x32_bf16 v[4:7], v[148:151], v[212:215], v[4:7]
	v_mfma_f32_16x16x32_bf16 v[0:3], v[156:159], v[212:215], v[0:3]
	s_setprio 0
	s_barrier
	s_add_i32 s11, 0, 0x18000
	s_add_i32 s14, 0, 0x1c000
	v_add_u32_e32 v140, s11, v233
	v_add_u32_e32 v156, s14, v233
	ds_read_b128 v[128:131], v140
	ds_read_b128 v[132:135], v140 offset:1024
	ds_read_b128 v[136:139], v140 offset:2048
	ds_read_b128 v[140:143], v140 offset:3072
	ds_read_b128 v[144:147], v156
	ds_read_b128 v[148:151], v156 offset:1024
	ds_read_b128 v[152:155], v156 offset:2048
	ds_read_b128 v[156:159], v156 offset:3072
	s_add_u32 s12, s62, 0x20000
	s_addc_u32 s13, s63, 0
	s_mov_b32 m0, s24
	ds_read_b128 v[160:163], v235 offset:32768
	ds_read_b128 v[164:167], v235 offset:33792
	ds_read_b128 v[168:171], v235 offset:34816
	ds_read_b128 v[172:175], v235 offset:35840
	ds_read_b128 v[176:179], v235 offset:36864
	ds_read_b128 v[180:183], v235 offset:37888
	ds_read_b128 v[208:211], v235 offset:38912
	ds_read_b128 v[212:215], v235 offset:39936
	global_load_lds_dwordx4 v202, s[12:13]
	s_mov_b32 m0, s29
	s_nop 0
	global_load_lds_dwordx4 v200, s[12:13]
	s_waitcnt vmcnt(8)
	s_waitcnt lgkmcnt(0)
	s_barrier
	s_setprio 1
	s_waitcnt lgkmcnt(0)
	v_mfma_f32_16x16x32_bf16 v[124:127], v[128:131], v[160:163], v[124:127]
	v_mfma_f32_16x16x32_bf16 v[120:123], v[136:139], v[160:163], v[120:123]
	v_mfma_f32_16x16x32_bf16 v[108:111], v[128:131], v[168:171], v[108:111]
	v_mfma_f32_16x16x32_bf16 v[104:107], v[136:139], v[168:171], v[104:107]
	v_mfma_f32_16x16x32_bf16 v[92:95], v[128:131], v[176:179], v[92:95]
	v_mfma_f32_16x16x32_bf16 v[88:91], v[136:139], v[176:179], v[88:91]
	v_mfma_f32_16x16x32_bf16 v[76:79], v[128:131], v[208:211], v[76:79]
	v_mfma_f32_16x16x32_bf16 v[72:75], v[136:139], v[208:211], v[72:75]
	v_mfma_f32_16x16x32_bf16 v[124:127], v[132:135], v[164:167], v[124:127]
	v_mfma_f32_16x16x32_bf16 v[120:123], v[140:143], v[164:167], v[120:123]
	v_mfma_f32_16x16x32_bf16 v[108:111], v[132:135], v[172:175], v[108:111]
	v_mfma_f32_16x16x32_bf16 v[104:107], v[140:143], v[172:175], v[104:107]
	v_mfma_f32_16x16x32_bf16 v[92:95], v[132:135], v[180:183], v[92:95]
	v_mfma_f32_16x16x32_bf16 v[88:91], v[140:143], v[180:183], v[88:91]
	v_mfma_f32_16x16x32_bf16 v[76:79], v[132:135], v[212:215], v[76:79]
	v_mfma_f32_16x16x32_bf16 v[72:75], v[140:143], v[212:215], v[72:75]
	s_setprio 0
	s_setprio 1
	v_mfma_f32_16x16x32_bf16 v[116:119], v[144:147], v[160:163], v[116:119]
	v_mfma_f32_16x16x32_bf16 v[112:115], v[152:155], v[160:163], v[112:115]
	v_mfma_f32_16x16x32_bf16 v[100:103], v[144:147], v[168:171], v[100:103]
	v_mfma_f32_16x16x32_bf16 v[96:99], v[152:155], v[168:171], v[96:99]
	v_mfma_f32_16x16x32_bf16 v[84:87], v[144:147], v[176:179], v[84:87]
	v_mfma_f32_16x16x32_bf16 v[80:83], v[152:155], v[176:179], v[80:83]
	v_mfma_f32_16x16x32_bf16 v[68:71], v[144:147], v[208:211], v[68:71]
	v_mfma_f32_16x16x32_bf16 v[64:67], v[152:155], v[208:211], v[64:67]
	v_mfma_f32_16x16x32_bf16 v[116:119], v[148:151], v[164:167], v[116:119]
	v_mfma_f32_16x16x32_bf16 v[112:115], v[156:159], v[164:167], v[112:115]
	v_mfma_f32_16x16x32_bf16 v[100:103], v[148:151], v[172:175], v[100:103]
	v_mfma_f32_16x16x32_bf16 v[96:99], v[156:159], v[172:175], v[96:99]
	v_mfma_f32_16x16x32_bf16 v[84:87], v[148:151], v[180:183], v[84:87]
	v_mfma_f32_16x16x32_bf16 v[80:83], v[156:159], v[180:183], v[80:83]
	v_mfma_f32_16x16x32_bf16 v[68:71], v[148:151], v[212:215], v[68:71]
	v_mfma_f32_16x16x32_bf16 v[64:67], v[156:159], v[212:215], v[64:67]
	s_setprio 0
	s_barrier
; #define PG8_STAGE(bufoff, gbase, voff) do { _Pragma("unroll") for (int _i = 0; _i < 2; ++_i) \
;         __builtin_amdgcn_global_load_lds((const unsigned*)((const char*)(gbase) + (voff)[_i]), (PG8_LAS unsigned*)(lds + (bufoff) + ldsw + _i * 8192), 16, 0, 0); } while (0)
; #define PG8_LDA(dst, b, h) do { _Pragma("unroll") for (int m = 0; m < 4; ++m) _Pragma("unroll") for (int k = 0; k < 2; ++k) dst[m][k] = *(const PG8_LAS bf16x8*)(lds + PG8_SA(b, h) + aoff + m * 2048 + k * 1024); } while (0)
; #define PG8_MMA(ai, bj, At, Bt) do { __builtin_amdgcn_s_setprio(1); _Pragma("unroll") for (int m = 0; m < 4; ++m) _Pragma("unroll") for (int n = 0; n < 2; ++n) _Pragma("unroll") for (int k = 0; k < 2; ++k) \
;         acc[ai][bj][m][n] = __builtin_amdgcn_mfma_f32_16x16x32_bf16(Bt[n][k], At[m][k], acc[ai][bj][m][n], 0, 0, 0); __builtin_amdgcn_s_setprio(0); } while (0)
; #define PG8_WAIT_V(n) asm volatile("s_waitcnt vmcnt(" #n ")" ::: "memory")
; #define PG8_WAIT_L(n) asm volatile("s_waitcnt lgkmcnt(" #n ")" ::: "memory")
; #define PG8_BAR __builtin_amdgcn_s_barrier()
; #define PG8_SCHED __builtin_amdgcn_sched_barrier(0)
; template <class Epi, class Sched, bool ALIGN_EPI = false, bool SP2 = false>
; __device__ __forceinline__ void gemm_phase(PG8_LAS unsigned char* lds, const Gemm g, const Sched& S, const Epi& E) {
;     ...
;             PG8_LDA(At, 1, 1); PG8_STAGE(PG8_SB(1, 0), b3, voffB); PG8_STAGE(PG8_SB(1, 1), b3 + hstep, voffB); PG8_STAGE(PG8_SA(1, 0), a3, voffA);
;             PG8_WAIT_V(8); PG8_WAIT_L(0); PG8_BAR; PG8_MMA(1, 0, At, B0); PG8_MMA(1, 1, At, B1); PG8_BAR; PG8_SCHED;
;     ...
;         if constexpr (ALIGN_EPI) { if (wr == 0) PG8_BAR; }
	s_add_i32 s11, s11, s9
	v_lshl_add_u64 v[216:217], v[216:217], 0, s[34:35]
	s_mov_b32 m0, s11
	ds_read_b128 v[160:163], v235 offset:49152
	ds_read_b128 v[164:167], v235 offset:50176
	ds_read_b128 v[168:171], v235 offset:51200
	ds_read_b128 v[172:175], v235 offset:52224
	ds_read_b128 v[176:179], v235 offset:53248
	ds_read_b128 v[180:183], v235 offset:54272
	ds_read_b128 v[208:211], v235 offset:55296
	ds_read_b128 v[212:215], v235 offset:56320
	global_load_lds_dwordx4 v[216:217], off
	s_add_i32 m0, s11, 0x2000
	s_add_u32 s12, s60, 0x20080
	v_lshl_add_u64 v[216:217], v[236:237], 0, s[34:35]
	s_addc_u32 s13, s61, 0
	s_add_i32 s11, s14, s9
	global_load_lds_dwordx4 v[216:217], off
	s_mov_b32 m0, s11
	s_nop 0
	global_load_lds_dwordx4 v188, s[12:13]
	s_add_i32 m0, s11, 0x2000
	s_nop 0
	global_load_lds_dwordx4 v198, s[12:13]
	v_lshl_add_u64 v[216:217], v[238:239], 0, s[34:35]
	s_mov_b32 m0, s38
	s_nop 0
	global_load_lds_dwordx4 v[216:217], off
	v_lshl_add_u64 v[216:217], v[240:241], 0, s[34:35]
	s_mov_b32 m0, s39
	s_nop 0
	global_load_lds_dwordx4 v[216:217], off
	s_waitcnt vmcnt(8)
	s_waitcnt lgkmcnt(0)
	s_barrier
	s_setprio 1
	s_waitcnt lgkmcnt(0)
	v_mfma_f32_16x16x32_bf16 v[60:63], v[128:131], v[160:163], v[60:63]
	v_mfma_f32_16x16x32_bf16 v[56:59], v[136:139], v[160:163], v[56:59]
	v_mfma_f32_16x16x32_bf16 v[44:47], v[128:131], v[168:171], v[44:47]
	v_mfma_f32_16x16x32_bf16 v[40:43], v[136:139], v[168:171], v[40:43]
	v_mfma_f32_16x16x32_bf16 v[28:31], v[128:131], v[176:179], v[28:31]
	v_mfma_f32_16x16x32_bf16 v[24:27], v[136:139], v[176:179], v[24:27]
	v_mfma_f32_16x16x32_bf16 v[12:15], v[128:131], v[208:211], v[12:15]
	v_mfma_f32_16x16x32_bf16 v[8:11], v[136:139], v[208:211], v[8:11]
	v_mfma_f32_16x16x32_bf16 v[60:63], v[132:135], v[164:167], v[60:63]
	v_mfma_f32_16x16x32_bf16 v[56:59], v[140:143], v[164:167], v[56:59]
	v_mfma_f32_16x16x32_bf16 v[44:47], v[132:135], v[172:175], v[44:47]
	v_mfma_f32_16x16x32_bf16 v[40:43], v[140:143], v[172:175], v[40:43]
	v_mfma_f32_16x16x32_bf16 v[28:31], v[132:135], v[180:183], v[28:31]
	v_mfma_f32_16x16x32_bf16 v[24:27], v[140:143], v[180:183], v[24:27]
	v_mfma_f32_16x16x32_bf16 v[12:15], v[132:135], v[212:215], v[12:15]
	v_mfma_f32_16x16x32_bf16 v[8:11], v[140:143], v[212:215], v[8:11]
	s_setprio 0
	s_setprio 1
	v_mfma_f32_16x16x32_bf16 v[52:55], v[144:147], v[160:163], v[52:55]
	v_mfma_f32_16x16x32_bf16 v[48:51], v[152:155], v[160:163], v[48:51]
	v_mfma_f32_16x16x32_bf16 v[36:39], v[144:147], v[168:171], v[36:39]
	v_mfma_f32_16x16x32_bf16 v[32:35], v[152:155], v[168:171], v[32:35]
	v_mfma_f32_16x16x32_bf16 v[20:23], v[144:147], v[176:179], v[20:23]
	v_mfma_f32_16x16x32_bf16 v[16:19], v[152:155], v[176:179], v[16:19]
	v_mfma_f32_16x16x32_bf16 v[4:7], v[144:147], v[208:211], v[4:7]
	v_mfma_f32_16x16x32_bf16 v[0:3], v[152:155], v[208:211], v[0:3]
	v_mfma_f32_16x16x32_bf16 v[52:55], v[148:151], v[164:167], v[52:55]
	v_mfma_f32_16x16x32_bf16 v[48:51], v[156:159], v[164:167], v[48:51]
	v_mfma_f32_16x16x32_bf16 v[36:39], v[148:151], v[172:175], v[36:39]
	v_mfma_f32_16x16x32_bf16 v[32:35], v[156:159], v[172:175], v[32:35]
	v_mfma_f32_16x16x32_bf16 v[20:23], v[148:151], v[180:183], v[20:23]
	v_mfma_f32_16x16x32_bf16 v[16:19], v[156:159], v[180:183], v[16:19]
	v_mfma_f32_16x16x32_bf16 v[4:7], v[148:151], v[212:215], v[4:7]
	v_mfma_f32_16x16x32_bf16 v[0:3], v[156:159], v[212:215], v[0:3]
	s_setprio 0
	s_barrier
	s_add_i32 s10, s10, 2
	s_add_u32 s58, s58, 0x100
	s_addc_u32 s59, s59, 0
	s_add_u32 s30, s30, 0x100
	s_addc_u32 s31, s31, 0
	s_cmp_gt_u32 s10, 5
	s_cbranch_scc0 .LBB0_574
	s_and_b64 vcc, exec, s[48:49]
	s_cbranch_vccz .LBB0_577
	s_barrier

; #define PG8_STAGE(bufoff, gbase, voff) do { _Pragma("unroll") for (int _i = 0; _i < 2; ++_i) \
;         __builtin_amdgcn_global_load_lds((const unsigned*)((const char*)(gbase) + (voff)[_i]), (PG8_LAS unsigned*)(lds + (bufoff) + ldsw + _i * 8192), 16, 0, 0); } while (0)
; #define PG8_LDA(dst, b, h) do { _Pragma("unroll") for (int m = 0; m < 4; ++m) _Pragma("unroll") for (int k = 0; k < 2; ++k) dst[m][k] = *(const PG8_LAS bf16x8*)(lds + PG8_SA(b, h) + aoff + m * 2048 + k * 1024); } while (0)
; #define PG8_LDB(dst, b, h) do { _Pragma("unroll") for (int n = 0; n < 2; ++n) _Pragma("unroll") for (int k = 0; k < 2; ++k) dst[n][k] = *(const PG8_LAS bf16x8*)(lds + PG8_SB(b, h) + boff + n * 2048 + k * 1024); } while (0)
; #define PG8_MMA(ai, bj, At, Bt) do { __builtin_amdgcn_s_setprio(1); _Pragma("unroll") for (int m = 0; m < 4; ++m) _Pragma("unroll") for (int n = 0; n < 2; ++n) _Pragma("unroll") for (int k = 0; k < 2; ++k) \
;         acc[ai][bj][m][n] = __builtin_amdgcn_mfma_f32_16x16x32_bf16(Bt[n][k], At[m][k], acc[ai][bj][m][n], 0, 0, 0); __builtin_amdgcn_s_setprio(0); } while (0)
; #define PG8_WAIT_V(n) asm volatile("s_waitcnt vmcnt(" #n ")" ::: "memory")
; #define PG8_WAIT_L(n) asm volatile("s_waitcnt lgkmcnt(" #n ")" ::: "memory")
; #define PG8_BAR __builtin_amdgcn_s_barrier()
; #define PG8_SCHED __builtin_amdgcn_sched_barrier(0)
; template <class Epi, class Sched, bool ALIGN_EPI = false, bool SP2 = false>
; __device__ __forceinline__ void gemm_phase(PG8_LAS unsigned char* lds, const Gemm g, const Sched& S, const Epi& E) {
;     ...
;             const char* a1 = cA + (size_t)(t + 1) * kstep;
;             const char* a2 = last ? nA : cA + (size_t)(t + 2) * kstep; const char* b2 = last ? nB : cB + (size_t)(t + 2) * kstep;
;             const char* a3 = a2 + kstep; const char* b3 = b2 + kstep;
;             if (last && has_next) S.a_ready(nxt);
;             if constexpr (SP2) {
;             PG8_LDB(B0, 0, 0); PG8_LDB(B1, 0, 1); PG8_SCHED; PG8_LDA(At, 0, 0); PG8_STAGE(PG8_SA(1, 1), a1 + hstep, voffA);
;             PG8_WAIT_V(8); PG8_WAIT_L(0); PG8_BAR; PG8_MMA(0, 0, At, B0); PG8_MMA(0, 1, At, B1); PG8_BAR; PG8_SCHED;
;             PG8_LDA(At, 0, 1); PG8_STAGE(PG8_SB(0, 0), b2, voffB); PG8_STAGE(PG8_SB(0, 1), b2 + hstep, voffB); PG8_STAGE(PG8_SA(0, 0), a2, voffA);
.LBB0_642:
	s_add_u32 s11, s56, 0xfffc0080
	s_addc_u32 s12, s57, -1
	s_add_i32 s13, 0, 0x10000
	s_cmp_eq_u32 s10, 12
	s_cselect_b32 s61, s51, s12
	s_cselect_b32 s60, s72, s11
	s_cselect_b32 s59, s49, s31
	s_cselect_b32 s58, s73, s30
	s_add_i32 s11, 0, 0x14000
	v_add_u32_e32 v154, s13, v139
	v_add_u32_e32 v170, s11, v139
	ds_read_b128 v[142:145], v154
	ds_read_b128 v[146:149], v154 offset:1024
	ds_read_b128 v[150:153], v154 offset:2048
	ds_read_b128 v[154:157], v154 offset:3072
	ds_read_b128 v[158:161], v170
	ds_read_b128 v[162:165], v170 offset:1024
	ds_read_b128 v[166:169], v170 offset:2048
	ds_read_b128 v[170:173], v170 offset:3072
	s_add_i32 m0, s20, 0xc000
	ds_read_b128 v[174:177], v141
	ds_read_b128 v[178:181], v141 offset:1024
	ds_read_b128 v[198:201], v141 offset:2048
	ds_read_b128 v[202:205], v141 offset:3072
	ds_read_b128 v[206:209], v141 offset:4096
	ds_read_b128 v[210:213], v141 offset:5120
	ds_read_b128 v[214:217], v141 offset:6144
	ds_read_b128 v[232:235], v141 offset:7168
	global_load_lds_dwordx4 v134, s[56:57]
	s_add_i32 m0, s20, 0xe000
	s_nop 0
	global_load_lds_dwordx4 v136, s[56:57]
	s_waitcnt vmcnt(8)
	s_waitcnt lgkmcnt(0)
	s_barrier
	s_setprio 1
	s_waitcnt lgkmcnt(0)
	v_mfma_f32_16x16x32_bf16 v[124:127], v[142:145], v[174:177], v[124:127]
	v_mfma_f32_16x16x32_bf16 v[120:123], v[150:153], v[174:177], v[120:123]
	v_mfma_f32_16x16x32_bf16 v[116:119], v[142:145], v[198:201], v[116:119]
	v_mfma_f32_16x16x32_bf16 v[112:115], v[150:153], v[198:201], v[112:115]
	v_mfma_f32_16x16x32_bf16 v[100:103], v[142:145], v[206:209], v[100:103]
	v_mfma_f32_16x16x32_bf16 v[96:99], v[150:153], v[206:209], v[96:99]
	v_mfma_f32_16x16x32_bf16 v[84:87], v[142:145], v[214:217], v[84:87]
	v_mfma_f32_16x16x32_bf16 v[80:83], v[150:153], v[214:217], v[80:83]
	v_mfma_f32_16x16x32_bf16 v[124:127], v[146:149], v[178:181], v[124:127]
	v_mfma_f32_16x16x32_bf16 v[120:123], v[154:157], v[178:181], v[120:123]
	v_mfma_f32_16x16x32_bf16 v[116:119], v[146:149], v[202:205], v[116:119]
	v_mfma_f32_16x16x32_bf16 v[112:115], v[154:157], v[202:205], v[112:115]
	v_mfma_f32_16x16x32_bf16 v[100:103], v[146:149], v[210:213], v[100:103]
	v_mfma_f32_16x16x32_bf16 v[96:99], v[154:157], v[210:213], v[96:99]
	v_mfma_f32_16x16x32_bf16 v[84:87], v[146:149], v[232:235], v[84:87]
	v_mfma_f32_16x16x32_bf16 v[80:83], v[154:157], v[232:235], v[80:83]
	s_setprio 0
	s_setprio 1
	v_mfma_f32_16x16x32_bf16 v[108:111], v[158:161], v[174:177], v[108:111]
	v_mfma_f32_16x16x32_bf16 v[104:107], v[166:169], v[174:177], v[104:107]
	v_mfma_f32_16x16x32_bf16 v[92:95], v[158:161], v[198:201], v[92:95]
	v_mfma_f32_16x16x32_bf16 v[88:91], v[166:169], v[198:201], v[88:91]
	v_mfma_f32_16x16x32_bf16 v[76:79], v[158:161], v[206:209], v[76:79]
	v_mfma_f32_16x16x32_bf16 v[72:75], v[166:169], v[206:209], v[72:75]
	v_mfma_f32_16x16x32_bf16 v[68:71], v[158:161], v[214:217], v[68:71]
	v_mfma_f32_16x16x32_bf16 v[64:67], v[166:169], v[214:217], v[64:67]
	v_mfma_f32_16x16x32_bf16 v[108:111], v[162:165], v[178:181], v[108:111]
	v_mfma_f32_16x16x32_bf16 v[104:107], v[170:173], v[178:181], v[104:107]
	v_mfma_f32_16x16x32_bf16 v[92:95], v[162:165], v[202:205], v[92:95]
	v_mfma_f32_16x16x32_bf16 v[88:91], v[170:173], v[202:205], v[88:91]
	v_mfma_f32_16x16x32_bf16 v[76:79], v[162:165], v[210:213], v[76:79]
	v_mfma_f32_16x16x32_bf16 v[72:75], v[170:173], v[210:213], v[72:75]
	v_mfma_f32_16x16x32_bf16 v[68:71], v[162:165], v[232:235], v[68:71]
	v_mfma_f32_16x16x32_bf16 v[64:67], v[170:173], v[232:235], v[64:67]
	s_setprio 0
	s_barrier
	s_add_i32 s12, s13, s9
	v_lshl_add_u64 v[182:183], s[58:59], 0, v[188:189]
	s_mov_b32 m0, s12
	ds_read_b128 v[174:177], v141 offset:16384
	ds_read_b128 v[178:181], v141 offset:17408
	ds_read_b128 v[198:201], v141 offset:18432
	ds_read_b128 v[202:205], v141 offset:19456
	ds_read_b128 v[206:209], v141 offset:20480
	ds_read_b128 v[210:213], v141 offset:21504
	ds_read_b128 v[214:217], v141 offset:22528
	ds_read_b128 v[232:235], v141 offset:23552
	global_load_lds_dwordx4 v[182:183], off
	s_add_i32 m0, s12, 0x2000
	s_add_u32 s12, s58, 0x40000
	v_lshl_add_u64 v[236:237], s[58:59], 0, v[128:129]
	s_addc_u32 s13, s59, 0
	s_add_i32 s11, s11, s9
	global_load_lds_dwordx4 v[236:237], off
	s_mov_b32 m0, s11
	v_lshl_add_u64 v[240:241], s[60:61], 0, v[130:131]
	global_load_lds_dwordx4 v188, s[12:13]
	s_add_i32 m0, s11, 0x2000
	s_nop 0
	global_load_lds_dwordx4 v128, s[12:13]
	v_lshl_add_u64 v[238:239], s[60:61], 0, v[132:133]
	s_mov_b32 m0, s20
	s_nop 0
	global_load_lds_dwordx4 v[238:239], off
	s_mov_b32 m0, s21
	s_nop 0
	global_load_lds_dwordx4 v[240:241], off
	s_waitcnt vmcnt(8)
	s_waitcnt lgkmcnt(0)
	s_barrier
; #define PG8_STAGE(bufoff, gbase, voff) do { _Pragma("unroll") for (int _i = 0; _i < 2; ++_i) \
;         __builtin_amdgcn_global_load_lds((const unsigned*)((const char*)(gbase) + (voff)[_i]), (PG8_LAS unsigned*)(lds + (bufoff) + ldsw + _i * 8192), 16, 0, 0); } while (0)
; #define PG8_LDA(dst, b, h) do { _Pragma("unroll") for (int m = 0; m < 4; ++m) _Pragma("unroll") for (int k = 0; k < 2; ++k) dst[m][k] = *(const PG8_LAS bf16x8*)(lds + PG8_SA(b, h) + aoff + m * 2048 + k * 1024); } while (0)
; #define PG8_LDB(dst, b, h) do { _Pragma("unroll") for (int n = 0; n < 2; ++n) _Pragma("unroll") for (int k = 0; k < 2; ++k) dst[n][k] = *(const PG8_LAS bf16x8*)(lds + PG8_SB(b, h) + boff + n * 2048 + k * 1024); } while (0)
; #define PG8_MMA(ai, bj, At, Bt) do { __builtin_amdgcn_s_setprio(1); _Pragma("unroll") for (int m = 0; m < 4; ++m) _Pragma("unroll") for (int n = 0; n < 2; ++n) _Pragma("unroll") for (int k = 0; k < 2; ++k) \
;         acc[ai][bj][m][n] = __builtin_amdgcn_mfma_f32_16x16x32_bf16(Bt[n][k], At[m][k], acc[ai][bj][m][n], 0, 0, 0); __builtin_amdgcn_s_setprio(0); } while (0)
; #define PG8_WAIT_V(n) asm volatile("s_waitcnt vmcnt(" #n ")" ::: "memory")
; #define PG8_WAIT_L(n) asm volatile("s_waitcnt lgkmcnt(" #n ")" ::: "memory")
; #define PG8_BAR __builtin_amdgcn_s_barrier()
; #define PG8_SCHED __builtin_amdgcn_sched_barrier(0)
; template <class Epi, class Sched, bool ALIGN_EPI = false, bool SP2 = false>
; __device__ __forceinline__ void gemm_phase(PG8_LAS unsigned char* lds, const Gemm g, const Sched& S, const Epi& E) {
;     ...
;             PG8_WAIT_V(8); PG8_WAIT_L(0); PG8_BAR; PG8_MMA(1, 0, At, B0); PG8_MMA(1, 1, At, B1); PG8_BAR; PG8_SCHED;
;             PG8_LDB(B0, 1, 0); PG8_LDB(B1, 1, 1); PG8_SCHED; PG8_LDA(At, 1, 0); PG8_STAGE(PG8_SA(0, 1), a2 + hstep, voffA);
;             PG8_WAIT_V(8); PG8_WAIT_L(0); PG8_BAR; PG8_MMA(0, 0, At, B0); PG8_MMA(0, 1, At, B1); PG8_BAR; PG8_SCHED;
	s_setprio 1
	s_waitcnt lgkmcnt(0)
	v_mfma_f32_16x16x32_bf16 v[60:63], v[142:145], v[174:177], v[60:63]
	v_mfma_f32_16x16x32_bf16 v[56:59], v[150:153], v[174:177], v[56:59]
	v_mfma_f32_16x16x32_bf16 v[52:55], v[142:145], v[198:201], v[52:55]
	v_mfma_f32_16x16x32_bf16 v[48:51], v[150:153], v[198:201], v[48:51]
	v_mfma_f32_16x16x32_bf16 v[36:39], v[142:145], v[206:209], v[36:39]
	v_mfma_f32_16x16x32_bf16 v[32:35], v[150:153], v[206:209], v[32:35]
	v_mfma_f32_16x16x32_bf16 v[20:23], v[142:145], v[214:217], v[20:23]
	v_mfma_f32_16x16x32_bf16 v[16:19], v[150:153], v[214:217], v[16:19]
	v_mfma_f32_16x16x32_bf16 v[60:63], v[146:149], v[178:181], v[60:63]
	v_mfma_f32_16x16x32_bf16 v[56:59], v[154:157], v[178:181], v[56:59]
	v_mfma_f32_16x16x32_bf16 v[52:55], v[146:149], v[202:205], v[52:55]
	v_mfma_f32_16x16x32_bf16 v[48:51], v[154:157], v[202:205], v[48:51]
	v_mfma_f32_16x16x32_bf16 v[36:39], v[146:149], v[210:213], v[36:39]
	v_mfma_f32_16x16x32_bf16 v[32:35], v[154:157], v[210:213], v[32:35]
	v_mfma_f32_16x16x32_bf16 v[20:23], v[146:149], v[232:235], v[20:23]
	v_mfma_f32_16x16x32_bf16 v[16:19], v[154:157], v[232:235], v[16:19]
	s_setprio 0
	s_setprio 1
	v_mfma_f32_16x16x32_bf16 v[44:47], v[158:161], v[174:177], v[44:47]
	v_mfma_f32_16x16x32_bf16 v[40:43], v[166:169], v[174:177], v[40:43]
	v_mfma_f32_16x16x32_bf16 v[28:31], v[158:161], v[198:201], v[28:31]
	v_mfma_f32_16x16x32_bf16 v[24:27], v[166:169], v[198:201], v[24:27]
	v_mfma_f32_16x16x32_bf16 v[12:15], v[158:161], v[206:209], v[12:15]
	v_mfma_f32_16x16x32_bf16 v[8:11], v[166:169], v[206:209], v[8:11]
	v_mfma_f32_16x16x32_bf16 v[4:7], v[158:161], v[214:217], v[4:7]
	v_mfma_f32_16x16x32_bf16 v[0:3], v[166:169], v[214:217], v[0:3]
	v_mfma_f32_16x16x32_bf16 v[44:47], v[162:165], v[178:181], v[44:47]
	v_mfma_f32_16x16x32_bf16 v[40:43], v[170:173], v[178:181], v[40:43]
	v_mfma_f32_16x16x32_bf16 v[28:31], v[162:165], v[202:205], v[28:31]
	v_mfma_f32_16x16x32_bf16 v[24:27], v[170:173], v[202:205], v[24:27]
	v_mfma_f32_16x16x32_bf16 v[12:15], v[162:165], v[210:213], v[12:15]
	v_mfma_f32_16x16x32_bf16 v[8:11], v[170:173], v[210:213], v[8:11]
	v_mfma_f32_16x16x32_bf16 v[4:7], v[162:165], v[232:235], v[4:7]
	v_mfma_f32_16x16x32_bf16 v[0:3], v[170:173], v[232:235], v[0:3]
	s_setprio 0
	s_barrier
	s_add_i32 s11, 0, 0x18000
	s_add_i32 s14, 0, 0x1c000
	v_add_u32_e32 v154, s11, v139
	v_add_u32_e32 v170, s14, v139
	ds_read_b128 v[142:145], v154
	ds_read_b128 v[146:149], v154 offset:1024
	ds_read_b128 v[150:153], v154 offset:2048
	ds_read_b128 v[154:157], v154 offset:3072
	ds_read_b128 v[158:161], v170
	ds_read_b128 v[162:165], v170 offset:1024
	ds_read_b128 v[166:169], v170 offset:2048
	ds_read_b128 v[170:173], v170 offset:3072
	s_add_u32 s12, s60, 0x40000
	s_addc_u32 s13, s61, 0
	s_mov_b32 m0, s24
	ds_read_b128 v[174:177], v141 offset:32768
	ds_read_b128 v[178:181], v141 offset:33792
	ds_read_b128 v[198:201], v141 offset:34816
	ds_read_b128 v[202:205], v141 offset:35840
	ds_read_b128 v[206:209], v141 offset:36864
	ds_read_b128 v[210:213], v141 offset:37888
	ds_read_b128 v[214:217], v141 offset:38912
	ds_read_b128 v[232:235], v141 offset:39936
	global_load_lds_dwordx4 v132, s[12:13]
	s_mov_b32 m0, s29
	s_nop 0
	global_load_lds_dwordx4 v130, s[12:13]
	s_waitcnt vmcnt(8)
	s_waitcnt lgkmcnt(0)
	s_barrier
	s_setprio 1
	s_waitcnt lgkmcnt(0)
	v_mfma_f32_16x16x32_bf16 v[124:127], v[142:145], v[174:177], v[124:127]
	v_mfma_f32_16x16x32_bf16 v[120:123], v[150:153], v[174:177], v[120:123]
	v_mfma_f32_16x16x32_bf16 v[116:119], v[142:145], v[198:201], v[116:119]
	v_mfma_f32_16x16x32_bf16 v[112:115], v[150:153], v[198:201], v[112:115]
	v_mfma_f32_16x16x32_bf16 v[100:103], v[142:145], v[206:209], v[100:103]
	v_mfma_f32_16x16x32_bf16 v[96:99], v[150:153], v[206:209], v[96:99]
	v_mfma_f32_16x16x32_bf16 v[84:87], v[142:145], v[214:217], v[84:87]
	v_mfma_f32_16x16x32_bf16 v[80:83], v[150:153], v[214:217], v[80:83]
	v_mfma_f32_16x16x32_bf16 v[124:127], v[146:149], v[178:181], v[124:127]
	v_mfma_f32_16x16x32_bf16 v[120:123], v[154:157], v[178:181], v[120:123]
	v_mfma_f32_16x16x32_bf16 v[116:119], v[146:149], v[202:205], v[116:119]
	v_mfma_f32_16x16x32_bf16 v[112:115], v[154:157], v[202:205], v[112:115]
	v_mfma_f32_16x16x32_bf16 v[100:103], v[146:149], v[210:213], v[100:103]
	v_mfma_f32_16x16x32_bf16 v[96:99], v[154:157], v[210:213], v[96:99]
	v_mfma_f32_16x16x32_bf16 v[84:87], v[146:149], v[232:235], v[84:87]
	v_mfma_f32_16x16x32_bf16 v[80:83], v[154:157], v[232:235], v[80:83]
	s_setprio 0
	s_setprio 1
	v_mfma_f32_16x16x32_bf16 v[108:111], v[158:161], v[174:177], v[108:111]
	v_mfma_f32_16x16x32_bf16 v[104:107], v[166:169], v[174:177], v[104:107]
	v_mfma_f32_16x16x32_bf16 v[92:95], v[158:161], v[198:201], v[92:95]
	v_mfma_f32_16x16x32_bf16 v[88:91], v[166:169], v[198:201], v[88:91]
	v_mfma_f32_16x16x32_bf16 v[76:79], v[158:161], v[206:209], v[76:79]
	v_mfma_f32_16x16x32_bf16 v[72:75], v[166:169], v[206:209], v[72:75]
	v_mfma_f32_16x16x32_bf16 v[68:71], v[158:161], v[214:217], v[68:71]
	v_mfma_f32_16x16x32_bf16 v[64:67], v[166:169], v[214:217], v[64:67]
	v_mfma_f32_16x16x32_bf16 v[108:111], v[162:165], v[178:181], v[108:111]
	v_mfma_f32_16x16x32_bf16 v[104:107], v[170:173], v[178:181], v[104:107]
	v_mfma_f32_16x16x32_bf16 v[92:95], v[162:165], v[202:205], v[92:95]
	v_mfma_f32_16x16x32_bf16 v[88:91], v[170:173], v[202:205], v[88:91]
	v_mfma_f32_16x16x32_bf16 v[76:79], v[162:165], v[210:213], v[76:79]
	v_mfma_f32_16x16x32_bf16 v[72:75], v[170:173], v[210:213], v[72:75]
	v_mfma_f32_16x16x32_bf16 v[68:71], v[162:165], v[232:235], v[68:71]
	v_mfma_f32_16x16x32_bf16 v[64:67], v[170:173], v[232:235], v[64:67]
	s_setprio 0
	s_barrier
; #define PG8_STAGE(bufoff, gbase, voff) do { _Pragma("unroll") for (int _i = 0; _i < 2; ++_i) \
;         __builtin_amdgcn_global_load_lds((const unsigned*)((const char*)(gbase) + (voff)[_i]), (PG8_LAS unsigned*)(lds + (bufoff) + ldsw + _i * 8192), 16, 0, 0); } while (0)
; #define PG8_LDA(dst, b, h) do { _Pragma("unroll") for (int m = 0; m < 4; ++m) _Pragma("unroll") for (int k = 0; k < 2; ++k) dst[m][k] = *(const PG8_LAS bf16x8*)(lds + PG8_SA(b, h) + aoff + m * 2048 + k * 1024); } while (0)
; #define PG8_MMA(ai, bj, At, Bt) do { __builtin_amdgcn_s_setprio(1); _Pragma("unroll") for (int m = 0; m < 4; ++m) _Pragma("unroll") for (int n = 0; n < 2; ++n) _Pragma("unroll") for (int k = 0; k < 2; ++k) \
;         acc[ai][bj][m][n] = __builtin_amdgcn_mfma_f32_16x16x32_bf16(Bt[n][k], At[m][k], acc[ai][bj][m][n], 0, 0, 0); __builtin_amdgcn_s_setprio(0); } while (0)
; #define PG8_WAIT_V(n) asm volatile("s_waitcnt vmcnt(" #n ")" ::: "memory")
; #define PG8_WAIT_L(n) asm volatile("s_waitcnt lgkmcnt(" #n ")" ::: "memory")
; #define PG8_BAR __builtin_amdgcn_s_barrier()
; #define PG8_SCHED __builtin_amdgcn_sched_barrier(0)
; template <class Epi, class Sched, bool ALIGN_EPI = false, bool SP2 = false>
; __device__ __forceinline__ void gemm_phase(PG8_LAS unsigned char* lds, const Gemm g, const Sched& S, const Epi& E) {
;     ...
;             PG8_LDA(At, 1, 1); PG8_STAGE(PG8_SB(1, 0), b3, voffB); PG8_STAGE(PG8_SB(1, 1), b3 + hstep, voffB); PG8_STAGE(PG8_SA(1, 0), a3, voffA);
;             PG8_WAIT_V(8); PG8_WAIT_L(0); PG8_BAR; PG8_MMA(1, 0, At, B0); PG8_MMA(1, 1, At, B1); PG8_BAR; PG8_SCHED;
;     ...
;         if constexpr (ALIGN_EPI) { if (wr == 0) PG8_BAR; }
	s_add_i32 s11, s11, s9
	v_lshl_add_u64 v[182:183], v[182:183], 0, s[34:35]
	s_mov_b32 m0, s11
	ds_read_b128 v[174:177], v141 offset:49152
	ds_read_b128 v[178:181], v141 offset:50176
	ds_read_b128 v[198:201], v141 offset:51200
	ds_read_b128 v[202:205], v141 offset:52224
	ds_read_b128 v[206:209], v141 offset:53248
	ds_read_b128 v[210:213], v141 offset:54272
	ds_read_b128 v[214:217], v141 offset:55296
	ds_read_b128 v[232:235], v141 offset:56320
	global_load_lds_dwordx4 v[182:183], off
	s_add_i32 m0, s11, 0x2000
	s_add_u32 s12, s58, 0x40080
	v_lshl_add_u64 v[182:183], v[236:237], 0, s[34:35]
	s_addc_u32 s13, s59, 0
	s_add_i32 s11, s14, s9
	global_load_lds_dwordx4 v[182:183], off
	s_mov_b32 m0, s11
	s_nop 0
	global_load_lds_dwordx4 v188, s[12:13]
	s_add_i32 m0, s11, 0x2000
	s_nop 0
	global_load_lds_dwordx4 v128, s[12:13]
	v_lshl_add_u64 v[182:183], v[238:239], 0, s[34:35]
	s_mov_b32 m0, s38
	s_nop 0
	global_load_lds_dwordx4 v[182:183], off
	v_lshl_add_u64 v[182:183], v[240:241], 0, s[34:35]
	s_mov_b32 m0, s39
	s_nop 0
	global_load_lds_dwordx4 v[182:183], off
	s_waitcnt vmcnt(8)
	s_waitcnt lgkmcnt(0)
	s_barrier
	s_setprio 1
	s_waitcnt lgkmcnt(0)
	v_mfma_f32_16x16x32_bf16 v[60:63], v[142:145], v[174:177], v[60:63]
	v_mfma_f32_16x16x32_bf16 v[56:59], v[150:153], v[174:177], v[56:59]
	v_mfma_f32_16x16x32_bf16 v[52:55], v[142:145], v[198:201], v[52:55]
	v_mfma_f32_16x16x32_bf16 v[48:51], v[150:153], v[198:201], v[48:51]
	v_mfma_f32_16x16x32_bf16 v[36:39], v[142:145], v[206:209], v[36:39]
	v_mfma_f32_16x16x32_bf16 v[32:35], v[150:153], v[206:209], v[32:35]
	v_mfma_f32_16x16x32_bf16 v[20:23], v[142:145], v[214:217], v[20:23]
	v_mfma_f32_16x16x32_bf16 v[16:19], v[150:153], v[214:217], v[16:19]
	v_mfma_f32_16x16x32_bf16 v[60:63], v[146:149], v[178:181], v[60:63]
	v_mfma_f32_16x16x32_bf16 v[56:59], v[154:157], v[178:181], v[56:59]
	v_mfma_f32_16x16x32_bf16 v[52:55], v[146:149], v[202:205], v[52:55]
	v_mfma_f32_16x16x32_bf16 v[48:51], v[154:157], v[202:205], v[48:51]
	v_mfma_f32_16x16x32_bf16 v[36:39], v[146:149], v[210:213], v[36:39]
	v_mfma_f32_16x16x32_bf16 v[32:35], v[154:157], v[210:213], v[32:35]
	v_mfma_f32_16x16x32_bf16 v[20:23], v[146:149], v[232:235], v[20:23]
	v_mfma_f32_16x16x32_bf16 v[16:19], v[154:157], v[232:235], v[16:19]
	s_setprio 0
	s_setprio 1
	v_mfma_f32_16x16x32_bf16 v[44:47], v[158:161], v[174:177], v[44:47]
	v_mfma_f32_16x16x32_bf16 v[40:43], v[166:169], v[174:177], v[40:43]
	v_mfma_f32_16x16x32_bf16 v[28:31], v[158:161], v[198:201], v[28:31]
	v_mfma_f32_16x16x32_bf16 v[24:27], v[166:169], v[198:201], v[24:27]
	v_mfma_f32_16x16x32_bf16 v[12:15], v[158:161], v[206:209], v[12:15]
	v_mfma_f32_16x16x32_bf16 v[8:11], v[166:169], v[206:209], v[8:11]
	v_mfma_f32_16x16x32_bf16 v[4:7], v[158:161], v[214:217], v[4:7]
	v_mfma_f32_16x16x32_bf16 v[0:3], v[166:169], v[214:217], v[0:3]
	v_mfma_f32_16x16x32_bf16 v[44:47], v[162:165], v[178:181], v[44:47]
	v_mfma_f32_16x16x32_bf16 v[40:43], v[170:173], v[178:181], v[40:43]
	v_mfma_f32_16x16x32_bf16 v[28:31], v[162:165], v[202:205], v[28:31]
	v_mfma_f32_16x16x32_bf16 v[24:27], v[170:173], v[202:205], v[24:27]
	v_mfma_f32_16x16x32_bf16 v[12:15], v[162:165], v[210:213], v[12:15]
	v_mfma_f32_16x16x32_bf16 v[8:11], v[170:173], v[210:213], v[8:11]
	v_mfma_f32_16x16x32_bf16 v[4:7], v[162:165], v[232:235], v[4:7]
	v_mfma_f32_16x16x32_bf16 v[0:3], v[170:173], v[232:235], v[0:3]
	s_setprio 0
	s_barrier
	s_add_i32 s10, s10, 2
	s_add_u32 s56, s56, 0x100
	s_addc_u32 s57, s57, 0
	s_add_u32 s30, s30, 0x100
	s_addc_u32 s31, s31, 0
	s_cmp_gt_u32 s10, 13
	s_cbranch_scc0 .LBB0_642
	s_and_b64 vcc, exec, s[42:43]
	s_cbranch_vccz .LBB0_645
	s_barrier

; #define PG8_STAGE(bufoff, gbase, voff) do { _Pragma("unroll") for (int _i = 0; _i < 2; ++_i) \
;         __builtin_amdgcn_global_load_lds((const unsigned*)((const char*)(gbase) + (voff)[_i]), (PG8_LAS unsigned*)(lds + (bufoff) + ldsw + _i * 8192), 16, 0, 0); } while (0)
; #define PG8_LDA(dst, b, h) do { _Pragma("unroll") for (int m = 0; m < 4; ++m) _Pragma("unroll") for (int k = 0; k < 2; ++k) dst[m][k] = *(const PG8_LAS bf16x8*)(lds + PG8_SA(b, h) + aoff + m * 2048 + k * 1024); } while (0)
; #define PG8_LDB(dst, b, h) do { _Pragma("unroll") for (int n = 0; n < 2; ++n) _Pragma("unroll") for (int k = 0; k < 2; ++k) dst[n][k] = *(const PG8_LAS bf16x8*)(lds + PG8_SB(b, h) + boff + n * 2048 + k * 1024); } while (0)
; #define PG8_MMA(ai, bj, At, Bt) do { __builtin_amdgcn_s_setprio(1); _Pragma("unroll") for (int m = 0; m < 4; ++m) _Pragma("unroll") for (int n = 0; n < 2; ++n) _Pragma("unroll") for (int k = 0; k < 2; ++k) \
;         acc[ai][bj][m][n] = __builtin_amdgcn_mfma_f32_16x16x32_bf16(Bt[n][k], At[m][k], acc[ai][bj][m][n], 0, 0, 0); __builtin_amdgcn_s_setprio(0); } while (0)
; #define PG8_WAIT_V(n) asm volatile("s_waitcnt vmcnt(" #n ")" ::: "memory")
; #define PG8_WAIT_L(n) asm volatile("s_waitcnt lgkmcnt(" #n ")" ::: "memory")
; #define PG8_BAR __builtin_amdgcn_s_barrier()
; #define PG8_SCHED __builtin_amdgcn_sched_barrier(0)
; template <class Epi, class Sched, bool ALIGN_EPI = false, bool SP2 = false>
; __device__ __forceinline__ void gemm_phase(PG8_LAS unsigned char* lds, const Gemm g, const Sched& S, const Epi& E) {
;     ...
;             const char* a1 = cA + (size_t)(t + 1) * kstep;
;             const char* a2 = last ? nA : cA + (size_t)(t + 2) * kstep; const char* b2 = last ? nB : cB + (size_t)(t + 2) * kstep;
;             const char* a3 = a2 + kstep; const char* b3 = b2 + kstep;
;             if (last && has_next) S.a_ready(nxt);
;             if constexpr (SP2) {
;             PG8_LDB(B0, 0, 0); PG8_LDB(B1, 0, 1); PG8_SCHED; PG8_LDA(At, 0, 0); PG8_STAGE(PG8_SA(1, 1), a1 + hstep, voffA);
;             PG8_WAIT_V(8); PG8_WAIT_L(0); PG8_BAR; PG8_MMA(0, 0, At, B0); PG8_MMA(0, 1, At, B1); PG8_BAR; PG8_SCHED;
;             PG8_LDA(At, 0, 1); PG8_STAGE(PG8_SB(0, 0), b2, voffB); PG8_STAGE(PG8_SB(0, 1), b2 + hstep, voffB); PG8_STAGE(PG8_SA(0, 0), a2, voffA);
.LBB0_767:
	s_add_u32 s11, s60, 0xfffc0080
	s_addc_u32 s12, s61, -1
	s_add_i32 s13, 0, 0x10000
	s_cmp_eq_u32 s10, 12
	s_cselect_b32 vcc_hi, s53, s12
	s_cselect_b32 vcc_lo, s55, s11
	s_cselect_b32 s63, s51, s31
	s_cselect_b32 s62, s72, s30
	s_add_i32 s11, 0, 0x14000
	v_add_u32_e32 v154, s13, v143
	v_add_u32_e32 v170, s11, v143
	ds_read_b128 v[138:141], v154
	ds_read_b128 v[146:149], v154 offset:1024
	ds_read_b128 v[150:153], v154 offset:2048
	ds_read_b128 v[154:157], v154 offset:3072
	ds_read_b128 v[158:161], v170
	ds_read_b128 v[162:165], v170 offset:1024
	ds_read_b128 v[166:169], v170 offset:2048
	ds_read_b128 v[170:173], v170 offset:3072
	s_add_i32 m0, s20, 0xc000
	ds_read_b128 v[174:177], v145
	ds_read_b128 v[178:181], v145 offset:1024
	ds_read_b128 v[198:201], v145 offset:2048
	ds_read_b128 v[202:205], v145 offset:3072
	ds_read_b128 v[206:209], v145 offset:4096
	ds_read_b128 v[210:213], v145 offset:5120
	ds_read_b128 v[214:217], v145 offset:6144
	ds_read_b128 v[232:235], v145 offset:7168
	global_load_lds_dwordx4 v134, s[60:61]
	s_add_i32 m0, s20, 0xe000
	s_nop 0
	global_load_lds_dwordx4 v136, s[60:61]
	s_waitcnt vmcnt(8)
	s_waitcnt lgkmcnt(0)
	s_barrier
	s_setprio 1
	s_waitcnt lgkmcnt(0)
	v_mfma_f32_16x16x32_bf16 v[124:127], v[138:141], v[174:177], v[124:127]
	v_mfma_f32_16x16x32_bf16 v[120:123], v[150:153], v[174:177], v[120:123]
	v_mfma_f32_16x16x32_bf16 v[108:111], v[138:141], v[198:201], v[108:111]
	v_mfma_f32_16x16x32_bf16 v[104:107], v[150:153], v[198:201], v[104:107]
	v_mfma_f32_16x16x32_bf16 v[92:95], v[138:141], v[206:209], v[92:95]
	v_mfma_f32_16x16x32_bf16 v[88:91], v[150:153], v[206:209], v[88:91]
	v_mfma_f32_16x16x32_bf16 v[76:79], v[138:141], v[214:217], v[76:79]
	v_mfma_f32_16x16x32_bf16 v[72:75], v[150:153], v[214:217], v[72:75]
	v_mfma_f32_16x16x32_bf16 v[124:127], v[146:149], v[178:181], v[124:127]
	v_mfma_f32_16x16x32_bf16 v[120:123], v[154:157], v[178:181], v[120:123]
	v_mfma_f32_16x16x32_bf16 v[108:111], v[146:149], v[202:205], v[108:111]
	v_mfma_f32_16x16x32_bf16 v[104:107], v[154:157], v[202:205], v[104:107]
	v_mfma_f32_16x16x32_bf16 v[92:95], v[146:149], v[210:213], v[92:95]
	v_mfma_f32_16x16x32_bf16 v[88:91], v[154:157], v[210:213], v[88:91]
	v_mfma_f32_16x16x32_bf16 v[76:79], v[146:149], v[232:235], v[76:79]
	v_mfma_f32_16x16x32_bf16 v[72:75], v[154:157], v[232:235], v[72:75]
	s_setprio 0
	s_setprio 1
	v_mfma_f32_16x16x32_bf16 v[116:119], v[158:161], v[174:177], v[116:119]
	v_mfma_f32_16x16x32_bf16 v[112:115], v[166:169], v[174:177], v[112:115]
	v_mfma_f32_16x16x32_bf16 v[100:103], v[158:161], v[198:201], v[100:103]
	v_mfma_f32_16x16x32_bf16 v[96:99], v[166:169], v[198:201], v[96:99]
	v_mfma_f32_16x16x32_bf16 v[84:87], v[158:161], v[206:209], v[84:87]
	v_mfma_f32_16x16x32_bf16 v[80:83], v[166:169], v[206:209], v[80:83]
	v_mfma_f32_16x16x32_bf16 v[68:71], v[158:161], v[214:217], v[68:71]
	v_mfma_f32_16x16x32_bf16 v[64:67], v[166:169], v[214:217], v[64:67]
	v_mfma_f32_16x16x32_bf16 v[116:119], v[162:165], v[178:181], v[116:119]
	v_mfma_f32_16x16x32_bf16 v[112:115], v[170:173], v[178:181], v[112:115]
	v_mfma_f32_16x16x32_bf16 v[100:103], v[162:165], v[202:205], v[100:103]
	v_mfma_f32_16x16x32_bf16 v[96:99], v[170:173], v[202:205], v[96:99]
	v_mfma_f32_16x16x32_bf16 v[84:87], v[162:165], v[210:213], v[84:87]
	v_mfma_f32_16x16x32_bf16 v[80:83], v[170:173], v[210:213], v[80:83]
	v_mfma_f32_16x16x32_bf16 v[68:71], v[162:165], v[232:235], v[68:71]
	v_mfma_f32_16x16x32_bf16 v[64:67], v[170:173], v[232:235], v[64:67]
	s_setprio 0
	s_barrier
	s_add_i32 s12, s13, s9
	v_lshl_add_u64 v[182:183], s[62:63], 0, v[188:189]
	s_mov_b32 m0, s12
	ds_read_b128 v[174:177], v145 offset:16384
	ds_read_b128 v[178:181], v145 offset:17408
	ds_read_b128 v[198:201], v145 offset:18432
	ds_read_b128 v[202:205], v145 offset:19456
	ds_read_b128 v[206:209], v145 offset:20480
	ds_read_b128 v[210:213], v145 offset:21504
	ds_read_b128 v[214:217], v145 offset:22528
	ds_read_b128 v[232:235], v145 offset:23552
	global_load_lds_dwordx4 v[182:183], off
	s_add_i32 m0, s12, 0x2000
	s_add_u32 s12, s62, 0x40000
	v_lshl_add_u64 v[236:237], s[62:63], 0, v[128:129]
	s_addc_u32 s13, s63, 0
	s_add_i32 s11, s11, s9
	global_load_lds_dwordx4 v[236:237], off
	s_mov_b32 m0, s11
	v_lshl_add_u64 v[240:241], vcc, 0, v[130:131]
	global_load_lds_dwordx4 v188, s[12:13]
	s_add_i32 m0, s11, 0x2000
	s_nop 0
	global_load_lds_dwordx4 v128, s[12:13]
	v_lshl_add_u64 v[238:239], vcc, 0, v[132:133]
	s_mov_b32 m0, s20
	s_nop 0
	global_load_lds_dwordx4 v[238:239], off
	s_mov_b32 m0, s21
	s_nop 0
	global_load_lds_dwordx4 v[240:241], off
	s_waitcnt vmcnt(8)
	s_waitcnt lgkmcnt(0)
	s_barrier
; #define PG8_STAGE(bufoff, gbase, voff) do { _Pragma("unroll") for (int _i = 0; _i < 2; ++_i) \
;         __builtin_amdgcn_global_load_lds((const unsigned*)((const char*)(gbase) + (voff)[_i]), (PG8_LAS unsigned*)(lds + (bufoff) + ldsw + _i * 8192), 16, 0, 0); } while (0)
; #define PG8_LDA(dst, b, h) do { _Pragma("unroll") for (int m = 0; m < 4; ++m) _Pragma("unroll") for (int k = 0; k < 2; ++k) dst[m][k] = *(const PG8_LAS bf16x8*)(lds + PG8_SA(b, h) + aoff + m * 2048 + k * 1024); } while (0)
; #define PG8_LDB(dst, b, h) do { _Pragma("unroll") for (int n = 0; n < 2; ++n) _Pragma("unroll") for (int k = 0; k < 2; ++k) dst[n][k] = *(const PG8_LAS bf16x8*)(lds + PG8_SB(b, h) + boff + n * 2048 + k * 1024); } while (0)
; #define PG8_MMA(ai, bj, At, Bt) do { __builtin_amdgcn_s_setprio(1); _Pragma("unroll") for (int m = 0; m < 4; ++m) _Pragma("unroll") for (int n = 0; n < 2; ++n) _Pragma("unroll") for (int k = 0; k < 2; ++k) \
;         acc[ai][bj][m][n] = __builtin_amdgcn_mfma_f32_16x16x32_bf16(Bt[n][k], At[m][k], acc[ai][bj][m][n], 0, 0, 0); __builtin_amdgcn_s_setprio(0); } while (0)
; #define PG8_WAIT_V(n) asm volatile("s_waitcnt vmcnt(" #n ")" ::: "memory")
; #define PG8_WAIT_L(n) asm volatile("s_waitcnt lgkmcnt(" #n ")" ::: "memory")
; #define PG8_BAR __builtin_amdgcn_s_barrier()
; #define PG8_SCHED __builtin_amdgcn_sched_barrier(0)
; template <class Epi, class Sched, bool ALIGN_EPI = false, bool SP2 = false>
; __device__ __forceinline__ void gemm_phase(PG8_LAS unsigned char* lds, const Gemm g, const Sched& S, const Epi& E) {
;     ...
;             PG8_WAIT_V(8); PG8_WAIT_L(0); PG8_BAR; PG8_MMA(1, 0, At, B0); PG8_MMA(1, 1, At, B1); PG8_BAR; PG8_SCHED;
;             PG8_LDB(B0, 1, 0); PG8_LDB(B1, 1, 1); PG8_SCHED; PG8_LDA(At, 1, 0); PG8_STAGE(PG8_SA(0, 1), a2 + hstep, voffA);
;             PG8_WAIT_V(8); PG8_WAIT_L(0); PG8_BAR; PG8_MMA(0, 0, At, B0); PG8_MMA(0, 1, At, B1); PG8_BAR; PG8_SCHED;
	s_setprio 1
	s_waitcnt lgkmcnt(0)
	v_mfma_f32_16x16x32_bf16 v[60:63], v[138:141], v[174:177], v[60:63]
	v_mfma_f32_16x16x32_bf16 v[56:59], v[150:153], v[174:177], v[56:59]
	v_mfma_f32_16x16x32_bf16 v[44:47], v[138:141], v[198:201], v[44:47]
	v_mfma_f32_16x16x32_bf16 v[40:43], v[150:153], v[198:201], v[40:43]
	v_mfma_f32_16x16x32_bf16 v[28:31], v[138:141], v[206:209], v[28:31]
	v_mfma_f32_16x16x32_bf16 v[24:27], v[150:153], v[206:209], v[24:27]
	v_mfma_f32_16x16x32_bf16 v[12:15], v[138:141], v[214:217], v[12:15]
	v_mfma_f32_16x16x32_bf16 v[8:11], v[150:153], v[214:217], v[8:11]
	v_mfma_f32_16x16x32_bf16 v[60:63], v[146:149], v[178:181], v[60:63]
	v_mfma_f32_16x16x32_bf16 v[56:59], v[154:157], v[178:181], v[56:59]
	v_mfma_f32_16x16x32_bf16 v[44:47], v[146:149], v[202:205], v[44:47]
	v_mfma_f32_16x16x32_bf16 v[40:43], v[154:157], v[202:205], v[40:43]
	v_mfma_f32_16x16x32_bf16 v[28:31], v[146:149], v[210:213], v[28:31]
	v_mfma_f32_16x16x32_bf16 v[24:27], v[154:157], v[210:213], v[24:27]
	v_mfma_f32_16x16x32_bf16 v[12:15], v[146:149], v[232:235], v[12:15]
	v_mfma_f32_16x16x32_bf16 v[8:11], v[154:157], v[232:235], v[8:11]
	s_setprio 0
	s_setprio 1
	v_mfma_f32_16x16x32_bf16 v[52:55], v[158:161], v[174:177], v[52:55]
	v_mfma_f32_16x16x32_bf16 v[48:51], v[166:169], v[174:177], v[48:51]
	v_mfma_f32_16x16x32_bf16 v[36:39], v[158:161], v[198:201], v[36:39]
	v_mfma_f32_16x16x32_bf16 v[32:35], v[166:169], v[198:201], v[32:35]
	v_mfma_f32_16x16x32_bf16 v[20:23], v[158:161], v[206:209], v[20:23]
	v_mfma_f32_16x16x32_bf16 v[16:19], v[166:169], v[206:209], v[16:19]
	v_mfma_f32_16x16x32_bf16 v[4:7], v[158:161], v[214:217], v[4:7]
	v_mfma_f32_16x16x32_bf16 v[0:3], v[166:169], v[214:217], v[0:3]
	v_mfma_f32_16x16x32_bf16 v[52:55], v[162:165], v[178:181], v[52:55]
	v_mfma_f32_16x16x32_bf16 v[48:51], v[170:173], v[178:181], v[48:51]
	v_mfma_f32_16x16x32_bf16 v[36:39], v[162:165], v[202:205], v[36:39]
	v_mfma_f32_16x16x32_bf16 v[32:35], v[170:173], v[202:205], v[32:35]
	v_mfma_f32_16x16x32_bf16 v[20:23], v[162:165], v[210:213], v[20:23]
	v_mfma_f32_16x16x32_bf16 v[16:19], v[170:173], v[210:213], v[16:19]
	v_mfma_f32_16x16x32_bf16 v[4:7], v[162:165], v[232:235], v[4:7]
	v_mfma_f32_16x16x32_bf16 v[0:3], v[170:173], v[232:235], v[0:3]
	s_setprio 0
	s_barrier
	s_add_i32 s11, 0, 0x18000
	s_add_i32 s14, 0, 0x1c000
	v_add_u32_e32 v154, s11, v143
	v_add_u32_e32 v170, s14, v143
	ds_read_b128 v[138:141], v154
	ds_read_b128 v[146:149], v154 offset:1024
	ds_read_b128 v[150:153], v154 offset:2048
	ds_read_b128 v[154:157], v154 offset:3072
	ds_read_b128 v[158:161], v170
	ds_read_b128 v[162:165], v170 offset:1024
	ds_read_b128 v[166:169], v170 offset:2048
	ds_read_b128 v[170:173], v170 offset:3072
	s_add_u32 s12, vcc_lo, 0x40000
	s_addc_u32 s13, vcc_hi, 0
	s_mov_b32 m0, s29
	ds_read_b128 v[174:177], v145 offset:32768
	ds_read_b128 v[178:181], v145 offset:33792
	ds_read_b128 v[198:201], v145 offset:34816
	ds_read_b128 v[202:205], v145 offset:35840
	ds_read_b128 v[206:209], v145 offset:36864
	ds_read_b128 v[210:213], v145 offset:37888
	ds_read_b128 v[214:217], v145 offset:38912
	ds_read_b128 v[232:235], v145 offset:39936
	global_load_lds_dwordx4 v132, s[12:13]
	s_mov_b32 m0, s38
	s_nop 0
	global_load_lds_dwordx4 v130, s[12:13]
	s_waitcnt vmcnt(8)
	s_waitcnt lgkmcnt(0)
	s_barrier
	s_setprio 1
	s_waitcnt lgkmcnt(0)
	v_mfma_f32_16x16x32_bf16 v[124:127], v[138:141], v[174:177], v[124:127]
	v_mfma_f32_16x16x32_bf16 v[120:123], v[150:153], v[174:177], v[120:123]
	v_mfma_f32_16x16x32_bf16 v[108:111], v[138:141], v[198:201], v[108:111]
	v_mfma_f32_16x16x32_bf16 v[104:107], v[150:153], v[198:201], v[104:107]
	v_mfma_f32_16x16x32_bf16 v[92:95], v[138:141], v[206:209], v[92:95]
	v_mfma_f32_16x16x32_bf16 v[88:91], v[150:153], v[206:209], v[88:91]
	v_mfma_f32_16x16x32_bf16 v[76:79], v[138:141], v[214:217], v[76:79]
	v_mfma_f32_16x16x32_bf16 v[72:75], v[150:153], v[214:217], v[72:75]
	v_mfma_f32_16x16x32_bf16 v[124:127], v[146:149], v[178:181], v[124:127]
	v_mfma_f32_16x16x32_bf16 v[120:123], v[154:157], v[178:181], v[120:123]
	v_mfma_f32_16x16x32_bf16 v[108:111], v[146:149], v[202:205], v[108:111]
	v_mfma_f32_16x16x32_bf16 v[104:107], v[154:157], v[202:205], v[104:107]
	v_mfma_f32_16x16x32_bf16 v[92:95], v[146:149], v[210:213], v[92:95]
	v_mfma_f32_16x16x32_bf16 v[88:91], v[154:157], v[210:213], v[88:91]
	v_mfma_f32_16x16x32_bf16 v[76:79], v[146:149], v[232:235], v[76:79]
	v_mfma_f32_16x16x32_bf16 v[72:75], v[154:157], v[232:235], v[72:75]
	s_setprio 0
	s_setprio 1
	v_mfma_f32_16x16x32_bf16 v[116:119], v[158:161], v[174:177], v[116:119]
	v_mfma_f32_16x16x32_bf16 v[112:115], v[166:169], v[174:177], v[112:115]
	v_mfma_f32_16x16x32_bf16 v[100:103], v[158:161], v[198:201], v[100:103]
	v_mfma_f32_16x16x32_bf16 v[96:99], v[166:169], v[198:201], v[96:99]
	v_mfma_f32_16x16x32_bf16 v[84:87], v[158:161], v[206:209], v[84:87]
	v_mfma_f32_16x16x32_bf16 v[80:83], v[166:169], v[206:209], v[80:83]
	v_mfma_f32_16x16x32_bf16 v[68:71], v[158:161], v[214:217], v[68:71]
	v_mfma_f32_16x16x32_bf16 v[64:67], v[166:169], v[214:217], v[64:67]
	v_mfma_f32_16x16x32_bf16 v[116:119], v[162:165], v[178:181], v[116:119]
	v_mfma_f32_16x16x32_bf16 v[112:115], v[170:173], v[178:181], v[112:115]
	v_mfma_f32_16x16x32_bf16 v[100:103], v[162:165], v[202:205], v[100:103]
	v_mfma_f32_16x16x32_bf16 v[96:99], v[170:173], v[202:205], v[96:99]
	v_mfma_f32_16x16x32_bf16 v[84:87], v[162:165], v[210:213], v[84:87]
	v_mfma_f32_16x16x32_bf16 v[80:83], v[170:173], v[210:213], v[80:83]
	v_mfma_f32_16x16x32_bf16 v[68:71], v[162:165], v[232:235], v[68:71]
	v_mfma_f32_16x16x32_bf16 v[64:67], v[170:173], v[232:235], v[64:67]
	s_setprio 0
	s_barrier
; #define PG8_STAGE(bufoff, gbase, voff) do { _Pragma("unroll") for (int _i = 0; _i < 2; ++_i) \
;         __builtin_amdgcn_global_load_lds((const unsigned*)((const char*)(gbase) + (voff)[_i]), (PG8_LAS unsigned*)(lds + (bufoff) + ldsw + _i * 8192), 16, 0, 0); } while (0)
; #define PG8_LDA(dst, b, h) do { _Pragma("unroll") for (int m = 0; m < 4; ++m) _Pragma("unroll") for (int k = 0; k < 2; ++k) dst[m][k] = *(const PG8_LAS bf16x8*)(lds + PG8_SA(b, h) + aoff + m * 2048 + k * 1024); } while (0)
; #define PG8_MMA(ai, bj, At, Bt) do { __builtin_amdgcn_s_setprio(1); _Pragma("unroll") for (int m = 0; m < 4; ++m) _Pragma("unroll") for (int n = 0; n < 2; ++n) _Pragma("unroll") for (int k = 0; k < 2; ++k) \
;         acc[ai][bj][m][n] = __builtin_amdgcn_mfma_f32_16x16x32_bf16(Bt[n][k], At[m][k], acc[ai][bj][m][n], 0, 0, 0); __builtin_amdgcn_s_setprio(0); } while (0)
; #define PG8_WAIT_V(n) asm volatile("s_waitcnt vmcnt(" #n ")" ::: "memory")
; #define PG8_WAIT_L(n) asm volatile("s_waitcnt lgkmcnt(" #n ")" ::: "memory")
; #define PG8_BAR __builtin_amdgcn_s_barrier()
; #define PG8_SCHED __builtin_amdgcn_sched_barrier(0)
; template <class Epi, class Sched, bool ALIGN_EPI = false, bool SP2 = false>
; __device__ __forceinline__ void gemm_phase(PG8_LAS unsigned char* lds, const Gemm g, const Sched& S, const Epi& E) {
;     ...
;             PG8_LDA(At, 1, 1); PG8_STAGE(PG8_SB(1, 0), b3, voffB); PG8_STAGE(PG8_SB(1, 1), b3 + hstep, voffB); PG8_STAGE(PG8_SA(1, 0), a3, voffA);
;             PG8_WAIT_V(8); PG8_WAIT_L(0); PG8_BAR; PG8_MMA(1, 0, At, B0); PG8_MMA(1, 1, At, B1); PG8_BAR; PG8_SCHED;
;     ...
;         if constexpr (ALIGN_EPI) { if (wr == 0) PG8_BAR; }
	s_add_i32 s11, s11, s9
	v_lshl_add_u64 v[182:183], v[182:183], 0, s[34:35]
	s_mov_b32 m0, s11
	ds_read_b128 v[174:177], v145 offset:49152
	ds_read_b128 v[178:181], v145 offset:50176
	ds_read_b128 v[198:201], v145 offset:51200
	ds_read_b128 v[202:205], v145 offset:52224
	ds_read_b128 v[206:209], v145 offset:53248
	ds_read_b128 v[210:213], v145 offset:54272
	ds_read_b128 v[214:217], v145 offset:55296
	ds_read_b128 v[232:235], v145 offset:56320
	global_load_lds_dwordx4 v[182:183], off
	s_add_i32 m0, s11, 0x2000
	s_add_u32 s12, s62, 0x40080
	v_lshl_add_u64 v[182:183], v[236:237], 0, s[34:35]
	s_addc_u32 s13, s63, 0
	s_add_i32 s11, s14, s9
	global_load_lds_dwordx4 v[182:183], off
	s_mov_b32 m0, s11
	s_nop 0
	global_load_lds_dwordx4 v188, s[12:13]
	s_add_i32 m0, s11, 0x2000
	s_nop 0
	global_load_lds_dwordx4 v128, s[12:13]
	v_lshl_add_u64 v[182:183], v[238:239], 0, s[34:35]
	s_mov_b32 m0, s39
	s_nop 0
	global_load_lds_dwordx4 v[182:183], off
	v_lshl_add_u64 v[182:183], v[240:241], 0, s[34:35]
	s_mov_b32 m0, s44
	s_nop 0
	global_load_lds_dwordx4 v[182:183], off
	s_waitcnt vmcnt(8)
	s_waitcnt lgkmcnt(0)
	s_barrier
	s_setprio 1
	s_waitcnt lgkmcnt(0)
	v_mfma_f32_16x16x32_bf16 v[60:63], v[138:141], v[174:177], v[60:63]
	v_mfma_f32_16x16x32_bf16 v[56:59], v[150:153], v[174:177], v[56:59]
	v_mfma_f32_16x16x32_bf16 v[44:47], v[138:141], v[198:201], v[44:47]
	v_mfma_f32_16x16x32_bf16 v[40:43], v[150:153], v[198:201], v[40:43]
	v_mfma_f32_16x16x32_bf16 v[28:31], v[138:141], v[206:209], v[28:31]
	v_mfma_f32_16x16x32_bf16 v[24:27], v[150:153], v[206:209], v[24:27]
	v_mfma_f32_16x16x32_bf16 v[12:15], v[138:141], v[214:217], v[12:15]
	v_mfma_f32_16x16x32_bf16 v[8:11], v[150:153], v[214:217], v[8:11]
	v_mfma_f32_16x16x32_bf16 v[60:63], v[146:149], v[178:181], v[60:63]
	v_mfma_f32_16x16x32_bf16 v[56:59], v[154:157], v[178:181], v[56:59]
	v_mfma_f32_16x16x32_bf16 v[44:47], v[146:149], v[202:205], v[44:47]
	v_mfma_f32_16x16x32_bf16 v[40:43], v[154:157], v[202:205], v[40:43]
	v_mfma_f32_16x16x32_bf16 v[28:31], v[146:149], v[210:213], v[28:31]
	v_mfma_f32_16x16x32_bf16 v[24:27], v[154:157], v[210:213], v[24:27]
	v_mfma_f32_16x16x32_bf16 v[12:15], v[146:149], v[232:235], v[12:15]
	v_mfma_f32_16x16x32_bf16 v[8:11], v[154:157], v[232:235], v[8:11]
	s_setprio 0
	s_setprio 1
	v_mfma_f32_16x16x32_bf16 v[52:55], v[158:161], v[174:177], v[52:55]
	v_mfma_f32_16x16x32_bf16 v[48:51], v[166:169], v[174:177], v[48:51]
	v_mfma_f32_16x16x32_bf16 v[36:39], v[158:161], v[198:201], v[36:39]
	v_mfma_f32_16x16x32_bf16 v[32:35], v[166:169], v[198:201], v[32:35]
	v_mfma_f32_16x16x32_bf16 v[20:23], v[158:161], v[206:209], v[20:23]
	v_mfma_f32_16x16x32_bf16 v[16:19], v[166:169], v[206:209], v[16:19]
	v_mfma_f32_16x16x32_bf16 v[4:7], v[158:161], v[214:217], v[4:7]
	v_mfma_f32_16x16x32_bf16 v[0:3], v[166:169], v[214:217], v[0:3]
	v_mfma_f32_16x16x32_bf16 v[52:55], v[162:165], v[178:181], v[52:55]
	v_mfma_f32_16x16x32_bf16 v[48:51], v[170:173], v[178:181], v[48:51]
	v_mfma_f32_16x16x32_bf16 v[36:39], v[162:165], v[202:205], v[36:39]
	v_mfma_f32_16x16x32_bf16 v[32:35], v[170:173], v[202:205], v[32:35]
	v_mfma_f32_16x16x32_bf16 v[20:23], v[162:165], v[210:213], v[20:23]
	v_mfma_f32_16x16x32_bf16 v[16:19], v[170:173], v[210:213], v[16:19]
	v_mfma_f32_16x16x32_bf16 v[4:7], v[162:165], v[232:235], v[4:7]
	v_mfma_f32_16x16x32_bf16 v[0:3], v[170:173], v[232:235], v[0:3]
	s_setprio 0
	s_barrier
	s_add_i32 s10, s10, 2
	s_add_u32 s60, s60, 0x100
	s_addc_u32 s61, s61, 0
	s_add_u32 s30, s30, 0x100
	s_addc_u32 s31, s31, 0
	s_cmp_gt_u32 s10, 13
	s_cbranch_scc0 .LBB0_767
	s_and_b64 vcc, exec, s[48:49]
	s_cbranch_vccz .LBB0_770
	s_barrier

; #define PG8_STAGE(bufoff, gbase, voff) do { _Pragma("unroll") for (int _i = 0; _i < 2; ++_i) \
;         __builtin_amdgcn_global_load_lds((const unsigned*)((const char*)(gbase) + (voff)[_i]), (PG8_LAS unsigned*)(lds + (bufoff) + ldsw + _i * 8192), 16, 0, 0); } while (0)
; #define PG8_LDA(dst, b, h) do { _Pragma("unroll") for (int m = 0; m < 4; ++m) _Pragma("unroll") for (int k = 0; k < 2; ++k) dst[m][k] = *(const PG8_LAS bf16x8*)(lds + PG8_SA(b, h) + aoff + m * 2048 + k * 1024); } while (0)
; #define PG8_LDB(dst, b, h) do { _Pragma("unroll") for (int n = 0; n < 2; ++n) _Pragma("unroll") for (int k = 0; k < 2; ++k) dst[n][k] = *(const PG8_LAS bf16x8*)(lds + PG8_SB(b, h) + boff + n * 2048 + k * 1024); } while (0)
; #define PG8_MMA(ai, bj, At, Bt) do { __builtin_amdgcn_s_setprio(1); _Pragma("unroll") for (int m = 0; m < 4; ++m) _Pragma("unroll") for (int n = 0; n < 2; ++n) _Pragma("unroll") for (int k = 0; k < 2; ++k) \
;         acc[ai][bj][m][n] = __builtin_amdgcn_mfma_f32_16x16x32_bf16(Bt[n][k], At[m][k], acc[ai][bj][m][n], 0, 0, 0); __builtin_amdgcn_s_setprio(0); } while (0)
; #define PG8_WAIT_V(n) asm volatile("s_waitcnt vmcnt(" #n ")" ::: "memory")
; #define PG8_WAIT_L(n) asm volatile("s_waitcnt lgkmcnt(" #n ")" ::: "memory")
; #define PG8_BAR __builtin_amdgcn_s_barrier()
; #define PG8_SCHED __builtin_amdgcn_sched_barrier(0)
; template <class Epi, class Sched, bool ALIGN_EPI = false, bool SP2 = false>
; __device__ __forceinline__ void gemm_phase(PG8_LAS unsigned char* lds, const Gemm g, const Sched& S, const Epi& E) {
;     ...
;             const char* a1 = cA + (size_t)(t + 1) * kstep;
;             const char* a2 = last ? nA : cA + (size_t)(t + 2) * kstep; const char* b2 = last ? nB : cB + (size_t)(t + 2) * kstep;
;             const char* a3 = a2 + kstep; const char* b3 = b2 + kstep;
;             if (last && has_next) S.a_ready(nxt);
;             if constexpr (SP2) {
;             PG8_LDB(B0, 0, 0); PG8_LDB(B1, 0, 1); PG8_SCHED; PG8_LDA(At, 0, 0); PG8_STAGE(PG8_SA(1, 1), a1 + hstep, voffA);
;             PG8_WAIT_V(8); PG8_WAIT_L(0); PG8_BAR; PG8_MMA(0, 0, At, B0); PG8_MMA(0, 1, At, B1); PG8_BAR; PG8_SCHED;
;             PG8_LDA(At, 0, 1); PG8_STAGE(PG8_SB(0, 0), b2, voffB); PG8_STAGE(PG8_SB(0, 1), b2 + hstep, voffB); PG8_STAGE(PG8_SA(0, 0), a2, voffA);
.LBB0_839:
	s_add_u32 s58, s56, 0x100
	s_addc_u32 s59, s57, 0
	s_add_i32 s11, 0, 0x10000
	s_cmp_eq_u32 s10, 40
	s_cselect_b32 s63, s43, s59
	s_cselect_b32 s62, s42, s58
	s_cselect_b32 s61, s55, s31
	s_cselect_b32 s60, s54, s30
	s_add_i32 s14, 0, 0x14000
	v_add_u32_e32 v154, s11, v139
	v_add_u32_e32 v170, s14, v139
	ds_read_b128 v[142:145], v154
	ds_read_b128 v[146:149], v154 offset:1024
	ds_read_b128 v[150:153], v154 offset:2048
	ds_read_b128 v[154:157], v154 offset:3072
	ds_read_b128 v[158:161], v170
	ds_read_b128 v[162:165], v170 offset:1024
	ds_read_b128 v[166:169], v170 offset:2048
	ds_read_b128 v[170:173], v170 offset:3072
	s_add_i32 m0, s8, 0xc000
	ds_read_b128 v[174:177], v141
	ds_read_b128 v[178:181], v141 offset:1024
	ds_read_b128 v[198:201], v141 offset:2048
	ds_read_b128 v[202:205], v141 offset:3072
	ds_read_b128 v[206:209], v141 offset:4096
	ds_read_b128 v[210:213], v141 offset:5120
	ds_read_b128 v[214:217], v141 offset:6144
	ds_read_b128 v[232:235], v141 offset:7168
	global_load_lds_dwordx4 v134, s[56:57]
	s_add_i32 m0, s8, 0xe000
	s_nop 0
	global_load_lds_dwordx4 v136, s[56:57]
	s_waitcnt vmcnt(8)
	s_waitcnt lgkmcnt(0)
	s_barrier
	s_setprio 1
	s_waitcnt lgkmcnt(0)
	v_mfma_f32_16x16x32_bf16 v[124:127], v[142:145], v[174:177], v[124:127]
	v_mfma_f32_16x16x32_bf16 v[120:123], v[150:153], v[174:177], v[120:123]
	v_mfma_f32_16x16x32_bf16 v[116:119], v[142:145], v[198:201], v[116:119]
	v_mfma_f32_16x16x32_bf16 v[112:115], v[150:153], v[198:201], v[112:115]
	v_mfma_f32_16x16x32_bf16 v[100:103], v[142:145], v[206:209], v[100:103]
	v_mfma_f32_16x16x32_bf16 v[96:99], v[150:153], v[206:209], v[96:99]
	v_mfma_f32_16x16x32_bf16 v[84:87], v[142:145], v[214:217], v[84:87]
	v_mfma_f32_16x16x32_bf16 v[80:83], v[150:153], v[214:217], v[80:83]
	v_mfma_f32_16x16x32_bf16 v[124:127], v[146:149], v[178:181], v[124:127]
	v_mfma_f32_16x16x32_bf16 v[120:123], v[154:157], v[178:181], v[120:123]
	v_mfma_f32_16x16x32_bf16 v[116:119], v[146:149], v[202:205], v[116:119]
	v_mfma_f32_16x16x32_bf16 v[112:115], v[154:157], v[202:205], v[112:115]
	v_mfma_f32_16x16x32_bf16 v[100:103], v[146:149], v[210:213], v[100:103]
	v_mfma_f32_16x16x32_bf16 v[96:99], v[154:157], v[210:213], v[96:99]
	v_mfma_f32_16x16x32_bf16 v[84:87], v[146:149], v[232:235], v[84:87]
	v_mfma_f32_16x16x32_bf16 v[80:83], v[154:157], v[232:235], v[80:83]
	s_setprio 0
	s_setprio 1
	v_mfma_f32_16x16x32_bf16 v[108:111], v[158:161], v[174:177], v[108:111]
	v_mfma_f32_16x16x32_bf16 v[104:107], v[166:169], v[174:177], v[104:107]
	v_mfma_f32_16x16x32_bf16 v[92:95], v[158:161], v[198:201], v[92:95]
	v_mfma_f32_16x16x32_bf16 v[88:91], v[166:169], v[198:201], v[88:91]
	v_mfma_f32_16x16x32_bf16 v[76:79], v[158:161], v[206:209], v[76:79]
	v_mfma_f32_16x16x32_bf16 v[72:75], v[166:169], v[206:209], v[72:75]
	v_mfma_f32_16x16x32_bf16 v[68:71], v[158:161], v[214:217], v[68:71]
	v_mfma_f32_16x16x32_bf16 v[64:67], v[166:169], v[214:217], v[64:67]
	v_mfma_f32_16x16x32_bf16 v[108:111], v[162:165], v[178:181], v[108:111]
	v_mfma_f32_16x16x32_bf16 v[104:107], v[170:173], v[178:181], v[104:107]
	v_mfma_f32_16x16x32_bf16 v[92:95], v[162:165], v[202:205], v[92:95]
	v_mfma_f32_16x16x32_bf16 v[88:91], v[170:173], v[202:205], v[88:91]
	v_mfma_f32_16x16x32_bf16 v[76:79], v[162:165], v[210:213], v[76:79]
	v_mfma_f32_16x16x32_bf16 v[72:75], v[170:173], v[210:213], v[72:75]
	v_mfma_f32_16x16x32_bf16 v[68:71], v[162:165], v[232:235], v[68:71]
	v_mfma_f32_16x16x32_bf16 v[64:67], v[170:173], v[232:235], v[64:67]
	s_setprio 0
	s_barrier
	s_add_i32 s11, s11, s3
	v_lshl_add_u64 v[182:183], s[60:61], 0, v[188:189]
	s_mov_b32 m0, s11
	ds_read_b128 v[174:177], v141 offset:16384
	ds_read_b128 v[178:181], v141 offset:17408
	ds_read_b128 v[198:201], v141 offset:18432
	ds_read_b128 v[202:205], v141 offset:19456
	ds_read_b128 v[206:209], v141 offset:20480
	ds_read_b128 v[210:213], v141 offset:21504
	ds_read_b128 v[214:217], v141 offset:22528
	ds_read_b128 v[232:235], v141 offset:23552
	global_load_lds_dwordx4 v[182:183], off
	s_add_i32 m0, s11, 0x2000
	s_add_u32 s12, s60, 0xb0000
	v_lshl_add_u64 v[236:237], s[60:61], 0, v[128:129]
	s_addc_u32 s13, s61, 0
	s_add_i32 s11, s14, s3
	global_load_lds_dwordx4 v[236:237], off
	s_mov_b32 m0, s11
	v_lshl_add_u64 v[240:241], s[62:63], 0, v[130:131]
	global_load_lds_dwordx4 v188, s[12:13]
	s_add_i32 m0, s11, 0x2000
	s_nop 0
	global_load_lds_dwordx4 v128, s[12:13]
	v_lshl_add_u64 v[238:239], s[62:63], 0, v[132:133]
	s_mov_b32 m0, s8
	s_nop 0
	global_load_lds_dwordx4 v[238:239], off
	s_mov_b32 m0, s9
	s_nop 0
	global_load_lds_dwordx4 v[240:241], off
	s_waitcnt vmcnt(8)
	s_waitcnt lgkmcnt(0)
	s_barrier
; #define PG8_STAGE(bufoff, gbase, voff) do { _Pragma("unroll") for (int _i = 0; _i < 2; ++_i) \
;         __builtin_amdgcn_global_load_lds((const unsigned*)((const char*)(gbase) + (voff)[_i]), (PG8_LAS unsigned*)(lds + (bufoff) + ldsw + _i * 8192), 16, 0, 0); } while (0)
; #define PG8_LDA(dst, b, h) do { _Pragma("unroll") for (int m = 0; m < 4; ++m) _Pragma("unroll") for (int k = 0; k < 2; ++k) dst[m][k] = *(const PG8_LAS bf16x8*)(lds + PG8_SA(b, h) + aoff + m * 2048 + k * 1024); } while (0)
; #define PG8_LDB(dst, b, h) do { _Pragma("unroll") for (int n = 0; n < 2; ++n) _Pragma("unroll") for (int k = 0; k < 2; ++k) dst[n][k] = *(const PG8_LAS bf16x8*)(lds + PG8_SB(b, h) + boff + n * 2048 + k * 1024); } while (0)
; #define PG8_MMA(ai, bj, At, Bt) do { __builtin_amdgcn_s_setprio(1); _Pragma("unroll") for (int m = 0; m < 4; ++m) _Pragma("unroll") for (int n = 0; n < 2; ++n) _Pragma("unroll") for (int k = 0; k < 2; ++k) \
;         acc[ai][bj][m][n] = __builtin_amdgcn_mfma_f32_16x16x32_bf16(Bt[n][k], At[m][k], acc[ai][bj][m][n], 0, 0, 0); __builtin_amdgcn_s_setprio(0); } while (0)
; #define PG8_WAIT_V(n) asm volatile("s_waitcnt vmcnt(" #n ")" ::: "memory")
; #define PG8_WAIT_L(n) asm volatile("s_waitcnt lgkmcnt(" #n ")" ::: "memory")
; #define PG8_BAR __builtin_amdgcn_s_barrier()
; #define PG8_SCHED __builtin_amdgcn_sched_barrier(0)
; template <class Epi, class Sched, bool ALIGN_EPI = false, bool SP2 = false>
; __device__ __forceinline__ void gemm_phase(PG8_LAS unsigned char* lds, const Gemm g, const Sched& S, const Epi& E) {
;     ...
;             PG8_WAIT_V(8); PG8_WAIT_L(0); PG8_BAR; PG8_MMA(1, 0, At, B0); PG8_MMA(1, 1, At, B1); PG8_BAR; PG8_SCHED;
;             PG8_LDB(B0, 1, 0); PG8_LDB(B1, 1, 1); PG8_SCHED; PG8_LDA(At, 1, 0); PG8_STAGE(PG8_SA(0, 1), a2 + hstep, voffA);
;             PG8_WAIT_V(8); PG8_WAIT_L(0); PG8_BAR; PG8_MMA(0, 0, At, B0); PG8_MMA(0, 1, At, B1); PG8_BAR; PG8_SCHED;
	s_setprio 1
	s_waitcnt lgkmcnt(0)
	v_mfma_f32_16x16x32_bf16 v[60:63], v[142:145], v[174:177], v[60:63]
	v_mfma_f32_16x16x32_bf16 v[56:59], v[150:153], v[174:177], v[56:59]
	v_mfma_f32_16x16x32_bf16 v[52:55], v[142:145], v[198:201], v[52:55]
	v_mfma_f32_16x16x32_bf16 v[48:51], v[150:153], v[198:201], v[48:51]
	v_mfma_f32_16x16x32_bf16 v[36:39], v[142:145], v[206:209], v[36:39]
	v_mfma_f32_16x16x32_bf16 v[32:35], v[150:153], v[206:209], v[32:35]
	v_mfma_f32_16x16x32_bf16 v[20:23], v[142:145], v[214:217], v[20:23]
	v_mfma_f32_16x16x32_bf16 v[16:19], v[150:153], v[214:217], v[16:19]
	v_mfma_f32_16x16x32_bf16 v[60:63], v[146:149], v[178:181], v[60:63]
	v_mfma_f32_16x16x32_bf16 v[56:59], v[154:157], v[178:181], v[56:59]
	v_mfma_f32_16x16x32_bf16 v[52:55], v[146:149], v[202:205], v[52:55]
	v_mfma_f32_16x16x32_bf16 v[48:51], v[154:157], v[202:205], v[48:51]
	v_mfma_f32_16x16x32_bf16 v[36:39], v[146:149], v[210:213], v[36:39]
	v_mfma_f32_16x16x32_bf16 v[32:35], v[154:157], v[210:213], v[32:35]
	v_mfma_f32_16x16x32_bf16 v[20:23], v[146:149], v[232:235], v[20:23]
	v_mfma_f32_16x16x32_bf16 v[16:19], v[154:157], v[232:235], v[16:19]
	s_setprio 0
	s_setprio 1
	v_mfma_f32_16x16x32_bf16 v[44:47], v[158:161], v[174:177], v[44:47]
	v_mfma_f32_16x16x32_bf16 v[40:43], v[166:169], v[174:177], v[40:43]
	v_mfma_f32_16x16x32_bf16 v[28:31], v[158:161], v[198:201], v[28:31]
	v_mfma_f32_16x16x32_bf16 v[24:27], v[166:169], v[198:201], v[24:27]
	v_mfma_f32_16x16x32_bf16 v[12:15], v[158:161], v[206:209], v[12:15]
	v_mfma_f32_16x16x32_bf16 v[8:11], v[166:169], v[206:209], v[8:11]
	v_mfma_f32_16x16x32_bf16 v[4:7], v[158:161], v[214:217], v[4:7]
	v_mfma_f32_16x16x32_bf16 v[0:3], v[166:169], v[214:217], v[0:3]
	v_mfma_f32_16x16x32_bf16 v[44:47], v[162:165], v[178:181], v[44:47]
	v_mfma_f32_16x16x32_bf16 v[40:43], v[170:173], v[178:181], v[40:43]
	v_mfma_f32_16x16x32_bf16 v[28:31], v[162:165], v[202:205], v[28:31]
	v_mfma_f32_16x16x32_bf16 v[24:27], v[170:173], v[202:205], v[24:27]
	v_mfma_f32_16x16x32_bf16 v[12:15], v[162:165], v[210:213], v[12:15]
	v_mfma_f32_16x16x32_bf16 v[8:11], v[170:173], v[210:213], v[8:11]
	v_mfma_f32_16x16x32_bf16 v[4:7], v[162:165], v[232:235], v[4:7]
	v_mfma_f32_16x16x32_bf16 v[0:3], v[170:173], v[232:235], v[0:3]
	s_setprio 0
	s_barrier
	s_add_i32 s11, 0, 0x18000
	s_add_i32 s14, 0, 0x1c000
	v_add_u32_e32 v154, s11, v139
	v_add_u32_e32 v170, s14, v139
	ds_read_b128 v[142:145], v154
	ds_read_b128 v[146:149], v154 offset:1024
	ds_read_b128 v[150:153], v154 offset:2048
	ds_read_b128 v[154:157], v154 offset:3072
	ds_read_b128 v[158:161], v170
	ds_read_b128 v[162:165], v170 offset:1024
	ds_read_b128 v[166:169], v170 offset:2048
	ds_read_b128 v[170:173], v170 offset:3072
	s_add_u32 s12, s62, 0xb0000
	s_addc_u32 s13, s63, 0
	s_mov_b32 m0, s20
	ds_read_b128 v[174:177], v141 offset:32768
	ds_read_b128 v[178:181], v141 offset:33792
	ds_read_b128 v[198:201], v141 offset:34816
	ds_read_b128 v[202:205], v141 offset:35840
	ds_read_b128 v[206:209], v141 offset:36864
	ds_read_b128 v[210:213], v141 offset:37888
	ds_read_b128 v[214:217], v141 offset:38912
	ds_read_b128 v[232:235], v141 offset:39936
	global_load_lds_dwordx4 v132, s[12:13]
	s_mov_b32 m0, s21
	s_nop 0
	global_load_lds_dwordx4 v130, s[12:13]
	s_waitcnt vmcnt(8)
	s_waitcnt lgkmcnt(0)
	s_barrier
	s_setprio 1
	s_waitcnt lgkmcnt(0)
	v_mfma_f32_16x16x32_bf16 v[124:127], v[142:145], v[174:177], v[124:127]
	v_mfma_f32_16x16x32_bf16 v[120:123], v[150:153], v[174:177], v[120:123]
	v_mfma_f32_16x16x32_bf16 v[116:119], v[142:145], v[198:201], v[116:119]
	v_mfma_f32_16x16x32_bf16 v[112:115], v[150:153], v[198:201], v[112:115]
	v_mfma_f32_16x16x32_bf16 v[100:103], v[142:145], v[206:209], v[100:103]
	v_mfma_f32_16x16x32_bf16 v[96:99], v[150:153], v[206:209], v[96:99]
	v_mfma_f32_16x16x32_bf16 v[84:87], v[142:145], v[214:217], v[84:87]
	v_mfma_f32_16x16x32_bf16 v[80:83], v[150:153], v[214:217], v[80:83]
	v_mfma_f32_16x16x32_bf16 v[124:127], v[146:149], v[178:181], v[124:127]
	v_mfma_f32_16x16x32_bf16 v[120:123], v[154:157], v[178:181], v[120:123]
	v_mfma_f32_16x16x32_bf16 v[116:119], v[146:149], v[202:205], v[116:119]
	v_mfma_f32_16x16x32_bf16 v[112:115], v[154:157], v[202:205], v[112:115]
	v_mfma_f32_16x16x32_bf16 v[100:103], v[146:149], v[210:213], v[100:103]
	v_mfma_f32_16x16x32_bf16 v[96:99], v[154:157], v[210:213], v[96:99]
	v_mfma_f32_16x16x32_bf16 v[84:87], v[146:149], v[232:235], v[84:87]
	v_mfma_f32_16x16x32_bf16 v[80:83], v[154:157], v[232:235], v[80:83]
	s_setprio 0
	s_setprio 1
	v_mfma_f32_16x16x32_bf16 v[108:111], v[158:161], v[174:177], v[108:111]
	v_mfma_f32_16x16x32_bf16 v[104:107], v[166:169], v[174:177], v[104:107]
	v_mfma_f32_16x16x32_bf16 v[92:95], v[158:161], v[198:201], v[92:95]
	v_mfma_f32_16x16x32_bf16 v[88:91], v[166:169], v[198:201], v[88:91]
	v_mfma_f32_16x16x32_bf16 v[76:79], v[158:161], v[206:209], v[76:79]
	v_mfma_f32_16x16x32_bf16 v[72:75], v[166:169], v[206:209], v[72:75]
	v_mfma_f32_16x16x32_bf16 v[68:71], v[158:161], v[214:217], v[68:71]
	v_mfma_f32_16x16x32_bf16 v[64:67], v[166:169], v[214:217], v[64:67]
	v_mfma_f32_16x16x32_bf16 v[108:111], v[162:165], v[178:181], v[108:111]
	v_mfma_f32_16x16x32_bf16 v[104:107], v[170:173], v[178:181], v[104:107]
	v_mfma_f32_16x16x32_bf16 v[92:95], v[162:165], v[202:205], v[92:95]
	v_mfma_f32_16x16x32_bf16 v[88:91], v[170:173], v[202:205], v[88:91]
	v_mfma_f32_16x16x32_bf16 v[76:79], v[162:165], v[210:213], v[76:79]
	v_mfma_f32_16x16x32_bf16 v[72:75], v[170:173], v[210:213], v[72:75]
	v_mfma_f32_16x16x32_bf16 v[68:71], v[162:165], v[232:235], v[68:71]
	v_mfma_f32_16x16x32_bf16 v[64:67], v[170:173], v[232:235], v[64:67]
	s_setprio 0
	s_barrier
; #define PG8_STAGE(bufoff, gbase, voff) do { _Pragma("unroll") for (int _i = 0; _i < 2; ++_i) \
;         __builtin_amdgcn_global_load_lds((const unsigned*)((const char*)(gbase) + (voff)[_i]), (PG8_LAS unsigned*)(lds + (bufoff) + ldsw + _i * 8192), 16, 0, 0); } while (0)
; #define PG8_LDA(dst, b, h) do { _Pragma("unroll") for (int m = 0; m < 4; ++m) _Pragma("unroll") for (int k = 0; k < 2; ++k) dst[m][k] = *(const PG8_LAS bf16x8*)(lds + PG8_SA(b, h) + aoff + m * 2048 + k * 1024); } while (0)
; #define PG8_MMA(ai, bj, At, Bt) do { __builtin_amdgcn_s_setprio(1); _Pragma("unroll") for (int m = 0; m < 4; ++m) _Pragma("unroll") for (int n = 0; n < 2; ++n) _Pragma("unroll") for (int k = 0; k < 2; ++k) \
;         acc[ai][bj][m][n] = __builtin_amdgcn_mfma_f32_16x16x32_bf16(Bt[n][k], At[m][k], acc[ai][bj][m][n], 0, 0, 0); __builtin_amdgcn_s_setprio(0); } while (0)
; #define PG8_WAIT_V(n) asm volatile("s_waitcnt vmcnt(" #n ")" ::: "memory")
; #define PG8_WAIT_L(n) asm volatile("s_waitcnt lgkmcnt(" #n ")" ::: "memory")
; #define PG8_BAR __builtin_amdgcn_s_barrier()
; #define PG8_SCHED __builtin_amdgcn_sched_barrier(0)
; template <class Epi, class Sched, bool ALIGN_EPI = false, bool SP2 = false>
; __device__ __forceinline__ void gemm_phase(PG8_LAS unsigned char* lds, const Gemm g, const Sched& S, const Epi& E) {
;     ...
;             PG8_LDA(At, 1, 1); PG8_STAGE(PG8_SB(1, 0), b3, voffB); PG8_STAGE(PG8_SB(1, 1), b3 + hstep, voffB); PG8_STAGE(PG8_SA(1, 0), a3, voffA);
;             PG8_WAIT_V(8); PG8_WAIT_L(0); PG8_BAR; PG8_MMA(1, 0, At, B0); PG8_MMA(1, 1, At, B1); PG8_BAR; PG8_SCHED;
;     ...
;         if constexpr (ALIGN_EPI) { if (wr == 0) PG8_BAR; }
	s_add_i32 s11, s11, s3
	v_lshl_add_u64 v[182:183], v[182:183], 0, s[34:35]
	s_mov_b32 m0, s11
	ds_read_b128 v[174:177], v141 offset:49152
	ds_read_b128 v[178:181], v141 offset:50176
	ds_read_b128 v[198:201], v141 offset:51200
	ds_read_b128 v[202:205], v141 offset:52224
	ds_read_b128 v[206:209], v141 offset:53248
	ds_read_b128 v[210:213], v141 offset:54272
	ds_read_b128 v[214:217], v141 offset:55296
	ds_read_b128 v[232:235], v141 offset:56320
	global_load_lds_dwordx4 v[182:183], off
	s_add_i32 m0, s11, 0x2000
	s_add_u32 s12, s60, 0xb0080
	v_lshl_add_u64 v[182:183], v[236:237], 0, s[34:35]
	s_addc_u32 s13, s61, 0
	s_add_i32 s11, s14, s3
	global_load_lds_dwordx4 v[182:183], off
	s_mov_b32 m0, s11
	s_nop 0
	global_load_lds_dwordx4 v188, s[12:13]
	s_add_i32 m0, s11, 0x2000
	s_nop 0
	global_load_lds_dwordx4 v128, s[12:13]
	v_lshl_add_u64 v[182:183], v[238:239], 0, s[34:35]
	s_mov_b32 m0, s29
	s_nop 0
	global_load_lds_dwordx4 v[182:183], off
	v_lshl_add_u64 v[182:183], v[240:241], 0, s[34:35]
	s_mov_b32 m0, s40
	s_nop 0
	global_load_lds_dwordx4 v[182:183], off
	s_waitcnt vmcnt(8)
	s_waitcnt lgkmcnt(0)
	s_barrier
	s_setprio 1
	s_waitcnt lgkmcnt(0)
	v_mfma_f32_16x16x32_bf16 v[60:63], v[142:145], v[174:177], v[60:63]
	v_mfma_f32_16x16x32_bf16 v[56:59], v[150:153], v[174:177], v[56:59]
	v_mfma_f32_16x16x32_bf16 v[52:55], v[142:145], v[198:201], v[52:55]
	v_mfma_f32_16x16x32_bf16 v[48:51], v[150:153], v[198:201], v[48:51]
	v_mfma_f32_16x16x32_bf16 v[36:39], v[142:145], v[206:209], v[36:39]
	v_mfma_f32_16x16x32_bf16 v[32:35], v[150:153], v[206:209], v[32:35]
	v_mfma_f32_16x16x32_bf16 v[20:23], v[142:145], v[214:217], v[20:23]
	v_mfma_f32_16x16x32_bf16 v[16:19], v[150:153], v[214:217], v[16:19]
	v_mfma_f32_16x16x32_bf16 v[60:63], v[146:149], v[178:181], v[60:63]
	v_mfma_f32_16x16x32_bf16 v[56:59], v[154:157], v[178:181], v[56:59]
	v_mfma_f32_16x16x32_bf16 v[52:55], v[146:149], v[202:205], v[52:55]
	v_mfma_f32_16x16x32_bf16 v[48:51], v[154:157], v[202:205], v[48:51]
	v_mfma_f32_16x16x32_bf16 v[36:39], v[146:149], v[210:213], v[36:39]
	v_mfma_f32_16x16x32_bf16 v[32:35], v[154:157], v[210:213], v[32:35]
	v_mfma_f32_16x16x32_bf16 v[20:23], v[146:149], v[232:235], v[20:23]
	v_mfma_f32_16x16x32_bf16 v[16:19], v[154:157], v[232:235], v[16:19]
	s_setprio 0
	s_setprio 1
	v_mfma_f32_16x16x32_bf16 v[44:47], v[158:161], v[174:177], v[44:47]
	v_mfma_f32_16x16x32_bf16 v[40:43], v[166:169], v[174:177], v[40:43]
	v_mfma_f32_16x16x32_bf16 v[28:31], v[158:161], v[198:201], v[28:31]
	v_mfma_f32_16x16x32_bf16 v[24:27], v[166:169], v[198:201], v[24:27]
	v_mfma_f32_16x16x32_bf16 v[12:15], v[158:161], v[206:209], v[12:15]
	v_mfma_f32_16x16x32_bf16 v[8:11], v[166:169], v[206:209], v[8:11]
	v_mfma_f32_16x16x32_bf16 v[4:7], v[158:161], v[214:217], v[4:7]
	v_mfma_f32_16x16x32_bf16 v[0:3], v[166:169], v[214:217], v[0:3]
	v_mfma_f32_16x16x32_bf16 v[44:47], v[162:165], v[178:181], v[44:47]
	v_mfma_f32_16x16x32_bf16 v[40:43], v[170:173], v[178:181], v[40:43]
	v_mfma_f32_16x16x32_bf16 v[28:31], v[162:165], v[202:205], v[28:31]
	v_mfma_f32_16x16x32_bf16 v[24:27], v[170:173], v[202:205], v[24:27]
	v_mfma_f32_16x16x32_bf16 v[12:15], v[162:165], v[210:213], v[12:15]
	v_mfma_f32_16x16x32_bf16 v[8:11], v[170:173], v[210:213], v[8:11]
	v_mfma_f32_16x16x32_bf16 v[4:7], v[162:165], v[232:235], v[4:7]
	v_mfma_f32_16x16x32_bf16 v[0:3], v[170:173], v[232:235], v[0:3]
	s_setprio 0
	s_barrier
	s_add_i32 s10, s10, 2
	s_add_u32 s30, s30, 0x100
	s_addc_u32 s31, s31, 0
	s_cmp_gt_u32 s10, 41
	s_mov_b64 s[56:57], s[58:59]
	s_cbranch_scc0 .LBB0_839
	s_and_b64 vcc, exec, s[50:51]
	s_cbranch_vccz .LBB0_842
	s_barrier
